# gdn prep forward substitution regenerated by hand with v_pk_fma_f32 on aligned row pairs, 8-quad L read-ahead ring, same f32 fused arithmetic per element
# speedup vs baseline: 1.0030x; 1.0030x over previous
; #define LAS __attribute__((address_space(3)))
; #define PIN16(o) asm volatile("" : "+v"(xr[o]), "+v"(xr[o + 1]), "+v"(xr[o + 2]), "+v"(xr[o + 3]), "+v"(xr[o + 4]), "+v"(xr[o + 5]), "+v"(xr[o + 6]), "+v"(xr[o + 7]), "+v"(xr[o + 8]), "+v"(xr[o + 9]), "+v"(xr[o + 10]), "+v"(xr[o + 11]), "+v"(xr[o + 12]), "+v"(xr[o + 13]), "+v"(xr[o + 14]), "+v"(xr[o + 15]) :: "memory")
; DI void gdn_prep_item(LAS unsigned char* lds, const Ctx& c, int l, int item) {
;     ...
;     if (tid < 256) {
;         const int col = tid; const LAS float* src = col < 128 ? vf + col : kf + (col - 128); const LAS float* mul = col < 128 ? betaL : (LAS float*)(lds + GP_BEK);
;         const LAS float* Lb = Lm; asm volatile("" : "+v"(Lb)); asm volatile("" : "+v"(mul));
;         float xr[64];
; #pragma unroll
;         for (int i = 0; i < 64; ++i) xr[i] = src[i * 129] * mul[i];
; #pragma unroll
;         for (int j = 0; j < 63; ++j) {
;             const float xj = xr[j];
; #pragma unroll
;             for (int i4 = (j + 1) / 4; i4 < 16; ++i4) { const f32x4 Lv = *(const LAS f32x4*)(Lb + j * 64 + 4 * i4);
; #pragma unroll
;                 for (int q = 0; q < 4; ++q) xr[4 * i4 + q] -= Lv[q] * xj; }
;     ...
;             PIN16(0); PIN16(16); PIN16(32); PIN16(48);
.LBB0_313:
	s_andn2_saveexec_b64 s[4:5], s[4:5]
	s_cbranch_execz .LBB0_209
	v_lshlrev_b32_e32 v0, 2, v26
	v_readlane_b32 s6, v254, 4
	v_mov_b32_e32 v4, s42
	s_nop 0
	v_add_u32_e32 v2, s6, v0
	s_add_i32 s6, 0, 0x1cd00
	v_add_u32_e32 v0, 0, v0
	v_mov_b32_e32 v3, s6
	s_movk_i32 s6, 0x80
	v_add_u32_e32 v0, 0x8600, v0
	v_cmp_gt_i32_e32 vcc, s6, v26
	v_readlane_b32 s6, v254, 5
	s_nop 0
	v_cndmask_b32_e32 v27, v3, v4, vcc
	v_cndmask_b32_e32 v38, v0, v2, vcc
	v_mov_b32_e32 v0, s6
	s_movk_i32 s6, 0x7f
	v_cmp_lt_i32_e32 vcc, s6, v26
	s_lshl_b64 s[6:7], s[40:41], 14
	ds_read2_b32 v[122:123], v38 offset1:129
	ds_read2_b32 v[90:91], v27 offset0:0 offset1:1
	v_add_u32_e32 v222, 0x400, v38
	ds_read2_b32 v[124:125], v222 offset0:2 offset1:131
	ds_read2_b32 v[92:93], v27 offset0:2 offset1:3
	v_add_u32_e32 v222, 0x800, v38
	ds_read2_b32 v[126:127], v222 offset0:4 offset1:133
	ds_read2_b32 v[94:95], v27 offset0:4 offset1:5
	v_add_u32_e32 v222, 0xc00, v38
	ds_read2_b32 v[128:129], v222 offset0:6 offset1:135
	ds_read2_b32 v[96:97], v27 offset0:6 offset1:7
	v_add_u32_e32 v222, 0x1000, v38
	ds_read2_b32 v[156:157], v222 offset0:8 offset1:137
	ds_read2_b32 v[98:99], v27 offset0:8 offset1:9
	v_add_u32_e32 v222, 0x1400, v38
	ds_read2_b32 v[158:159], v222 offset0:10 offset1:139
	ds_read2_b32 v[100:101], v27 offset0:10 offset1:11
	v_add_u32_e32 v222, 0x1800, v38
	ds_read2_b32 v[160:161], v222 offset0:12 offset1:141
	ds_read2_b32 v[102:103], v27 offset0:12 offset1:13
	v_add_u32_e32 v222, 0x1c00, v38
	ds_read2_b32 v[162:163], v222 offset0:14 offset1:143
	ds_read2_b32 v[104:105], v27 offset0:14 offset1:15
	ds_read_b128 v[106:109], v0
	ds_read_b128 v[110:113], v0 offset:16
	ds_read_b128 v[114:117], v0 offset:32
	ds_read_b128 v[118:121], v0 offset:48
	s_waitcnt lgkmcnt(0)
	v_pk_mul_f32 v[218:219], v[122:123], v[90:91]
	v_pk_mul_f32 v[220:221], v[106:107], v[218:219] op_sel_hi:[1,0]
	v_pk_fma_f32 v[122:123], v[122:123], v[90:91], v[220:221] neg_lo:[0,0,1] neg_hi:[0,0,1]
	v_pk_mul_f32 v[220:221], v[108:109], v[218:219] op_sel_hi:[1,0]
	v_pk_fma_f32 v[124:125], v[124:125], v[92:93], v[220:221] neg_lo:[0,0,1] neg_hi:[0,0,1]
	v_pk_mul_f32 v[220:221], v[110:111], v[218:219] op_sel_hi:[1,0]
	v_pk_fma_f32 v[126:127], v[126:127], v[94:95], v[220:221] neg_lo:[0,0,1] neg_hi:[0,0,1]
	v_pk_mul_f32 v[220:221], v[112:113], v[218:219] op_sel_hi:[1,0]
	v_pk_fma_f32 v[128:129], v[128:129], v[96:97], v[220:221] neg_lo:[0,0,1] neg_hi:[0,0,1]
	v_pk_mul_f32 v[220:221], v[114:115], v[218:219] op_sel_hi:[1,0]
	v_pk_fma_f32 v[156:157], v[156:157], v[98:99], v[220:221] neg_lo:[0,0,1] neg_hi:[0,0,1]
	v_pk_mul_f32 v[220:221], v[116:117], v[218:219] op_sel_hi:[1,0]
	v_pk_fma_f32 v[158:159], v[158:159], v[100:101], v[220:221] neg_lo:[0,0,1] neg_hi:[0,0,1]
	v_pk_mul_f32 v[220:221], v[118:119], v[218:219] op_sel_hi:[1,0]
	v_pk_fma_f32 v[160:161], v[160:161], v[102:103], v[220:221] neg_lo:[0,0,1] neg_hi:[0,0,1]
	v_pk_mul_f32 v[220:221], v[120:121], v[218:219] op_sel_hi:[1,0]
	v_pk_fma_f32 v[162:163], v[162:163], v[104:105], v[220:221] neg_lo:[0,0,1] neg_hi:[0,0,1]
	v_add_u32_e32 v222, 0x2000, v38
	ds_read2_b32 v[164:165], v222 offset0:16 offset1:145
	ds_read2_b32 v[90:91], v27 offset0:16 offset1:17
	v_add_u32_e32 v222, 0x2400, v38
	ds_read2_b32 v[166:167], v222 offset0:18 offset1:147
	ds_read2_b32 v[92:93], v27 offset0:18 offset1:19
	v_add_u32_e32 v222, 0x2800, v38
	ds_read2_b32 v[168:169], v222 offset0:20 offset1:149
	ds_read2_b32 v[94:95], v27 offset0:20 offset1:21
	v_add_u32_e32 v222, 0x2c00, v38
	ds_read2_b32 v[170:171], v222 offset0:22 offset1:151
	ds_read2_b32 v[96:97], v27 offset0:22 offset1:23
	v_add_u32_e32 v222, 0x3000, v38
	ds_read2_b32 v[172:173], v222 offset0:24 offset1:153
	ds_read2_b32 v[98:99], v27 offset0:24 offset1:25
	v_add_u32_e32 v222, 0x3400, v38
	ds_read2_b32 v[174:175], v222 offset0:26 offset1:155
	ds_read2_b32 v[100:101], v27 offset0:26 offset1:27
	v_add_u32_e32 v222, 0x3800, v38
	ds_read2_b32 v[176:177], v222 offset0:28 offset1:157
	ds_read2_b32 v[102:103], v27 offset0:28 offset1:29
	v_add_u32_e32 v222, 0x3c00, v38
	ds_read2_b32 v[178:179], v222 offset0:30 offset1:159
	ds_read2_b32 v[104:105], v27 offset0:30 offset1:31
	ds_read_b128 v[106:109], v0 offset:64
	ds_read_b128 v[110:113], v0 offset:80
	ds_read_b128 v[114:117], v0 offset:96
	ds_read_b128 v[118:121], v0 offset:112
	s_waitcnt lgkmcnt(0)
	v_pk_mul_f32 v[220:221], v[106:107], v[218:219] op_sel_hi:[1,0]
	v_pk_fma_f32 v[164:165], v[164:165], v[90:91], v[220:221] neg_lo:[0,0,1] neg_hi:[0,0,1]
	v_pk_mul_f32 v[220:221], v[108:109], v[218:219] op_sel_hi:[1,0]
	v_pk_fma_f32 v[166:167], v[166:167], v[92:93], v[220:221] neg_lo:[0,0,1] neg_hi:[0,0,1]
	v_pk_mul_f32 v[220:221], v[110:111], v[218:219] op_sel_hi:[1,0]
	v_pk_fma_f32 v[168:169], v[168:169], v[94:95], v[220:221] neg_lo:[0,0,1] neg_hi:[0,0,1]
	v_pk_mul_f32 v[220:221], v[112:113], v[218:219] op_sel_hi:[1,0]
	v_pk_fma_f32 v[170:171], v[170:171], v[96:97], v[220:221] neg_lo:[0,0,1] neg_hi:[0,0,1]
	v_pk_mul_f32 v[220:221], v[114:115], v[218:219] op_sel_hi:[1,0]
	v_pk_fma_f32 v[172:173], v[172:173], v[98:99], v[220:221] neg_lo:[0,0,1] neg_hi:[0,0,1]
	v_pk_mul_f32 v[220:221], v[116:117], v[218:219] op_sel_hi:[1,0]
	v_pk_fma_f32 v[174:175], v[174:175], v[100:101], v[220:221] neg_lo:[0,0,1] neg_hi:[0,0,1]
	v_pk_mul_f32 v[220:221], v[118:119], v[218:219] op_sel_hi:[1,0]
	v_pk_fma_f32 v[176:177], v[176:177], v[102:103], v[220:221] neg_lo:[0,0,1] neg_hi:[0,0,1]
	v_pk_mul_f32 v[220:221], v[120:121], v[218:219] op_sel_hi:[1,0]
	v_pk_fma_f32 v[178:179], v[178:179], v[104:105], v[220:221] neg_lo:[0,0,1] neg_hi:[0,0,1]
	v_add_u32_e32 v222, 0x4000, v38
	ds_read2_b32 v[180:181], v222 offset0:32 offset1:161
	ds_read2_b32 v[90:91], v27 offset0:32 offset1:33
	v_add_u32_e32 v222, 0x4400, v38
	ds_read2_b32 v[182:183], v222 offset0:34 offset1:163
	ds_read2_b32 v[92:93], v27 offset0:34 offset1:35
	v_add_u32_e32 v222, 0x4800, v38
	ds_read2_b32 v[184:185], v222 offset0:36 offset1:165
	ds_read2_b32 v[94:95], v27 offset0:36 offset1:37
	v_add_u32_e32 v222, 0x4c00, v38
	ds_read2_b32 v[186:187], v222 offset0:38 offset1:167
	ds_read2_b32 v[96:97], v27 offset0:38 offset1:39
	v_add_u32_e32 v222, 0x5000, v38
	ds_read2_b32 v[188:189], v222 offset0:40 offset1:169
	ds_read2_b32 v[98:99], v27 offset0:40 offset1:41
	v_add_u32_e32 v222, 0x5400, v38
	ds_read2_b32 v[190:191], v222 offset0:42 offset1:171
	ds_read2_b32 v[100:101], v27 offset0:42 offset1:43
	v_add_u32_e32 v222, 0x5800, v38
	ds_read2_b32 v[192:193], v222 offset0:44 offset1:173
	ds_read2_b32 v[102:103], v27 offset0:44 offset1:45
	v_add_u32_e32 v222, 0x5c00, v38
	ds_read2_b32 v[198:199], v222 offset0:46 offset1:175
	ds_read2_b32 v[104:105], v27 offset0:46 offset1:47
	ds_read_b128 v[106:109], v0 offset:128
	ds_read_b128 v[110:113], v0 offset:144
	ds_read_b128 v[114:117], v0 offset:160
	ds_read_b128 v[118:121], v0 offset:176
	s_waitcnt lgkmcnt(0)
; #define LAS __attribute__((address_space(3)))
; #define PIN16(o) asm volatile("" : "+v"(xr[o]), "+v"(xr[o + 1]), "+v"(xr[o + 2]), "+v"(xr[o + 3]), "+v"(xr[o + 4]), "+v"(xr[o + 5]), "+v"(xr[o + 6]), "+v"(xr[o + 7]), "+v"(xr[o + 8]), "+v"(xr[o + 9]), "+v"(xr[o + 10]), "+v"(xr[o + 11]), "+v"(xr[o + 12]), "+v"(xr[o + 13]), "+v"(xr[o + 14]), "+v"(xr[o + 15]) :: "memory")
; DI void gdn_prep_item(LAS unsigned char* lds, const Ctx& c, int l, int item) {
;     ...
; #pragma unroll
;         for (int j = 0; j < 63; ++j) {
;             const float xj = xr[j];
; #pragma unroll
;             for (int i4 = (j + 1) / 4; i4 < 16; ++i4) { const f32x4 Lv = *(const LAS f32x4*)(Lb + j * 64 + 4 * i4);
; #pragma unroll
;                 for (int q = 0; q < 4; ++q) xr[4 * i4 + q] -= Lv[q] * xj; }
;     ...
;             PIN16(0); PIN16(16); PIN16(32); PIN16(48);
	v_pk_mul_f32 v[220:221], v[106:107], v[218:219] op_sel_hi:[1,0]
	v_pk_fma_f32 v[180:181], v[180:181], v[90:91], v[220:221] neg_lo:[0,0,1] neg_hi:[0,0,1]
	v_pk_mul_f32 v[220:221], v[108:109], v[218:219] op_sel_hi:[1,0]
	v_pk_fma_f32 v[182:183], v[182:183], v[92:93], v[220:221] neg_lo:[0,0,1] neg_hi:[0,0,1]
	v_pk_mul_f32 v[220:221], v[110:111], v[218:219] op_sel_hi:[1,0]
	v_pk_fma_f32 v[184:185], v[184:185], v[94:95], v[220:221] neg_lo:[0,0,1] neg_hi:[0,0,1]
	v_pk_mul_f32 v[220:221], v[112:113], v[218:219] op_sel_hi:[1,0]
	v_pk_fma_f32 v[186:187], v[186:187], v[96:97], v[220:221] neg_lo:[0,0,1] neg_hi:[0,0,1]
	v_pk_mul_f32 v[220:221], v[114:115], v[218:219] op_sel_hi:[1,0]
	v_pk_fma_f32 v[188:189], v[188:189], v[98:99], v[220:221] neg_lo:[0,0,1] neg_hi:[0,0,1]
	v_pk_mul_f32 v[220:221], v[116:117], v[218:219] op_sel_hi:[1,0]
	v_pk_fma_f32 v[190:191], v[190:191], v[100:101], v[220:221] neg_lo:[0,0,1] neg_hi:[0,0,1]
	v_pk_mul_f32 v[220:221], v[118:119], v[218:219] op_sel_hi:[1,0]
	v_pk_fma_f32 v[192:193], v[192:193], v[102:103], v[220:221] neg_lo:[0,0,1] neg_hi:[0,0,1]
	v_pk_mul_f32 v[220:221], v[120:121], v[218:219] op_sel_hi:[1,0]
	v_pk_fma_f32 v[198:199], v[198:199], v[104:105], v[220:221] neg_lo:[0,0,1] neg_hi:[0,0,1]
	v_add_u32_e32 v222, 0x6000, v38
	ds_read2_b32 v[200:201], v222 offset0:48 offset1:177
	ds_read2_b32 v[90:91], v27 offset0:48 offset1:49
	v_add_u32_e32 v222, 0x6400, v38
	ds_read2_b32 v[202:203], v222 offset0:50 offset1:179
	ds_read2_b32 v[92:93], v27 offset0:50 offset1:51
	v_add_u32_e32 v222, 0x6800, v38
	ds_read2_b32 v[204:205], v222 offset0:52 offset1:181
	ds_read2_b32 v[94:95], v27 offset0:52 offset1:53
	v_add_u32_e32 v222, 0x6c00, v38
	ds_read2_b32 v[208:209], v222 offset0:54 offset1:183
	ds_read2_b32 v[96:97], v27 offset0:54 offset1:55
	v_add_u32_e32 v222, 0x7000, v38
	ds_read2_b32 v[210:211], v222 offset0:56 offset1:185
	ds_read2_b32 v[98:99], v27 offset0:56 offset1:57
	v_add_u32_e32 v222, 0x7400, v38
	ds_read2_b32 v[212:213], v222 offset0:58 offset1:187
	ds_read2_b32 v[100:101], v27 offset0:58 offset1:59
	v_add_u32_e32 v222, 0x7800, v38
	ds_read2_b32 v[214:215], v222 offset0:60 offset1:189
	ds_read2_b32 v[102:103], v27 offset0:60 offset1:61
	v_add_u32_e32 v222, 0x7c00, v38
	ds_read2_b32 v[216:217], v222 offset0:62 offset1:191
	ds_read2_b32 v[104:105], v27 offset0:62 offset1:63
	ds_read_b128 v[106:109], v0 offset:192
	ds_read_b128 v[110:113], v0 offset:208
	ds_read_b128 v[114:117], v0 offset:224
	ds_read_b128 v[118:121], v0 offset:240
	s_waitcnt lgkmcnt(0)
	v_pk_mul_f32 v[220:221], v[106:107], v[218:219] op_sel_hi:[1,0]
	v_pk_fma_f32 v[200:201], v[200:201], v[90:91], v[220:221] neg_lo:[0,0,1] neg_hi:[0,0,1]
	v_pk_mul_f32 v[220:221], v[108:109], v[218:219] op_sel_hi:[1,0]
	v_pk_fma_f32 v[202:203], v[202:203], v[92:93], v[220:221] neg_lo:[0,0,1] neg_hi:[0,0,1]
	v_pk_mul_f32 v[220:221], v[110:111], v[218:219] op_sel_hi:[1,0]
	v_pk_fma_f32 v[204:205], v[204:205], v[94:95], v[220:221] neg_lo:[0,0,1] neg_hi:[0,0,1]
	v_pk_mul_f32 v[220:221], v[112:113], v[218:219] op_sel_hi:[1,0]
	v_pk_fma_f32 v[208:209], v[208:209], v[96:97], v[220:221] neg_lo:[0,0,1] neg_hi:[0,0,1]
	v_pk_mul_f32 v[220:221], v[114:115], v[218:219] op_sel_hi:[1,0]
	v_pk_fma_f32 v[210:211], v[210:211], v[98:99], v[220:221] neg_lo:[0,0,1] neg_hi:[0,0,1]
	v_pk_mul_f32 v[220:221], v[116:117], v[218:219] op_sel_hi:[1,0]
	v_pk_fma_f32 v[212:213], v[212:213], v[100:101], v[220:221] neg_lo:[0,0,1] neg_hi:[0,0,1]
	v_pk_mul_f32 v[220:221], v[118:119], v[218:219] op_sel_hi:[1,0]
	v_pk_fma_f32 v[214:215], v[214:215], v[102:103], v[220:221] neg_lo:[0,0,1] neg_hi:[0,0,1]
	v_pk_mul_f32 v[220:221], v[120:121], v[218:219] op_sel_hi:[1,0]
	v_pk_fma_f32 v[216:217], v[216:217], v[104:105], v[220:221] neg_lo:[0,0,1] neg_hi:[0,0,1]
	ds_read_b128 v[90:93], v0 offset:256
	ds_read_b128 v[94:97], v0 offset:272
	ds_read_b128 v[98:101], v0 offset:288
	ds_read_b128 v[102:105], v0 offset:304
	ds_read_b128 v[106:109], v0 offset:320
	ds_read_b128 v[110:113], v0 offset:336
	ds_read_b128 v[114:117], v0 offset:352
	s_waitcnt lgkmcnt(6)
	v_pk_fma_f32 v[124:125], v[92:93], v[122:123], v[124:125] op_sel:[0,1,0] neg_lo:[1,0,0] neg_hi:[1,0,0]
	ds_read_b128 v[118:121], v0 offset:368
	s_waitcnt lgkmcnt(6)
	v_pk_fma_f32 v[126:127], v[94:95], v[122:123], v[126:127] op_sel:[0,1,0] neg_lo:[1,0,0] neg_hi:[1,0,0]
	v_pk_fma_f32 v[128:129], v[96:97], v[122:123], v[128:129] op_sel:[0,1,0] neg_lo:[1,0,0] neg_hi:[1,0,0]
	ds_read_b128 v[90:93], v0 offset:384
	s_waitcnt lgkmcnt(6)
	v_pk_fma_f32 v[156:157], v[98:99], v[122:123], v[156:157] op_sel:[0,1,0] neg_lo:[1,0,0] neg_hi:[1,0,0]
	v_pk_fma_f32 v[158:159], v[100:101], v[122:123], v[158:159] op_sel:[0,1,0] neg_lo:[1,0,0] neg_hi:[1,0,0]
	ds_read_b128 v[94:97], v0 offset:400
	s_waitcnt lgkmcnt(6)
	v_pk_fma_f32 v[160:161], v[102:103], v[122:123], v[160:161] op_sel:[0,1,0] neg_lo:[1,0,0] neg_hi:[1,0,0]
	v_pk_fma_f32 v[162:163], v[104:105], v[122:123], v[162:163] op_sel:[0,1,0] neg_lo:[1,0,0] neg_hi:[1,0,0]
	ds_read_b128 v[98:101], v0 offset:416
	s_waitcnt lgkmcnt(6)
	v_pk_fma_f32 v[164:165], v[106:107], v[122:123], v[164:165] op_sel:[0,1,0] neg_lo:[1,0,0] neg_hi:[1,0,0]
	v_pk_fma_f32 v[166:167], v[108:109], v[122:123], v[166:167] op_sel:[0,1,0] neg_lo:[1,0,0] neg_hi:[1,0,0]
	ds_read_b128 v[102:105], v0 offset:432
	s_waitcnt lgkmcnt(6)
	v_pk_fma_f32 v[168:169], v[110:111], v[122:123], v[168:169] op_sel:[0,1,0] neg_lo:[1,0,0] neg_hi:[1,0,0]
	v_pk_fma_f32 v[170:171], v[112:113], v[122:123], v[170:171] op_sel:[0,1,0] neg_lo:[1,0,0] neg_hi:[1,0,0]
	ds_read_b128 v[106:109], v0 offset:448
	s_waitcnt lgkmcnt(6)
; #define LAS __attribute__((address_space(3)))
; #define PIN16(o) asm volatile("" : "+v"(xr[o]), "+v"(xr[o + 1]), "+v"(xr[o + 2]), "+v"(xr[o + 3]), "+v"(xr[o + 4]), "+v"(xr[o + 5]), "+v"(xr[o + 6]), "+v"(xr[o + 7]), "+v"(xr[o + 8]), "+v"(xr[o + 9]), "+v"(xr[o + 10]), "+v"(xr[o + 11]), "+v"(xr[o + 12]), "+v"(xr[o + 13]), "+v"(xr[o + 14]), "+v"(xr[o + 15]) :: "memory")
; DI void gdn_prep_item(LAS unsigned char* lds, const Ctx& c, int l, int item) {
;     ...
; #pragma unroll
;         for (int j = 0; j < 63; ++j) {
;             const float xj = xr[j];
; #pragma unroll
;             for (int i4 = (j + 1) / 4; i4 < 16; ++i4) { const f32x4 Lv = *(const LAS f32x4*)(Lb + j * 64 + 4 * i4);
; #pragma unroll
;                 for (int q = 0; q < 4; ++q) xr[4 * i4 + q] -= Lv[q] * xj; }
;     ...
;             PIN16(0); PIN16(16); PIN16(32); PIN16(48);
	v_pk_fma_f32 v[172:173], v[114:115], v[122:123], v[172:173] op_sel:[0,1,0] neg_lo:[1,0,0] neg_hi:[1,0,0]
	v_pk_fma_f32 v[174:175], v[116:117], v[122:123], v[174:175] op_sel:[0,1,0] neg_lo:[1,0,0] neg_hi:[1,0,0]
	ds_read_b128 v[110:113], v0 offset:464
	s_waitcnt lgkmcnt(6)
	v_pk_fma_f32 v[176:177], v[118:119], v[122:123], v[176:177] op_sel:[0,1,0] neg_lo:[1,0,0] neg_hi:[1,0,0]
	v_pk_fma_f32 v[178:179], v[120:121], v[122:123], v[178:179] op_sel:[0,1,0] neg_lo:[1,0,0] neg_hi:[1,0,0]
	ds_read_b128 v[114:117], v0 offset:480
	s_waitcnt lgkmcnt(6)
	v_pk_fma_f32 v[180:181], v[90:91], v[122:123], v[180:181] op_sel:[0,1,0] neg_lo:[1,0,0] neg_hi:[1,0,0]
	v_pk_fma_f32 v[182:183], v[92:93], v[122:123], v[182:183] op_sel:[0,1,0] neg_lo:[1,0,0] neg_hi:[1,0,0]
	ds_read_b128 v[118:121], v0 offset:496
	s_waitcnt lgkmcnt(6)
	v_pk_fma_f32 v[184:185], v[94:95], v[122:123], v[184:185] op_sel:[0,1,0] neg_lo:[1,0,0] neg_hi:[1,0,0]
	v_pk_fma_f32 v[186:187], v[96:97], v[122:123], v[186:187] op_sel:[0,1,0] neg_lo:[1,0,0] neg_hi:[1,0,0]
	ds_read_b128 v[90:93], v0 offset:512
	s_waitcnt lgkmcnt(6)
	v_pk_fma_f32 v[188:189], v[98:99], v[122:123], v[188:189] op_sel:[0,1,0] neg_lo:[1,0,0] neg_hi:[1,0,0]
	v_pk_fma_f32 v[190:191], v[100:101], v[122:123], v[190:191] op_sel:[0,1,0] neg_lo:[1,0,0] neg_hi:[1,0,0]
	ds_read_b128 v[94:97], v0 offset:528
	s_waitcnt lgkmcnt(6)
	v_pk_fma_f32 v[192:193], v[102:103], v[122:123], v[192:193] op_sel:[0,1,0] neg_lo:[1,0,0] neg_hi:[1,0,0]
	v_pk_fma_f32 v[198:199], v[104:105], v[122:123], v[198:199] op_sel:[0,1,0] neg_lo:[1,0,0] neg_hi:[1,0,0]
	ds_read_b128 v[98:101], v0 offset:544
	s_waitcnt lgkmcnt(6)
	v_pk_fma_f32 v[200:201], v[106:107], v[122:123], v[200:201] op_sel:[0,1,0] neg_lo:[1,0,0] neg_hi:[1,0,0]
	v_pk_fma_f32 v[202:203], v[108:109], v[122:123], v[202:203] op_sel:[0,1,0] neg_lo:[1,0,0] neg_hi:[1,0,0]
	ds_read_b128 v[102:105], v0 offset:560
	s_waitcnt lgkmcnt(6)
	v_pk_fma_f32 v[204:205], v[110:111], v[122:123], v[204:205] op_sel:[0,1,0] neg_lo:[1,0,0] neg_hi:[1,0,0]
	v_pk_fma_f32 v[208:209], v[112:113], v[122:123], v[208:209] op_sel:[0,1,0] neg_lo:[1,0,0] neg_hi:[1,0,0]
	ds_read_b128 v[106:109], v0 offset:576
	s_waitcnt lgkmcnt(6)
	v_pk_fma_f32 v[210:211], v[114:115], v[122:123], v[210:211] op_sel:[0,1,0] neg_lo:[1,0,0] neg_hi:[1,0,0]
	v_pk_fma_f32 v[212:213], v[116:117], v[122:123], v[212:213] op_sel:[0,1,0] neg_lo:[1,0,0] neg_hi:[1,0,0]
	ds_read_b128 v[110:113], v0 offset:592
	s_waitcnt lgkmcnt(6)
	v_pk_fma_f32 v[214:215], v[118:119], v[122:123], v[214:215] op_sel:[0,1,0] neg_lo:[1,0,0] neg_hi:[1,0,0]
	v_pk_fma_f32 v[216:217], v[120:121], v[122:123], v[216:217] op_sel:[0,1,0] neg_lo:[1,0,0] neg_hi:[1,0,0]
	ds_read_b128 v[114:117], v0 offset:608
	s_waitcnt lgkmcnt(6)
	v_pk_fma_f32 v[124:125], v[92:93], v[124:125], v[124:125] op_sel_hi:[1,0,1] neg_lo:[1,0,0] neg_hi:[1,0,0]
	ds_read_b128 v[118:121], v0 offset:624
	s_waitcnt lgkmcnt(6)
	v_pk_fma_f32 v[126:127], v[94:95], v[124:125], v[126:127] op_sel_hi:[1,0,1] neg_lo:[1,0,0] neg_hi:[1,0,0]
	v_pk_fma_f32 v[128:129], v[96:97], v[124:125], v[128:129] op_sel_hi:[1,0,1] neg_lo:[1,0,0] neg_hi:[1,0,0]
	ds_read_b128 v[90:93], v0 offset:640
	s_waitcnt lgkmcnt(6)
	v_pk_fma_f32 v[156:157], v[98:99], v[124:125], v[156:157] op_sel_hi:[1,0,1] neg_lo:[1,0,0] neg_hi:[1,0,0]
	v_pk_fma_f32 v[158:159], v[100:101], v[124:125], v[158:159] op_sel_hi:[1,0,1] neg_lo:[1,0,0] neg_hi:[1,0,0]
	ds_read_b128 v[94:97], v0 offset:656
	s_waitcnt lgkmcnt(6)
	v_pk_fma_f32 v[160:161], v[102:103], v[124:125], v[160:161] op_sel_hi:[1,0,1] neg_lo:[1,0,0] neg_hi:[1,0,0]
	v_pk_fma_f32 v[162:163], v[104:105], v[124:125], v[162:163] op_sel_hi:[1,0,1] neg_lo:[1,0,0] neg_hi:[1,0,0]
	ds_read_b128 v[98:101], v0 offset:672
	s_waitcnt lgkmcnt(6)
	v_pk_fma_f32 v[164:165], v[106:107], v[124:125], v[164:165] op_sel_hi:[1,0,1] neg_lo:[1,0,0] neg_hi:[1,0,0]
	v_pk_fma_f32 v[166:167], v[108:109], v[124:125], v[166:167] op_sel_hi:[1,0,1] neg_lo:[1,0,0] neg_hi:[1,0,0]
	ds_read_b128 v[102:105], v0 offset:688
	s_waitcnt lgkmcnt(6)
	v_pk_fma_f32 v[168:169], v[110:111], v[124:125], v[168:169] op_sel_hi:[1,0,1] neg_lo:[1,0,0] neg_hi:[1,0,0]
	v_pk_fma_f32 v[170:171], v[112:113], v[124:125], v[170:171] op_sel_hi:[1,0,1] neg_lo:[1,0,0] neg_hi:[1,0,0]
	ds_read_b128 v[106:109], v0 offset:704
	s_waitcnt lgkmcnt(6)
	v_pk_fma_f32 v[172:173], v[114:115], v[124:125], v[172:173] op_sel_hi:[1,0,1] neg_lo:[1,0,0] neg_hi:[1,0,0]
	v_pk_fma_f32 v[174:175], v[116:117], v[124:125], v[174:175] op_sel_hi:[1,0,1] neg_lo:[1,0,0] neg_hi:[1,0,0]
	ds_read_b128 v[110:113], v0 offset:720
	s_waitcnt lgkmcnt(6)
	v_pk_fma_f32 v[176:177], v[118:119], v[124:125], v[176:177] op_sel_hi:[1,0,1] neg_lo:[1,0,0] neg_hi:[1,0,0]
	v_pk_fma_f32 v[178:179], v[120:121], v[124:125], v[178:179] op_sel_hi:[1,0,1] neg_lo:[1,0,0] neg_hi:[1,0,0]
	ds_read_b128 v[114:117], v0 offset:736
	s_waitcnt lgkmcnt(6)
	v_pk_fma_f32 v[180:181], v[90:91], v[124:125], v[180:181] op_sel_hi:[1,0,1] neg_lo:[1,0,0] neg_hi:[1,0,0]
	v_pk_fma_f32 v[182:183], v[92:93], v[124:125], v[182:183] op_sel_hi:[1,0,1] neg_lo:[1,0,0] neg_hi:[1,0,0]
	ds_read_b128 v[118:121], v0 offset:752
	s_waitcnt lgkmcnt(6)
	v_pk_fma_f32 v[184:185], v[94:95], v[124:125], v[184:185] op_sel_hi:[1,0,1] neg_lo:[1,0,0] neg_hi:[1,0,0]
	v_pk_fma_f32 v[186:187], v[96:97], v[124:125], v[186:187] op_sel_hi:[1,0,1] neg_lo:[1,0,0] neg_hi:[1,0,0]
	ds_read_b128 v[90:93], v0 offset:784
	s_waitcnt lgkmcnt(6)
	v_pk_fma_f32 v[188:189], v[98:99], v[124:125], v[188:189] op_sel_hi:[1,0,1] neg_lo:[1,0,0] neg_hi:[1,0,0]
	v_pk_fma_f32 v[190:191], v[100:101], v[124:125], v[190:191] op_sel_hi:[1,0,1] neg_lo:[1,0,0] neg_hi:[1,0,0]
	ds_read_b128 v[94:97], v0 offset:800
	s_waitcnt lgkmcnt(6)
; #define LAS __attribute__((address_space(3)))
; #define PIN16(o) asm volatile("" : "+v"(xr[o]), "+v"(xr[o + 1]), "+v"(xr[o + 2]), "+v"(xr[o + 3]), "+v"(xr[o + 4]), "+v"(xr[o + 5]), "+v"(xr[o + 6]), "+v"(xr[o + 7]), "+v"(xr[o + 8]), "+v"(xr[o + 9]), "+v"(xr[o + 10]), "+v"(xr[o + 11]), "+v"(xr[o + 12]), "+v"(xr[o + 13]), "+v"(xr[o + 14]), "+v"(xr[o + 15]) :: "memory")
; DI void gdn_prep_item(LAS unsigned char* lds, const Ctx& c, int l, int item) {
;     ...
; #pragma unroll
;         for (int j = 0; j < 63; ++j) {
;             const float xj = xr[j];
; #pragma unroll
;             for (int i4 = (j + 1) / 4; i4 < 16; ++i4) { const f32x4 Lv = *(const LAS f32x4*)(Lb + j * 64 + 4 * i4);
; #pragma unroll
;                 for (int q = 0; q < 4; ++q) xr[4 * i4 + q] -= Lv[q] * xj; }
;     ...
;             PIN16(0); PIN16(16); PIN16(32); PIN16(48);
	v_pk_fma_f32 v[192:193], v[102:103], v[124:125], v[192:193] op_sel_hi:[1,0,1] neg_lo:[1,0,0] neg_hi:[1,0,0]
	v_pk_fma_f32 v[198:199], v[104:105], v[124:125], v[198:199] op_sel_hi:[1,0,1] neg_lo:[1,0,0] neg_hi:[1,0,0]
	ds_read_b128 v[98:101], v0 offset:816
	s_waitcnt lgkmcnt(6)
	v_pk_fma_f32 v[200:201], v[106:107], v[124:125], v[200:201] op_sel_hi:[1,0,1] neg_lo:[1,0,0] neg_hi:[1,0,0]
	v_pk_fma_f32 v[202:203], v[108:109], v[124:125], v[202:203] op_sel_hi:[1,0,1] neg_lo:[1,0,0] neg_hi:[1,0,0]
	ds_read_b128 v[102:105], v0 offset:832
	s_waitcnt lgkmcnt(6)
	v_pk_fma_f32 v[204:205], v[110:111], v[124:125], v[204:205] op_sel_hi:[1,0,1] neg_lo:[1,0,0] neg_hi:[1,0,0]
	v_pk_fma_f32 v[208:209], v[112:113], v[124:125], v[208:209] op_sel_hi:[1,0,1] neg_lo:[1,0,0] neg_hi:[1,0,0]
	ds_read_b128 v[106:109], v0 offset:848
	s_waitcnt lgkmcnt(6)
	v_pk_fma_f32 v[210:211], v[114:115], v[124:125], v[210:211] op_sel_hi:[1,0,1] neg_lo:[1,0,0] neg_hi:[1,0,0]
	v_pk_fma_f32 v[212:213], v[116:117], v[124:125], v[212:213] op_sel_hi:[1,0,1] neg_lo:[1,0,0] neg_hi:[1,0,0]
	ds_read_b128 v[110:113], v0 offset:864
	s_waitcnt lgkmcnt(6)
	v_pk_fma_f32 v[214:215], v[118:119], v[124:125], v[214:215] op_sel_hi:[1,0,1] neg_lo:[1,0,0] neg_hi:[1,0,0]
	v_pk_fma_f32 v[216:217], v[120:121], v[124:125], v[216:217] op_sel_hi:[1,0,1] neg_lo:[1,0,0] neg_hi:[1,0,0]
	ds_read_b128 v[114:117], v0 offset:880
	s_waitcnt lgkmcnt(6)
	v_pk_fma_f32 v[126:127], v[90:91], v[124:125], v[126:127] op_sel:[0,1,0] neg_lo:[1,0,0] neg_hi:[1,0,0]
	v_pk_fma_f32 v[128:129], v[92:93], v[124:125], v[128:129] op_sel:[0,1,0] neg_lo:[1,0,0] neg_hi:[1,0,0]
	ds_read_b128 v[118:121], v0 offset:896
	s_waitcnt lgkmcnt(6)
	v_pk_fma_f32 v[156:157], v[94:95], v[124:125], v[156:157] op_sel:[0,1,0] neg_lo:[1,0,0] neg_hi:[1,0,0]
	v_pk_fma_f32 v[158:159], v[96:97], v[124:125], v[158:159] op_sel:[0,1,0] neg_lo:[1,0,0] neg_hi:[1,0,0]
	ds_read_b128 v[90:93], v0 offset:912
	s_waitcnt lgkmcnt(6)
	v_pk_fma_f32 v[160:161], v[98:99], v[124:125], v[160:161] op_sel:[0,1,0] neg_lo:[1,0,0] neg_hi:[1,0,0]
	v_pk_fma_f32 v[162:163], v[100:101], v[124:125], v[162:163] op_sel:[0,1,0] neg_lo:[1,0,0] neg_hi:[1,0,0]
	ds_read_b128 v[94:97], v0 offset:928
	s_waitcnt lgkmcnt(6)
	v_pk_fma_f32 v[164:165], v[102:103], v[124:125], v[164:165] op_sel:[0,1,0] neg_lo:[1,0,0] neg_hi:[1,0,0]
	v_pk_fma_f32 v[166:167], v[104:105], v[124:125], v[166:167] op_sel:[0,1,0] neg_lo:[1,0,0] neg_hi:[1,0,0]
	ds_read_b128 v[98:101], v0 offset:944
	s_waitcnt lgkmcnt(6)
	v_pk_fma_f32 v[168:169], v[106:107], v[124:125], v[168:169] op_sel:[0,1,0] neg_lo:[1,0,0] neg_hi:[1,0,0]
	v_pk_fma_f32 v[170:171], v[108:109], v[124:125], v[170:171] op_sel:[0,1,0] neg_lo:[1,0,0] neg_hi:[1,0,0]
	ds_read_b128 v[102:105], v0 offset:960
	s_waitcnt lgkmcnt(6)
	v_pk_fma_f32 v[172:173], v[110:111], v[124:125], v[172:173] op_sel:[0,1,0] neg_lo:[1,0,0] neg_hi:[1,0,0]
	v_pk_fma_f32 v[174:175], v[112:113], v[124:125], v[174:175] op_sel:[0,1,0] neg_lo:[1,0,0] neg_hi:[1,0,0]
	ds_read_b128 v[106:109], v0 offset:976
	s_waitcnt lgkmcnt(6)
	v_pk_fma_f32 v[176:177], v[114:115], v[124:125], v[176:177] op_sel:[0,1,0] neg_lo:[1,0,0] neg_hi:[1,0,0]
	v_pk_fma_f32 v[178:179], v[116:117], v[124:125], v[178:179] op_sel:[0,1,0] neg_lo:[1,0,0] neg_hi:[1,0,0]
	ds_read_b128 v[110:113], v0 offset:992
	s_waitcnt lgkmcnt(6)
	v_pk_fma_f32 v[180:181], v[118:119], v[124:125], v[180:181] op_sel:[0,1,0] neg_lo:[1,0,0] neg_hi:[1,0,0]
	v_pk_fma_f32 v[182:183], v[120:121], v[124:125], v[182:183] op_sel:[0,1,0] neg_lo:[1,0,0] neg_hi:[1,0,0]
	ds_read_b128 v[114:117], v0 offset:1008
	s_waitcnt lgkmcnt(6)
	v_pk_fma_f32 v[184:185], v[90:91], v[124:125], v[184:185] op_sel:[0,1,0] neg_lo:[1,0,0] neg_hi:[1,0,0]
	v_pk_fma_f32 v[186:187], v[92:93], v[124:125], v[186:187] op_sel:[0,1,0] neg_lo:[1,0,0] neg_hi:[1,0,0]
	ds_read_b128 v[118:121], v0 offset:1040
	s_waitcnt lgkmcnt(6)
	v_pk_fma_f32 v[188:189], v[94:95], v[124:125], v[188:189] op_sel:[0,1,0] neg_lo:[1,0,0] neg_hi:[1,0,0]
	v_pk_fma_f32 v[190:191], v[96:97], v[124:125], v[190:191] op_sel:[0,1,0] neg_lo:[1,0,0] neg_hi:[1,0,0]
	ds_read_b128 v[90:93], v0 offset:1056
	s_waitcnt lgkmcnt(6)
	v_pk_fma_f32 v[192:193], v[98:99], v[124:125], v[192:193] op_sel:[0,1,0] neg_lo:[1,0,0] neg_hi:[1,0,0]
	v_pk_fma_f32 v[198:199], v[100:101], v[124:125], v[198:199] op_sel:[0,1,0] neg_lo:[1,0,0] neg_hi:[1,0,0]
	ds_read_b128 v[94:97], v0 offset:1072
	s_waitcnt lgkmcnt(6)
	v_pk_fma_f32 v[200:201], v[102:103], v[124:125], v[200:201] op_sel:[0,1,0] neg_lo:[1,0,0] neg_hi:[1,0,0]
	v_pk_fma_f32 v[202:203], v[104:105], v[124:125], v[202:203] op_sel:[0,1,0] neg_lo:[1,0,0] neg_hi:[1,0,0]
	ds_read_b128 v[98:101], v0 offset:1088
	s_waitcnt lgkmcnt(6)
	v_pk_fma_f32 v[204:205], v[106:107], v[124:125], v[204:205] op_sel:[0,1,0] neg_lo:[1,0,0] neg_hi:[1,0,0]
	v_pk_fma_f32 v[208:209], v[108:109], v[124:125], v[208:209] op_sel:[0,1,0] neg_lo:[1,0,0] neg_hi:[1,0,0]
	ds_read_b128 v[102:105], v0 offset:1104
	s_waitcnt lgkmcnt(6)
	v_pk_fma_f32 v[210:211], v[110:111], v[124:125], v[210:211] op_sel:[0,1,0] neg_lo:[1,0,0] neg_hi:[1,0,0]
	v_pk_fma_f32 v[212:213], v[112:113], v[124:125], v[212:213] op_sel:[0,1,0] neg_lo:[1,0,0] neg_hi:[1,0,0]
	ds_read_b128 v[106:109], v0 offset:1120
	s_waitcnt lgkmcnt(6)
	v_pk_fma_f32 v[214:215], v[114:115], v[124:125], v[214:215] op_sel:[0,1,0] neg_lo:[1,0,0] neg_hi:[1,0,0]
	v_pk_fma_f32 v[216:217], v[116:117], v[124:125], v[216:217] op_sel:[0,1,0] neg_lo:[1,0,0] neg_hi:[1,0,0]
	ds_read_b128 v[110:113], v0 offset:1136
	s_waitcnt lgkmcnt(6)
	v_pk_fma_f32 v[126:127], v[118:119], v[126:127], v[126:127] op_sel_hi:[1,0,1] neg_lo:[1,0,0] neg_hi:[1,0,0]
	v_pk_fma_f32 v[128:129], v[120:121], v[126:127], v[128:129] op_sel_hi:[1,0,1] neg_lo:[1,0,0] neg_hi:[1,0,0]
	ds_read_b128 v[114:117], v0 offset:1152
	s_waitcnt lgkmcnt(6)
; #define LAS __attribute__((address_space(3)))
; #define PIN16(o) asm volatile("" : "+v"(xr[o]), "+v"(xr[o + 1]), "+v"(xr[o + 2]), "+v"(xr[o + 3]), "+v"(xr[o + 4]), "+v"(xr[o + 5]), "+v"(xr[o + 6]), "+v"(xr[o + 7]), "+v"(xr[o + 8]), "+v"(xr[o + 9]), "+v"(xr[o + 10]), "+v"(xr[o + 11]), "+v"(xr[o + 12]), "+v"(xr[o + 13]), "+v"(xr[o + 14]), "+v"(xr[o + 15]) :: "memory")
; DI void gdn_prep_item(LAS unsigned char* lds, const Ctx& c, int l, int item) {
;     ...
; #pragma unroll
;         for (int j = 0; j < 63; ++j) {
;             const float xj = xr[j];
; #pragma unroll
;             for (int i4 = (j + 1) / 4; i4 < 16; ++i4) { const f32x4 Lv = *(const LAS f32x4*)(Lb + j * 64 + 4 * i4);
; #pragma unroll
;                 for (int q = 0; q < 4; ++q) xr[4 * i4 + q] -= Lv[q] * xj; }
;     ...
;             PIN16(0); PIN16(16); PIN16(32); PIN16(48);
	v_pk_fma_f32 v[156:157], v[90:91], v[126:127], v[156:157] op_sel_hi:[1,0,1] neg_lo:[1,0,0] neg_hi:[1,0,0]
	v_pk_fma_f32 v[158:159], v[92:93], v[126:127], v[158:159] op_sel_hi:[1,0,1] neg_lo:[1,0,0] neg_hi:[1,0,0]
	ds_read_b128 v[118:121], v0 offset:1168
	s_waitcnt lgkmcnt(6)
	v_pk_fma_f32 v[160:161], v[94:95], v[126:127], v[160:161] op_sel_hi:[1,0,1] neg_lo:[1,0,0] neg_hi:[1,0,0]
	v_pk_fma_f32 v[162:163], v[96:97], v[126:127], v[162:163] op_sel_hi:[1,0,1] neg_lo:[1,0,0] neg_hi:[1,0,0]
	ds_read_b128 v[90:93], v0 offset:1184
	s_waitcnt lgkmcnt(6)
	v_pk_fma_f32 v[164:165], v[98:99], v[126:127], v[164:165] op_sel_hi:[1,0,1] neg_lo:[1,0,0] neg_hi:[1,0,0]
	v_pk_fma_f32 v[166:167], v[100:101], v[126:127], v[166:167] op_sel_hi:[1,0,1] neg_lo:[1,0,0] neg_hi:[1,0,0]
	ds_read_b128 v[94:97], v0 offset:1200
	s_waitcnt lgkmcnt(6)
	v_pk_fma_f32 v[168:169], v[102:103], v[126:127], v[168:169] op_sel_hi:[1,0,1] neg_lo:[1,0,0] neg_hi:[1,0,0]
	v_pk_fma_f32 v[170:171], v[104:105], v[126:127], v[170:171] op_sel_hi:[1,0,1] neg_lo:[1,0,0] neg_hi:[1,0,0]
	ds_read_b128 v[98:101], v0 offset:1216
	s_waitcnt lgkmcnt(6)
	v_pk_fma_f32 v[172:173], v[106:107], v[126:127], v[172:173] op_sel_hi:[1,0,1] neg_lo:[1,0,0] neg_hi:[1,0,0]
	v_pk_fma_f32 v[174:175], v[108:109], v[126:127], v[174:175] op_sel_hi:[1,0,1] neg_lo:[1,0,0] neg_hi:[1,0,0]
	ds_read_b128 v[102:105], v0 offset:1232
	s_waitcnt lgkmcnt(6)
	v_pk_fma_f32 v[176:177], v[110:111], v[126:127], v[176:177] op_sel_hi:[1,0,1] neg_lo:[1,0,0] neg_hi:[1,0,0]
	v_pk_fma_f32 v[178:179], v[112:113], v[126:127], v[178:179] op_sel_hi:[1,0,1] neg_lo:[1,0,0] neg_hi:[1,0,0]
	ds_read_b128 v[106:109], v0 offset:1248
	s_waitcnt lgkmcnt(6)
	v_pk_fma_f32 v[180:181], v[114:115], v[126:127], v[180:181] op_sel_hi:[1,0,1] neg_lo:[1,0,0] neg_hi:[1,0,0]
	v_pk_fma_f32 v[182:183], v[116:117], v[126:127], v[182:183] op_sel_hi:[1,0,1] neg_lo:[1,0,0] neg_hi:[1,0,0]
	ds_read_b128 v[110:113], v0 offset:1264
	s_waitcnt lgkmcnt(6)
	v_pk_fma_f32 v[184:185], v[118:119], v[126:127], v[184:185] op_sel_hi:[1,0,1] neg_lo:[1,0,0] neg_hi:[1,0,0]
	v_pk_fma_f32 v[186:187], v[120:121], v[126:127], v[186:187] op_sel_hi:[1,0,1] neg_lo:[1,0,0] neg_hi:[1,0,0]
	ds_read_b128 v[114:117], v0 offset:1296
	s_waitcnt lgkmcnt(6)
	v_pk_fma_f32 v[188:189], v[90:91], v[126:127], v[188:189] op_sel_hi:[1,0,1] neg_lo:[1,0,0] neg_hi:[1,0,0]
	v_pk_fma_f32 v[190:191], v[92:93], v[126:127], v[190:191] op_sel_hi:[1,0,1] neg_lo:[1,0,0] neg_hi:[1,0,0]
	ds_read_b128 v[118:121], v0 offset:1312
	s_waitcnt lgkmcnt(6)
	v_pk_fma_f32 v[192:193], v[94:95], v[126:127], v[192:193] op_sel_hi:[1,0,1] neg_lo:[1,0,0] neg_hi:[1,0,0]
	v_pk_fma_f32 v[198:199], v[96:97], v[126:127], v[198:199] op_sel_hi:[1,0,1] neg_lo:[1,0,0] neg_hi:[1,0,0]
	ds_read_b128 v[90:93], v0 offset:1328
	s_waitcnt lgkmcnt(6)
	v_pk_fma_f32 v[200:201], v[98:99], v[126:127], v[200:201] op_sel_hi:[1,0,1] neg_lo:[1,0,0] neg_hi:[1,0,0]
	v_pk_fma_f32 v[202:203], v[100:101], v[126:127], v[202:203] op_sel_hi:[1,0,1] neg_lo:[1,0,0] neg_hi:[1,0,0]
	ds_read_b128 v[94:97], v0 offset:1344
	s_waitcnt lgkmcnt(6)
	v_pk_fma_f32 v[204:205], v[102:103], v[126:127], v[204:205] op_sel_hi:[1,0,1] neg_lo:[1,0,0] neg_hi:[1,0,0]
	v_pk_fma_f32 v[208:209], v[104:105], v[126:127], v[208:209] op_sel_hi:[1,0,1] neg_lo:[1,0,0] neg_hi:[1,0,0]
	ds_read_b128 v[98:101], v0 offset:1360
	s_waitcnt lgkmcnt(6)
	v_pk_fma_f32 v[210:211], v[106:107], v[126:127], v[210:211] op_sel_hi:[1,0,1] neg_lo:[1,0,0] neg_hi:[1,0,0]
	v_pk_fma_f32 v[212:213], v[108:109], v[126:127], v[212:213] op_sel_hi:[1,0,1] neg_lo:[1,0,0] neg_hi:[1,0,0]
	ds_read_b128 v[102:105], v0 offset:1376
	s_waitcnt lgkmcnt(6)
	v_pk_fma_f32 v[214:215], v[110:111], v[126:127], v[214:215] op_sel_hi:[1,0,1] neg_lo:[1,0,0] neg_hi:[1,0,0]
	v_pk_fma_f32 v[216:217], v[112:113], v[126:127], v[216:217] op_sel_hi:[1,0,1] neg_lo:[1,0,0] neg_hi:[1,0,0]
	ds_read_b128 v[106:109], v0 offset:1392
	s_waitcnt lgkmcnt(6)
	v_pk_fma_f32 v[128:129], v[116:117], v[126:127], v[128:129] op_sel:[0,1,0] neg_lo:[1,0,0] neg_hi:[1,0,0]
	ds_read_b128 v[110:113], v0 offset:1408
	s_waitcnt lgkmcnt(6)
	v_pk_fma_f32 v[156:157], v[118:119], v[126:127], v[156:157] op_sel:[0,1,0] neg_lo:[1,0,0] neg_hi:[1,0,0]
	v_pk_fma_f32 v[158:159], v[120:121], v[126:127], v[158:159] op_sel:[0,1,0] neg_lo:[1,0,0] neg_hi:[1,0,0]
	ds_read_b128 v[114:117], v0 offset:1424
	s_waitcnt lgkmcnt(6)
	v_pk_fma_f32 v[160:161], v[90:91], v[126:127], v[160:161] op_sel:[0,1,0] neg_lo:[1,0,0] neg_hi:[1,0,0]
	v_pk_fma_f32 v[162:163], v[92:93], v[126:127], v[162:163] op_sel:[0,1,0] neg_lo:[1,0,0] neg_hi:[1,0,0]
	ds_read_b128 v[118:121], v0 offset:1440
	s_waitcnt lgkmcnt(6)
	v_pk_fma_f32 v[164:165], v[94:95], v[126:127], v[164:165] op_sel:[0,1,0] neg_lo:[1,0,0] neg_hi:[1,0,0]
	v_pk_fma_f32 v[166:167], v[96:97], v[126:127], v[166:167] op_sel:[0,1,0] neg_lo:[1,0,0] neg_hi:[1,0,0]
	ds_read_b128 v[90:93], v0 offset:1456
	s_waitcnt lgkmcnt(6)
	v_pk_fma_f32 v[168:169], v[98:99], v[126:127], v[168:169] op_sel:[0,1,0] neg_lo:[1,0,0] neg_hi:[1,0,0]
	v_pk_fma_f32 v[170:171], v[100:101], v[126:127], v[170:171] op_sel:[0,1,0] neg_lo:[1,0,0] neg_hi:[1,0,0]
	ds_read_b128 v[94:97], v0 offset:1472
	s_waitcnt lgkmcnt(6)
	v_pk_fma_f32 v[172:173], v[102:103], v[126:127], v[172:173] op_sel:[0,1,0] neg_lo:[1,0,0] neg_hi:[1,0,0]
	v_pk_fma_f32 v[174:175], v[104:105], v[126:127], v[174:175] op_sel:[0,1,0] neg_lo:[1,0,0] neg_hi:[1,0,0]
	ds_read_b128 v[98:101], v0 offset:1488
	s_waitcnt lgkmcnt(6)
	v_pk_fma_f32 v[176:177], v[106:107], v[126:127], v[176:177] op_sel:[0,1,0] neg_lo:[1,0,0] neg_hi:[1,0,0]
	v_pk_fma_f32 v[178:179], v[108:109], v[126:127], v[178:179] op_sel:[0,1,0] neg_lo:[1,0,0] neg_hi:[1,0,0]
	ds_read_b128 v[102:105], v0 offset:1504
	s_waitcnt lgkmcnt(6)
; #define LAS __attribute__((address_space(3)))
; #define PIN16(o) asm volatile("" : "+v"(xr[o]), "+v"(xr[o + 1]), "+v"(xr[o + 2]), "+v"(xr[o + 3]), "+v"(xr[o + 4]), "+v"(xr[o + 5]), "+v"(xr[o + 6]), "+v"(xr[o + 7]), "+v"(xr[o + 8]), "+v"(xr[o + 9]), "+v"(xr[o + 10]), "+v"(xr[o + 11]), "+v"(xr[o + 12]), "+v"(xr[o + 13]), "+v"(xr[o + 14]), "+v"(xr[o + 15]) :: "memory")
; DI void gdn_prep_item(LAS unsigned char* lds, const Ctx& c, int l, int item) {
;     ...
; #pragma unroll
;         for (int j = 0; j < 63; ++j) {
;             const float xj = xr[j];
; #pragma unroll
;             for (int i4 = (j + 1) / 4; i4 < 16; ++i4) { const f32x4 Lv = *(const LAS f32x4*)(Lb + j * 64 + 4 * i4);
; #pragma unroll
;                 for (int q = 0; q < 4; ++q) xr[4 * i4 + q] -= Lv[q] * xj; }
;     ...
;             PIN16(0); PIN16(16); PIN16(32); PIN16(48);
	v_pk_fma_f32 v[180:181], v[110:111], v[126:127], v[180:181] op_sel:[0,1,0] neg_lo:[1,0,0] neg_hi:[1,0,0]
	v_pk_fma_f32 v[182:183], v[112:113], v[126:127], v[182:183] op_sel:[0,1,0] neg_lo:[1,0,0] neg_hi:[1,0,0]
	ds_read_b128 v[106:109], v0 offset:1520
	s_waitcnt lgkmcnt(6)
	v_pk_fma_f32 v[184:185], v[114:115], v[126:127], v[184:185] op_sel:[0,1,0] neg_lo:[1,0,0] neg_hi:[1,0,0]
	v_pk_fma_f32 v[186:187], v[116:117], v[126:127], v[186:187] op_sel:[0,1,0] neg_lo:[1,0,0] neg_hi:[1,0,0]
	ds_read_b128 v[110:113], v0 offset:1552
	s_waitcnt lgkmcnt(6)
	v_pk_fma_f32 v[188:189], v[118:119], v[126:127], v[188:189] op_sel:[0,1,0] neg_lo:[1,0,0] neg_hi:[1,0,0]
	v_pk_fma_f32 v[190:191], v[120:121], v[126:127], v[190:191] op_sel:[0,1,0] neg_lo:[1,0,0] neg_hi:[1,0,0]
	ds_read_b128 v[114:117], v0 offset:1568
	s_waitcnt lgkmcnt(6)
	v_pk_fma_f32 v[192:193], v[90:91], v[126:127], v[192:193] op_sel:[0,1,0] neg_lo:[1,0,0] neg_hi:[1,0,0]
	v_pk_fma_f32 v[198:199], v[92:93], v[126:127], v[198:199] op_sel:[0,1,0] neg_lo:[1,0,0] neg_hi:[1,0,0]
	ds_read_b128 v[118:121], v0 offset:1584
	s_waitcnt lgkmcnt(6)
	v_pk_fma_f32 v[200:201], v[94:95], v[126:127], v[200:201] op_sel:[0,1,0] neg_lo:[1,0,0] neg_hi:[1,0,0]
	v_pk_fma_f32 v[202:203], v[96:97], v[126:127], v[202:203] op_sel:[0,1,0] neg_lo:[1,0,0] neg_hi:[1,0,0]
	ds_read_b128 v[90:93], v0 offset:1600
	s_waitcnt lgkmcnt(6)
	v_pk_fma_f32 v[204:205], v[98:99], v[126:127], v[204:205] op_sel:[0,1,0] neg_lo:[1,0,0] neg_hi:[1,0,0]
	v_pk_fma_f32 v[208:209], v[100:101], v[126:127], v[208:209] op_sel:[0,1,0] neg_lo:[1,0,0] neg_hi:[1,0,0]
	ds_read_b128 v[94:97], v0 offset:1616
	s_waitcnt lgkmcnt(6)
	v_pk_fma_f32 v[210:211], v[102:103], v[126:127], v[210:211] op_sel:[0,1,0] neg_lo:[1,0,0] neg_hi:[1,0,0]
	v_pk_fma_f32 v[212:213], v[104:105], v[126:127], v[212:213] op_sel:[0,1,0] neg_lo:[1,0,0] neg_hi:[1,0,0]
	ds_read_b128 v[98:101], v0 offset:1632
	s_waitcnt lgkmcnt(6)
	v_pk_fma_f32 v[214:215], v[106:107], v[126:127], v[214:215] op_sel:[0,1,0] neg_lo:[1,0,0] neg_hi:[1,0,0]
	v_pk_fma_f32 v[216:217], v[108:109], v[126:127], v[216:217] op_sel:[0,1,0] neg_lo:[1,0,0] neg_hi:[1,0,0]
	ds_read_b128 v[102:105], v0 offset:1648
	s_waitcnt lgkmcnt(6)
	v_pk_fma_f32 v[128:129], v[112:113], v[128:129], v[128:129] op_sel_hi:[1,0,1] neg_lo:[1,0,0] neg_hi:[1,0,0]
	ds_read_b128 v[106:109], v0 offset:1664
	s_waitcnt lgkmcnt(6)
	v_pk_fma_f32 v[156:157], v[114:115], v[128:129], v[156:157] op_sel_hi:[1,0,1] neg_lo:[1,0,0] neg_hi:[1,0,0]
	v_pk_fma_f32 v[158:159], v[116:117], v[128:129], v[158:159] op_sel_hi:[1,0,1] neg_lo:[1,0,0] neg_hi:[1,0,0]
	ds_read_b128 v[110:113], v0 offset:1680
	s_waitcnt lgkmcnt(6)
	v_pk_fma_f32 v[160:161], v[118:119], v[128:129], v[160:161] op_sel_hi:[1,0,1] neg_lo:[1,0,0] neg_hi:[1,0,0]
	v_pk_fma_f32 v[162:163], v[120:121], v[128:129], v[162:163] op_sel_hi:[1,0,1] neg_lo:[1,0,0] neg_hi:[1,0,0]
	ds_read_b128 v[114:117], v0 offset:1696
	s_waitcnt lgkmcnt(6)
	v_pk_fma_f32 v[164:165], v[90:91], v[128:129], v[164:165] op_sel_hi:[1,0,1] neg_lo:[1,0,0] neg_hi:[1,0,0]
	v_pk_fma_f32 v[166:167], v[92:93], v[128:129], v[166:167] op_sel_hi:[1,0,1] neg_lo:[1,0,0] neg_hi:[1,0,0]
	ds_read_b128 v[118:121], v0 offset:1712
	s_waitcnt lgkmcnt(6)
	v_pk_fma_f32 v[168:169], v[94:95], v[128:129], v[168:169] op_sel_hi:[1,0,1] neg_lo:[1,0,0] neg_hi:[1,0,0]
	v_pk_fma_f32 v[170:171], v[96:97], v[128:129], v[170:171] op_sel_hi:[1,0,1] neg_lo:[1,0,0] neg_hi:[1,0,0]
	ds_read_b128 v[90:93], v0 offset:1728
	s_waitcnt lgkmcnt(6)
	v_pk_fma_f32 v[172:173], v[98:99], v[128:129], v[172:173] op_sel_hi:[1,0,1] neg_lo:[1,0,0] neg_hi:[1,0,0]
	v_pk_fma_f32 v[174:175], v[100:101], v[128:129], v[174:175] op_sel_hi:[1,0,1] neg_lo:[1,0,0] neg_hi:[1,0,0]
	ds_read_b128 v[94:97], v0 offset:1744
	s_waitcnt lgkmcnt(6)
	v_pk_fma_f32 v[176:177], v[102:103], v[128:129], v[176:177] op_sel_hi:[1,0,1] neg_lo:[1,0,0] neg_hi:[1,0,0]
	v_pk_fma_f32 v[178:179], v[104:105], v[128:129], v[178:179] op_sel_hi:[1,0,1] neg_lo:[1,0,0] neg_hi:[1,0,0]
	ds_read_b128 v[98:101], v0 offset:1760
	s_waitcnt lgkmcnt(6)
	v_pk_fma_f32 v[180:181], v[106:107], v[128:129], v[180:181] op_sel_hi:[1,0,1] neg_lo:[1,0,0] neg_hi:[1,0,0]
	v_pk_fma_f32 v[182:183], v[108:109], v[128:129], v[182:183] op_sel_hi:[1,0,1] neg_lo:[1,0,0] neg_hi:[1,0,0]
	ds_read_b128 v[102:105], v0 offset:1776
	s_waitcnt lgkmcnt(6)
	v_pk_fma_f32 v[184:185], v[110:111], v[128:129], v[184:185] op_sel_hi:[1,0,1] neg_lo:[1,0,0] neg_hi:[1,0,0]
	v_pk_fma_f32 v[186:187], v[112:113], v[128:129], v[186:187] op_sel_hi:[1,0,1] neg_lo:[1,0,0] neg_hi:[1,0,0]
	ds_read_b128 v[106:109], v0 offset:1824
	s_waitcnt lgkmcnt(6)
	v_pk_fma_f32 v[188:189], v[114:115], v[128:129], v[188:189] op_sel_hi:[1,0,1] neg_lo:[1,0,0] neg_hi:[1,0,0]
	v_pk_fma_f32 v[190:191], v[116:117], v[128:129], v[190:191] op_sel_hi:[1,0,1] neg_lo:[1,0,0] neg_hi:[1,0,0]
	ds_read_b128 v[110:113], v0 offset:1840
	s_waitcnt lgkmcnt(6)
	v_pk_fma_f32 v[192:193], v[118:119], v[128:129], v[192:193] op_sel_hi:[1,0,1] neg_lo:[1,0,0] neg_hi:[1,0,0]
	v_pk_fma_f32 v[198:199], v[120:121], v[128:129], v[198:199] op_sel_hi:[1,0,1] neg_lo:[1,0,0] neg_hi:[1,0,0]
	ds_read_b128 v[114:117], v0 offset:1856
	s_waitcnt lgkmcnt(6)
	v_pk_fma_f32 v[200:201], v[90:91], v[128:129], v[200:201] op_sel_hi:[1,0,1] neg_lo:[1,0,0] neg_hi:[1,0,0]
	v_pk_fma_f32 v[202:203], v[92:93], v[128:129], v[202:203] op_sel_hi:[1,0,1] neg_lo:[1,0,0] neg_hi:[1,0,0]
	ds_read_b128 v[118:121], v0 offset:1872
	s_waitcnt lgkmcnt(6)
	v_pk_fma_f32 v[204:205], v[94:95], v[128:129], v[204:205] op_sel_hi:[1,0,1] neg_lo:[1,0,0] neg_hi:[1,0,0]
	v_pk_fma_f32 v[208:209], v[96:97], v[128:129], v[208:209] op_sel_hi:[1,0,1] neg_lo:[1,0,0] neg_hi:[1,0,0]
	ds_read_b128 v[90:93], v0 offset:1888
	s_waitcnt lgkmcnt(6)
; #define LAS __attribute__((address_space(3)))
; #define PIN16(o) asm volatile("" : "+v"(xr[o]), "+v"(xr[o + 1]), "+v"(xr[o + 2]), "+v"(xr[o + 3]), "+v"(xr[o + 4]), "+v"(xr[o + 5]), "+v"(xr[o + 6]), "+v"(xr[o + 7]), "+v"(xr[o + 8]), "+v"(xr[o + 9]), "+v"(xr[o + 10]), "+v"(xr[o + 11]), "+v"(xr[o + 12]), "+v"(xr[o + 13]), "+v"(xr[o + 14]), "+v"(xr[o + 15]) :: "memory")
; DI void gdn_prep_item(LAS unsigned char* lds, const Ctx& c, int l, int item) {
;     ...
; #pragma unroll
;         for (int j = 0; j < 63; ++j) {
;             const float xj = xr[j];
; #pragma unroll
;             for (int i4 = (j + 1) / 4; i4 < 16; ++i4) { const f32x4 Lv = *(const LAS f32x4*)(Lb + j * 64 + 4 * i4);
; #pragma unroll
;                 for (int q = 0; q < 4; ++q) xr[4 * i4 + q] -= Lv[q] * xj; }
;     ...
;             PIN16(0); PIN16(16); PIN16(32); PIN16(48);
	v_pk_fma_f32 v[210:211], v[98:99], v[128:129], v[210:211] op_sel_hi:[1,0,1] neg_lo:[1,0,0] neg_hi:[1,0,0]
	v_pk_fma_f32 v[212:213], v[100:101], v[128:129], v[212:213] op_sel_hi:[1,0,1] neg_lo:[1,0,0] neg_hi:[1,0,0]
	ds_read_b128 v[94:97], v0 offset:1904
	s_waitcnt lgkmcnt(6)
	v_pk_fma_f32 v[214:215], v[102:103], v[128:129], v[214:215] op_sel_hi:[1,0,1] neg_lo:[1,0,0] neg_hi:[1,0,0]
	v_pk_fma_f32 v[216:217], v[104:105], v[128:129], v[216:217] op_sel_hi:[1,0,1] neg_lo:[1,0,0] neg_hi:[1,0,0]
	ds_read_b128 v[98:101], v0 offset:1920
	s_waitcnt lgkmcnt(6)
	v_pk_fma_f32 v[156:157], v[106:107], v[128:129], v[156:157] op_sel:[0,1,0] neg_lo:[1,0,0] neg_hi:[1,0,0]
	v_pk_fma_f32 v[158:159], v[108:109], v[128:129], v[158:159] op_sel:[0,1,0] neg_lo:[1,0,0] neg_hi:[1,0,0]
	ds_read_b128 v[102:105], v0 offset:1936
	s_waitcnt lgkmcnt(6)
	v_pk_fma_f32 v[160:161], v[110:111], v[128:129], v[160:161] op_sel:[0,1,0] neg_lo:[1,0,0] neg_hi:[1,0,0]
	v_pk_fma_f32 v[162:163], v[112:113], v[128:129], v[162:163] op_sel:[0,1,0] neg_lo:[1,0,0] neg_hi:[1,0,0]
	ds_read_b128 v[106:109], v0 offset:1952
	s_waitcnt lgkmcnt(6)
	v_pk_fma_f32 v[164:165], v[114:115], v[128:129], v[164:165] op_sel:[0,1,0] neg_lo:[1,0,0] neg_hi:[1,0,0]
	v_pk_fma_f32 v[166:167], v[116:117], v[128:129], v[166:167] op_sel:[0,1,0] neg_lo:[1,0,0] neg_hi:[1,0,0]
	ds_read_b128 v[110:113], v0 offset:1968
	s_waitcnt lgkmcnt(6)
	v_pk_fma_f32 v[168:169], v[118:119], v[128:129], v[168:169] op_sel:[0,1,0] neg_lo:[1,0,0] neg_hi:[1,0,0]
	v_pk_fma_f32 v[170:171], v[120:121], v[128:129], v[170:171] op_sel:[0,1,0] neg_lo:[1,0,0] neg_hi:[1,0,0]
	ds_read_b128 v[114:117], v0 offset:1984
	s_waitcnt lgkmcnt(6)
	v_pk_fma_f32 v[172:173], v[90:91], v[128:129], v[172:173] op_sel:[0,1,0] neg_lo:[1,0,0] neg_hi:[1,0,0]
	v_pk_fma_f32 v[174:175], v[92:93], v[128:129], v[174:175] op_sel:[0,1,0] neg_lo:[1,0,0] neg_hi:[1,0,0]
	ds_read_b128 v[118:121], v0 offset:2000
	s_waitcnt lgkmcnt(6)
	v_pk_fma_f32 v[176:177], v[94:95], v[128:129], v[176:177] op_sel:[0,1,0] neg_lo:[1,0,0] neg_hi:[1,0,0]
	v_pk_fma_f32 v[178:179], v[96:97], v[128:129], v[178:179] op_sel:[0,1,0] neg_lo:[1,0,0] neg_hi:[1,0,0]
	ds_read_b128 v[90:93], v0 offset:2016
	s_waitcnt lgkmcnt(6)
	v_pk_fma_f32 v[180:181], v[98:99], v[128:129], v[180:181] op_sel:[0,1,0] neg_lo:[1,0,0] neg_hi:[1,0,0]
	v_pk_fma_f32 v[182:183], v[100:101], v[128:129], v[182:183] op_sel:[0,1,0] neg_lo:[1,0,0] neg_hi:[1,0,0]
	ds_read_b128 v[94:97], v0 offset:2032
	s_waitcnt lgkmcnt(6)
	v_pk_fma_f32 v[184:185], v[102:103], v[128:129], v[184:185] op_sel:[0,1,0] neg_lo:[1,0,0] neg_hi:[1,0,0]
	v_pk_fma_f32 v[186:187], v[104:105], v[128:129], v[186:187] op_sel:[0,1,0] neg_lo:[1,0,0] neg_hi:[1,0,0]
	ds_read_b128 v[98:101], v0 offset:2080
	s_waitcnt lgkmcnt(6)
	v_pk_fma_f32 v[188:189], v[106:107], v[128:129], v[188:189] op_sel:[0,1,0] neg_lo:[1,0,0] neg_hi:[1,0,0]
	v_pk_fma_f32 v[190:191], v[108:109], v[128:129], v[190:191] op_sel:[0,1,0] neg_lo:[1,0,0] neg_hi:[1,0,0]
	ds_read_b128 v[102:105], v0 offset:2096
	s_waitcnt lgkmcnt(6)
	v_pk_fma_f32 v[192:193], v[110:111], v[128:129], v[192:193] op_sel:[0,1,0] neg_lo:[1,0,0] neg_hi:[1,0,0]
	v_pk_fma_f32 v[198:199], v[112:113], v[128:129], v[198:199] op_sel:[0,1,0] neg_lo:[1,0,0] neg_hi:[1,0,0]
	ds_read_b128 v[106:109], v0 offset:2112
	s_waitcnt lgkmcnt(6)
	v_pk_fma_f32 v[200:201], v[114:115], v[128:129], v[200:201] op_sel:[0,1,0] neg_lo:[1,0,0] neg_hi:[1,0,0]
	v_pk_fma_f32 v[202:203], v[116:117], v[128:129], v[202:203] op_sel:[0,1,0] neg_lo:[1,0,0] neg_hi:[1,0,0]
	ds_read_b128 v[110:113], v0 offset:2128
	s_waitcnt lgkmcnt(6)
	v_pk_fma_f32 v[204:205], v[118:119], v[128:129], v[204:205] op_sel:[0,1,0] neg_lo:[1,0,0] neg_hi:[1,0,0]
	v_pk_fma_f32 v[208:209], v[120:121], v[128:129], v[208:209] op_sel:[0,1,0] neg_lo:[1,0,0] neg_hi:[1,0,0]
	ds_read_b128 v[114:117], v0 offset:2144
	s_waitcnt lgkmcnt(6)
	v_pk_fma_f32 v[210:211], v[90:91], v[128:129], v[210:211] op_sel:[0,1,0] neg_lo:[1,0,0] neg_hi:[1,0,0]
	v_pk_fma_f32 v[212:213], v[92:93], v[128:129], v[212:213] op_sel:[0,1,0] neg_lo:[1,0,0] neg_hi:[1,0,0]
	ds_read_b128 v[118:121], v0 offset:2160
	s_waitcnt lgkmcnt(6)
	v_pk_fma_f32 v[214:215], v[94:95], v[128:129], v[214:215] op_sel:[0,1,0] neg_lo:[1,0,0] neg_hi:[1,0,0]
	v_pk_fma_f32 v[216:217], v[96:97], v[128:129], v[216:217] op_sel:[0,1,0] neg_lo:[1,0,0] neg_hi:[1,0,0]
	ds_read_b128 v[90:93], v0 offset:2176
	s_waitcnt lgkmcnt(6)
	v_pk_fma_f32 v[156:157], v[98:99], v[156:157], v[156:157] op_sel_hi:[1,0,1] neg_lo:[1,0,0] neg_hi:[1,0,0]
	v_pk_fma_f32 v[158:159], v[100:101], v[156:157], v[158:159] op_sel_hi:[1,0,1] neg_lo:[1,0,0] neg_hi:[1,0,0]
	ds_read_b128 v[94:97], v0 offset:2192
	s_waitcnt lgkmcnt(6)
	v_pk_fma_f32 v[160:161], v[102:103], v[156:157], v[160:161] op_sel_hi:[1,0,1] neg_lo:[1,0,0] neg_hi:[1,0,0]
	v_pk_fma_f32 v[162:163], v[104:105], v[156:157], v[162:163] op_sel_hi:[1,0,1] neg_lo:[1,0,0] neg_hi:[1,0,0]
	ds_read_b128 v[98:101], v0 offset:2208
	s_waitcnt lgkmcnt(6)
	v_pk_fma_f32 v[164:165], v[106:107], v[156:157], v[164:165] op_sel_hi:[1,0,1] neg_lo:[1,0,0] neg_hi:[1,0,0]
	v_pk_fma_f32 v[166:167], v[108:109], v[156:157], v[166:167] op_sel_hi:[1,0,1] neg_lo:[1,0,0] neg_hi:[1,0,0]
	ds_read_b128 v[102:105], v0 offset:2224
	s_waitcnt lgkmcnt(6)
	v_pk_fma_f32 v[168:169], v[110:111], v[156:157], v[168:169] op_sel_hi:[1,0,1] neg_lo:[1,0,0] neg_hi:[1,0,0]
	v_pk_fma_f32 v[170:171], v[112:113], v[156:157], v[170:171] op_sel_hi:[1,0,1] neg_lo:[1,0,0] neg_hi:[1,0,0]
	ds_read_b128 v[106:109], v0 offset:2240
	s_waitcnt lgkmcnt(6)
; #define LAS __attribute__((address_space(3)))
; #define PIN16(o) asm volatile("" : "+v"(xr[o]), "+v"(xr[o + 1]), "+v"(xr[o + 2]), "+v"(xr[o + 3]), "+v"(xr[o + 4]), "+v"(xr[o + 5]), "+v"(xr[o + 6]), "+v"(xr[o + 7]), "+v"(xr[o + 8]), "+v"(xr[o + 9]), "+v"(xr[o + 10]), "+v"(xr[o + 11]), "+v"(xr[o + 12]), "+v"(xr[o + 13]), "+v"(xr[o + 14]), "+v"(xr[o + 15]) :: "memory")
; DI void gdn_prep_item(LAS unsigned char* lds, const Ctx& c, int l, int item) {
;     ...
; #pragma unroll
;         for (int j = 0; j < 63; ++j) {
;             const float xj = xr[j];
; #pragma unroll
;             for (int i4 = (j + 1) / 4; i4 < 16; ++i4) { const f32x4 Lv = *(const LAS f32x4*)(Lb + j * 64 + 4 * i4);
; #pragma unroll
;                 for (int q = 0; q < 4; ++q) xr[4 * i4 + q] -= Lv[q] * xj; }
;     ...
;             PIN16(0); PIN16(16); PIN16(32); PIN16(48);
	v_pk_fma_f32 v[172:173], v[114:115], v[156:157], v[172:173] op_sel_hi:[1,0,1] neg_lo:[1,0,0] neg_hi:[1,0,0]
	v_pk_fma_f32 v[174:175], v[116:117], v[156:157], v[174:175] op_sel_hi:[1,0,1] neg_lo:[1,0,0] neg_hi:[1,0,0]
	ds_read_b128 v[110:113], v0 offset:2256
	s_waitcnt lgkmcnt(6)
	v_pk_fma_f32 v[176:177], v[118:119], v[156:157], v[176:177] op_sel_hi:[1,0,1] neg_lo:[1,0,0] neg_hi:[1,0,0]
	v_pk_fma_f32 v[178:179], v[120:121], v[156:157], v[178:179] op_sel_hi:[1,0,1] neg_lo:[1,0,0] neg_hi:[1,0,0]
	ds_read_b128 v[114:117], v0 offset:2272
	s_waitcnt lgkmcnt(6)
	v_pk_fma_f32 v[180:181], v[90:91], v[156:157], v[180:181] op_sel_hi:[1,0,1] neg_lo:[1,0,0] neg_hi:[1,0,0]
	v_pk_fma_f32 v[182:183], v[92:93], v[156:157], v[182:183] op_sel_hi:[1,0,1] neg_lo:[1,0,0] neg_hi:[1,0,0]
	ds_read_b128 v[118:121], v0 offset:2288
	s_waitcnt lgkmcnt(6)
	v_pk_fma_f32 v[184:185], v[94:95], v[156:157], v[184:185] op_sel_hi:[1,0,1] neg_lo:[1,0,0] neg_hi:[1,0,0]
	v_pk_fma_f32 v[186:187], v[96:97], v[156:157], v[186:187] op_sel_hi:[1,0,1] neg_lo:[1,0,0] neg_hi:[1,0,0]
	ds_read_b128 v[90:93], v0 offset:2336
	s_waitcnt lgkmcnt(6)
	v_pk_fma_f32 v[188:189], v[98:99], v[156:157], v[188:189] op_sel_hi:[1,0,1] neg_lo:[1,0,0] neg_hi:[1,0,0]
	v_pk_fma_f32 v[190:191], v[100:101], v[156:157], v[190:191] op_sel_hi:[1,0,1] neg_lo:[1,0,0] neg_hi:[1,0,0]
	ds_read_b128 v[94:97], v0 offset:2352
	s_waitcnt lgkmcnt(6)
	v_pk_fma_f32 v[192:193], v[102:103], v[156:157], v[192:193] op_sel_hi:[1,0,1] neg_lo:[1,0,0] neg_hi:[1,0,0]
	v_pk_fma_f32 v[198:199], v[104:105], v[156:157], v[198:199] op_sel_hi:[1,0,1] neg_lo:[1,0,0] neg_hi:[1,0,0]
	ds_read_b128 v[98:101], v0 offset:2368
	s_waitcnt lgkmcnt(6)
	v_pk_fma_f32 v[200:201], v[106:107], v[156:157], v[200:201] op_sel_hi:[1,0,1] neg_lo:[1,0,0] neg_hi:[1,0,0]
	v_pk_fma_f32 v[202:203], v[108:109], v[156:157], v[202:203] op_sel_hi:[1,0,1] neg_lo:[1,0,0] neg_hi:[1,0,0]
	ds_read_b128 v[102:105], v0 offset:2384
	s_waitcnt lgkmcnt(6)
	v_pk_fma_f32 v[204:205], v[110:111], v[156:157], v[204:205] op_sel_hi:[1,0,1] neg_lo:[1,0,0] neg_hi:[1,0,0]
	v_pk_fma_f32 v[208:209], v[112:113], v[156:157], v[208:209] op_sel_hi:[1,0,1] neg_lo:[1,0,0] neg_hi:[1,0,0]
	ds_read_b128 v[106:109], v0 offset:2400
	s_waitcnt lgkmcnt(6)
	v_pk_fma_f32 v[210:211], v[114:115], v[156:157], v[210:211] op_sel_hi:[1,0,1] neg_lo:[1,0,0] neg_hi:[1,0,0]
	v_pk_fma_f32 v[212:213], v[116:117], v[156:157], v[212:213] op_sel_hi:[1,0,1] neg_lo:[1,0,0] neg_hi:[1,0,0]
	ds_read_b128 v[110:113], v0 offset:2416
	s_waitcnt lgkmcnt(6)
	v_pk_fma_f32 v[214:215], v[118:119], v[156:157], v[214:215] op_sel_hi:[1,0,1] neg_lo:[1,0,0] neg_hi:[1,0,0]
	v_pk_fma_f32 v[216:217], v[120:121], v[156:157], v[216:217] op_sel_hi:[1,0,1] neg_lo:[1,0,0] neg_hi:[1,0,0]
	ds_read_b128 v[114:117], v0 offset:2432
	s_waitcnt lgkmcnt(6)
	v_pk_fma_f32 v[158:159], v[92:93], v[156:157], v[158:159] op_sel:[0,1,0] neg_lo:[1,0,0] neg_hi:[1,0,0]
	ds_read_b128 v[118:121], v0 offset:2448
	s_waitcnt lgkmcnt(6)
	v_pk_fma_f32 v[160:161], v[94:95], v[156:157], v[160:161] op_sel:[0,1,0] neg_lo:[1,0,0] neg_hi:[1,0,0]
	v_pk_fma_f32 v[162:163], v[96:97], v[156:157], v[162:163] op_sel:[0,1,0] neg_lo:[1,0,0] neg_hi:[1,0,0]
	ds_read_b128 v[90:93], v0 offset:2464
	s_waitcnt lgkmcnt(6)
	v_pk_fma_f32 v[164:165], v[98:99], v[156:157], v[164:165] op_sel:[0,1,0] neg_lo:[1,0,0] neg_hi:[1,0,0]
	v_pk_fma_f32 v[166:167], v[100:101], v[156:157], v[166:167] op_sel:[0,1,0] neg_lo:[1,0,0] neg_hi:[1,0,0]
	ds_read_b128 v[94:97], v0 offset:2480
	s_waitcnt lgkmcnt(6)
	v_pk_fma_f32 v[168:169], v[102:103], v[156:157], v[168:169] op_sel:[0,1,0] neg_lo:[1,0,0] neg_hi:[1,0,0]
	v_pk_fma_f32 v[170:171], v[104:105], v[156:157], v[170:171] op_sel:[0,1,0] neg_lo:[1,0,0] neg_hi:[1,0,0]
	ds_read_b128 v[98:101], v0 offset:2496
	s_waitcnt lgkmcnt(6)
	v_pk_fma_f32 v[172:173], v[106:107], v[156:157], v[172:173] op_sel:[0,1,0] neg_lo:[1,0,0] neg_hi:[1,0,0]
	v_pk_fma_f32 v[174:175], v[108:109], v[156:157], v[174:175] op_sel:[0,1,0] neg_lo:[1,0,0] neg_hi:[1,0,0]
	ds_read_b128 v[102:105], v0 offset:2512
	s_waitcnt lgkmcnt(6)
	v_pk_fma_f32 v[176:177], v[110:111], v[156:157], v[176:177] op_sel:[0,1,0] neg_lo:[1,0,0] neg_hi:[1,0,0]
	v_pk_fma_f32 v[178:179], v[112:113], v[156:157], v[178:179] op_sel:[0,1,0] neg_lo:[1,0,0] neg_hi:[1,0,0]
	ds_read_b128 v[106:109], v0 offset:2528
	s_waitcnt lgkmcnt(6)
	v_pk_fma_f32 v[180:181], v[114:115], v[156:157], v[180:181] op_sel:[0,1,0] neg_lo:[1,0,0] neg_hi:[1,0,0]
	v_pk_fma_f32 v[182:183], v[116:117], v[156:157], v[182:183] op_sel:[0,1,0] neg_lo:[1,0,0] neg_hi:[1,0,0]
	ds_read_b128 v[110:113], v0 offset:2544
	s_waitcnt lgkmcnt(6)
	v_pk_fma_f32 v[184:185], v[118:119], v[156:157], v[184:185] op_sel:[0,1,0] neg_lo:[1,0,0] neg_hi:[1,0,0]
	v_pk_fma_f32 v[186:187], v[120:121], v[156:157], v[186:187] op_sel:[0,1,0] neg_lo:[1,0,0] neg_hi:[1,0,0]
	ds_read_b128 v[114:117], v0 offset:2592
	s_waitcnt lgkmcnt(6)
	v_pk_fma_f32 v[188:189], v[90:91], v[156:157], v[188:189] op_sel:[0,1,0] neg_lo:[1,0,0] neg_hi:[1,0,0]
	v_pk_fma_f32 v[190:191], v[92:93], v[156:157], v[190:191] op_sel:[0,1,0] neg_lo:[1,0,0] neg_hi:[1,0,0]
	ds_read_b128 v[118:121], v0 offset:2608
	s_waitcnt lgkmcnt(6)
	v_pk_fma_f32 v[192:193], v[94:95], v[156:157], v[192:193] op_sel:[0,1,0] neg_lo:[1,0,0] neg_hi:[1,0,0]
	v_pk_fma_f32 v[198:199], v[96:97], v[156:157], v[198:199] op_sel:[0,1,0] neg_lo:[1,0,0] neg_hi:[1,0,0]
	ds_read_b128 v[90:93], v0 offset:2624
	s_waitcnt lgkmcnt(6)
	v_pk_fma_f32 v[200:201], v[98:99], v[156:157], v[200:201] op_sel:[0,1,0] neg_lo:[1,0,0] neg_hi:[1,0,0]
	v_pk_fma_f32 v[202:203], v[100:101], v[156:157], v[202:203] op_sel:[0,1,0] neg_lo:[1,0,0] neg_hi:[1,0,0]
	ds_read_b128 v[94:97], v0 offset:2640
	s_waitcnt lgkmcnt(6)
; #define LAS __attribute__((address_space(3)))
; #define PIN16(o) asm volatile("" : "+v"(xr[o]), "+v"(xr[o + 1]), "+v"(xr[o + 2]), "+v"(xr[o + 3]), "+v"(xr[o + 4]), "+v"(xr[o + 5]), "+v"(xr[o + 6]), "+v"(xr[o + 7]), "+v"(xr[o + 8]), "+v"(xr[o + 9]), "+v"(xr[o + 10]), "+v"(xr[o + 11]), "+v"(xr[o + 12]), "+v"(xr[o + 13]), "+v"(xr[o + 14]), "+v"(xr[o + 15]) :: "memory")
; DI void gdn_prep_item(LAS unsigned char* lds, const Ctx& c, int l, int item) {
;     ...
; #pragma unroll
;         for (int j = 0; j < 63; ++j) {
;             const float xj = xr[j];
; #pragma unroll
;             for (int i4 = (j + 1) / 4; i4 < 16; ++i4) { const f32x4 Lv = *(const LAS f32x4*)(Lb + j * 64 + 4 * i4);
; #pragma unroll
;                 for (int q = 0; q < 4; ++q) xr[4 * i4 + q] -= Lv[q] * xj; }
;     ...
;             PIN16(0); PIN16(16); PIN16(32); PIN16(48);
	v_pk_fma_f32 v[204:205], v[102:103], v[156:157], v[204:205] op_sel:[0,1,0] neg_lo:[1,0,0] neg_hi:[1,0,0]
	v_pk_fma_f32 v[208:209], v[104:105], v[156:157], v[208:209] op_sel:[0,1,0] neg_lo:[1,0,0] neg_hi:[1,0,0]
	ds_read_b128 v[98:101], v0 offset:2656
	s_waitcnt lgkmcnt(6)
	v_pk_fma_f32 v[210:211], v[106:107], v[156:157], v[210:211] op_sel:[0,1,0] neg_lo:[1,0,0] neg_hi:[1,0,0]
	v_pk_fma_f32 v[212:213], v[108:109], v[156:157], v[212:213] op_sel:[0,1,0] neg_lo:[1,0,0] neg_hi:[1,0,0]
	ds_read_b128 v[102:105], v0 offset:2672
	s_waitcnt lgkmcnt(6)
	v_pk_fma_f32 v[214:215], v[110:111], v[156:157], v[214:215] op_sel:[0,1,0] neg_lo:[1,0,0] neg_hi:[1,0,0]
	v_pk_fma_f32 v[216:217], v[112:113], v[156:157], v[216:217] op_sel:[0,1,0] neg_lo:[1,0,0] neg_hi:[1,0,0]
	ds_read_b128 v[106:109], v0 offset:2688
	s_waitcnt lgkmcnt(6)
	v_pk_fma_f32 v[158:159], v[116:117], v[158:159], v[158:159] op_sel_hi:[1,0,1] neg_lo:[1,0,0] neg_hi:[1,0,0]
	ds_read_b128 v[110:113], v0 offset:2704
	s_waitcnt lgkmcnt(6)
	v_pk_fma_f32 v[160:161], v[118:119], v[158:159], v[160:161] op_sel_hi:[1,0,1] neg_lo:[1,0,0] neg_hi:[1,0,0]
	v_pk_fma_f32 v[162:163], v[120:121], v[158:159], v[162:163] op_sel_hi:[1,0,1] neg_lo:[1,0,0] neg_hi:[1,0,0]
	ds_read_b128 v[114:117], v0 offset:2720
	s_waitcnt lgkmcnt(6)
	v_pk_fma_f32 v[164:165], v[90:91], v[158:159], v[164:165] op_sel_hi:[1,0,1] neg_lo:[1,0,0] neg_hi:[1,0,0]
	v_pk_fma_f32 v[166:167], v[92:93], v[158:159], v[166:167] op_sel_hi:[1,0,1] neg_lo:[1,0,0] neg_hi:[1,0,0]
	ds_read_b128 v[118:121], v0 offset:2736
	s_waitcnt lgkmcnt(6)
	v_pk_fma_f32 v[168:169], v[94:95], v[158:159], v[168:169] op_sel_hi:[1,0,1] neg_lo:[1,0,0] neg_hi:[1,0,0]
	v_pk_fma_f32 v[170:171], v[96:97], v[158:159], v[170:171] op_sel_hi:[1,0,1] neg_lo:[1,0,0] neg_hi:[1,0,0]
	ds_read_b128 v[90:93], v0 offset:2752
	s_waitcnt lgkmcnt(6)
	v_pk_fma_f32 v[172:173], v[98:99], v[158:159], v[172:173] op_sel_hi:[1,0,1] neg_lo:[1,0,0] neg_hi:[1,0,0]
	v_pk_fma_f32 v[174:175], v[100:101], v[158:159], v[174:175] op_sel_hi:[1,0,1] neg_lo:[1,0,0] neg_hi:[1,0,0]
	ds_read_b128 v[94:97], v0 offset:2768
	s_waitcnt lgkmcnt(6)
	v_pk_fma_f32 v[176:177], v[102:103], v[158:159], v[176:177] op_sel_hi:[1,0,1] neg_lo:[1,0,0] neg_hi:[1,0,0]
	v_pk_fma_f32 v[178:179], v[104:105], v[158:159], v[178:179] op_sel_hi:[1,0,1] neg_lo:[1,0,0] neg_hi:[1,0,0]
	ds_read_b128 v[98:101], v0 offset:2784
	s_waitcnt lgkmcnt(6)
	v_pk_fma_f32 v[180:181], v[106:107], v[158:159], v[180:181] op_sel_hi:[1,0,1] neg_lo:[1,0,0] neg_hi:[1,0,0]
	v_pk_fma_f32 v[182:183], v[108:109], v[158:159], v[182:183] op_sel_hi:[1,0,1] neg_lo:[1,0,0] neg_hi:[1,0,0]
	ds_read_b128 v[102:105], v0 offset:2800
	s_waitcnt lgkmcnt(6)
	v_pk_fma_f32 v[184:185], v[110:111], v[158:159], v[184:185] op_sel_hi:[1,0,1] neg_lo:[1,0,0] neg_hi:[1,0,0]
	v_pk_fma_f32 v[186:187], v[112:113], v[158:159], v[186:187] op_sel_hi:[1,0,1] neg_lo:[1,0,0] neg_hi:[1,0,0]
	ds_read_b128 v[106:109], v0 offset:2864
	s_waitcnt lgkmcnt(6)
	v_pk_fma_f32 v[188:189], v[114:115], v[158:159], v[188:189] op_sel_hi:[1,0,1] neg_lo:[1,0,0] neg_hi:[1,0,0]
	v_pk_fma_f32 v[190:191], v[116:117], v[158:159], v[190:191] op_sel_hi:[1,0,1] neg_lo:[1,0,0] neg_hi:[1,0,0]
	ds_read_b128 v[110:113], v0 offset:2880
	s_waitcnt lgkmcnt(6)
	v_pk_fma_f32 v[192:193], v[118:119], v[158:159], v[192:193] op_sel_hi:[1,0,1] neg_lo:[1,0,0] neg_hi:[1,0,0]
	v_pk_fma_f32 v[198:199], v[120:121], v[158:159], v[198:199] op_sel_hi:[1,0,1] neg_lo:[1,0,0] neg_hi:[1,0,0]
	ds_read_b128 v[114:117], v0 offset:2896
	s_waitcnt lgkmcnt(6)
	v_pk_fma_f32 v[200:201], v[90:91], v[158:159], v[200:201] op_sel_hi:[1,0,1] neg_lo:[1,0,0] neg_hi:[1,0,0]
	v_pk_fma_f32 v[202:203], v[92:93], v[158:159], v[202:203] op_sel_hi:[1,0,1] neg_lo:[1,0,0] neg_hi:[1,0,0]
	ds_read_b128 v[118:121], v0 offset:2912
	s_waitcnt lgkmcnt(6)
	v_pk_fma_f32 v[204:205], v[94:95], v[158:159], v[204:205] op_sel_hi:[1,0,1] neg_lo:[1,0,0] neg_hi:[1,0,0]
	v_pk_fma_f32 v[208:209], v[96:97], v[158:159], v[208:209] op_sel_hi:[1,0,1] neg_lo:[1,0,0] neg_hi:[1,0,0]
	ds_read_b128 v[90:93], v0 offset:2928
	s_waitcnt lgkmcnt(6)
	v_pk_fma_f32 v[210:211], v[98:99], v[158:159], v[210:211] op_sel_hi:[1,0,1] neg_lo:[1,0,0] neg_hi:[1,0,0]
	v_pk_fma_f32 v[212:213], v[100:101], v[158:159], v[212:213] op_sel_hi:[1,0,1] neg_lo:[1,0,0] neg_hi:[1,0,0]
	ds_read_b128 v[94:97], v0 offset:2944
	s_waitcnt lgkmcnt(6)
	v_pk_fma_f32 v[214:215], v[102:103], v[158:159], v[214:215] op_sel_hi:[1,0,1] neg_lo:[1,0,0] neg_hi:[1,0,0]
	v_pk_fma_f32 v[216:217], v[104:105], v[158:159], v[216:217] op_sel_hi:[1,0,1] neg_lo:[1,0,0] neg_hi:[1,0,0]
	ds_read_b128 v[98:101], v0 offset:2960
	s_waitcnt lgkmcnt(6)
	v_pk_fma_f32 v[160:161], v[106:107], v[158:159], v[160:161] op_sel:[0,1,0] neg_lo:[1,0,0] neg_hi:[1,0,0]
	v_pk_fma_f32 v[162:163], v[108:109], v[158:159], v[162:163] op_sel:[0,1,0] neg_lo:[1,0,0] neg_hi:[1,0,0]
	ds_read_b128 v[102:105], v0 offset:2976
	s_waitcnt lgkmcnt(6)
	v_pk_fma_f32 v[164:165], v[110:111], v[158:159], v[164:165] op_sel:[0,1,0] neg_lo:[1,0,0] neg_hi:[1,0,0]
	v_pk_fma_f32 v[166:167], v[112:113], v[158:159], v[166:167] op_sel:[0,1,0] neg_lo:[1,0,0] neg_hi:[1,0,0]
	ds_read_b128 v[106:109], v0 offset:2992
	s_waitcnt lgkmcnt(6)
	v_pk_fma_f32 v[168:169], v[114:115], v[158:159], v[168:169] op_sel:[0,1,0] neg_lo:[1,0,0] neg_hi:[1,0,0]
	v_pk_fma_f32 v[170:171], v[116:117], v[158:159], v[170:171] op_sel:[0,1,0] neg_lo:[1,0,0] neg_hi:[1,0,0]
	ds_read_b128 v[110:113], v0 offset:3008
	s_waitcnt lgkmcnt(6)
	v_pk_fma_f32 v[172:173], v[118:119], v[158:159], v[172:173] op_sel:[0,1,0] neg_lo:[1,0,0] neg_hi:[1,0,0]
	v_pk_fma_f32 v[174:175], v[120:121], v[158:159], v[174:175] op_sel:[0,1,0] neg_lo:[1,0,0] neg_hi:[1,0,0]
	ds_read_b128 v[114:117], v0 offset:3024
	s_waitcnt lgkmcnt(6)
; #define LAS __attribute__((address_space(3)))
; #define PIN16(o) asm volatile("" : "+v"(xr[o]), "+v"(xr[o + 1]), "+v"(xr[o + 2]), "+v"(xr[o + 3]), "+v"(xr[o + 4]), "+v"(xr[o + 5]), "+v"(xr[o + 6]), "+v"(xr[o + 7]), "+v"(xr[o + 8]), "+v"(xr[o + 9]), "+v"(xr[o + 10]), "+v"(xr[o + 11]), "+v"(xr[o + 12]), "+v"(xr[o + 13]), "+v"(xr[o + 14]), "+v"(xr[o + 15]) :: "memory")
; DI void gdn_prep_item(LAS unsigned char* lds, const Ctx& c, int l, int item) {
;     ...
; #pragma unroll
;         for (int j = 0; j < 63; ++j) {
;             const float xj = xr[j];
; #pragma unroll
;             for (int i4 = (j + 1) / 4; i4 < 16; ++i4) { const f32x4 Lv = *(const LAS f32x4*)(Lb + j * 64 + 4 * i4);
; #pragma unroll
;                 for (int q = 0; q < 4; ++q) xr[4 * i4 + q] -= Lv[q] * xj; }
;     ...
;             PIN16(0); PIN16(16); PIN16(32); PIN16(48);
	v_pk_fma_f32 v[176:177], v[90:91], v[158:159], v[176:177] op_sel:[0,1,0] neg_lo:[1,0,0] neg_hi:[1,0,0]
	v_pk_fma_f32 v[178:179], v[92:93], v[158:159], v[178:179] op_sel:[0,1,0] neg_lo:[1,0,0] neg_hi:[1,0,0]
	ds_read_b128 v[118:121], v0 offset:3040
	s_waitcnt lgkmcnt(6)
	v_pk_fma_f32 v[180:181], v[94:95], v[158:159], v[180:181] op_sel:[0,1,0] neg_lo:[1,0,0] neg_hi:[1,0,0]
	v_pk_fma_f32 v[182:183], v[96:97], v[158:159], v[182:183] op_sel:[0,1,0] neg_lo:[1,0,0] neg_hi:[1,0,0]
	ds_read_b128 v[90:93], v0 offset:3056
	s_waitcnt lgkmcnt(6)
	v_pk_fma_f32 v[184:185], v[98:99], v[158:159], v[184:185] op_sel:[0,1,0] neg_lo:[1,0,0] neg_hi:[1,0,0]
	v_pk_fma_f32 v[186:187], v[100:101], v[158:159], v[186:187] op_sel:[0,1,0] neg_lo:[1,0,0] neg_hi:[1,0,0]
	ds_read_b128 v[94:97], v0 offset:3120
	s_waitcnt lgkmcnt(6)
	v_pk_fma_f32 v[188:189], v[102:103], v[158:159], v[188:189] op_sel:[0,1,0] neg_lo:[1,0,0] neg_hi:[1,0,0]
	v_pk_fma_f32 v[190:191], v[104:105], v[158:159], v[190:191] op_sel:[0,1,0] neg_lo:[1,0,0] neg_hi:[1,0,0]
	ds_read_b128 v[98:101], v0 offset:3136
	s_waitcnt lgkmcnt(6)
	v_pk_fma_f32 v[192:193], v[106:107], v[158:159], v[192:193] op_sel:[0,1,0] neg_lo:[1,0,0] neg_hi:[1,0,0]
	v_pk_fma_f32 v[198:199], v[108:109], v[158:159], v[198:199] op_sel:[0,1,0] neg_lo:[1,0,0] neg_hi:[1,0,0]
	ds_read_b128 v[102:105], v0 offset:3152
	s_waitcnt lgkmcnt(6)
	v_pk_fma_f32 v[200:201], v[110:111], v[158:159], v[200:201] op_sel:[0,1,0] neg_lo:[1,0,0] neg_hi:[1,0,0]
	v_pk_fma_f32 v[202:203], v[112:113], v[158:159], v[202:203] op_sel:[0,1,0] neg_lo:[1,0,0] neg_hi:[1,0,0]
	ds_read_b128 v[106:109], v0 offset:3168
	s_waitcnt lgkmcnt(6)
	v_pk_fma_f32 v[204:205], v[114:115], v[158:159], v[204:205] op_sel:[0,1,0] neg_lo:[1,0,0] neg_hi:[1,0,0]
	v_pk_fma_f32 v[208:209], v[116:117], v[158:159], v[208:209] op_sel:[0,1,0] neg_lo:[1,0,0] neg_hi:[1,0,0]
	ds_read_b128 v[110:113], v0 offset:3184
	s_waitcnt lgkmcnt(6)
	v_pk_fma_f32 v[210:211], v[118:119], v[158:159], v[210:211] op_sel:[0,1,0] neg_lo:[1,0,0] neg_hi:[1,0,0]
	v_pk_fma_f32 v[212:213], v[120:121], v[158:159], v[212:213] op_sel:[0,1,0] neg_lo:[1,0,0] neg_hi:[1,0,0]
	ds_read_b128 v[114:117], v0 offset:3200
	s_waitcnt lgkmcnt(6)
	v_pk_fma_f32 v[214:215], v[90:91], v[158:159], v[214:215] op_sel:[0,1,0] neg_lo:[1,0,0] neg_hi:[1,0,0]
	v_pk_fma_f32 v[216:217], v[92:93], v[158:159], v[216:217] op_sel:[0,1,0] neg_lo:[1,0,0] neg_hi:[1,0,0]
	ds_read_b128 v[118:121], v0 offset:3216
	s_waitcnt lgkmcnt(6)
	v_pk_fma_f32 v[160:161], v[94:95], v[160:161], v[160:161] op_sel_hi:[1,0,1] neg_lo:[1,0,0] neg_hi:[1,0,0]
	v_pk_fma_f32 v[162:163], v[96:97], v[160:161], v[162:163] op_sel_hi:[1,0,1] neg_lo:[1,0,0] neg_hi:[1,0,0]
	ds_read_b128 v[90:93], v0 offset:3232
	s_waitcnt lgkmcnt(6)
	v_pk_fma_f32 v[164:165], v[98:99], v[160:161], v[164:165] op_sel_hi:[1,0,1] neg_lo:[1,0,0] neg_hi:[1,0,0]
	v_pk_fma_f32 v[166:167], v[100:101], v[160:161], v[166:167] op_sel_hi:[1,0,1] neg_lo:[1,0,0] neg_hi:[1,0,0]
	ds_read_b128 v[94:97], v0 offset:3248
	s_waitcnt lgkmcnt(6)
	v_pk_fma_f32 v[168:169], v[102:103], v[160:161], v[168:169] op_sel_hi:[1,0,1] neg_lo:[1,0,0] neg_hi:[1,0,0]
	v_pk_fma_f32 v[170:171], v[104:105], v[160:161], v[170:171] op_sel_hi:[1,0,1] neg_lo:[1,0,0] neg_hi:[1,0,0]
	ds_read_b128 v[98:101], v0 offset:3264
	s_waitcnt lgkmcnt(6)
	v_pk_fma_f32 v[172:173], v[106:107], v[160:161], v[172:173] op_sel_hi:[1,0,1] neg_lo:[1,0,0] neg_hi:[1,0,0]
	v_pk_fma_f32 v[174:175], v[108:109], v[160:161], v[174:175] op_sel_hi:[1,0,1] neg_lo:[1,0,0] neg_hi:[1,0,0]
	ds_read_b128 v[102:105], v0 offset:3280
	s_waitcnt lgkmcnt(6)
	v_pk_fma_f32 v[176:177], v[110:111], v[160:161], v[176:177] op_sel_hi:[1,0,1] neg_lo:[1,0,0] neg_hi:[1,0,0]
	v_pk_fma_f32 v[178:179], v[112:113], v[160:161], v[178:179] op_sel_hi:[1,0,1] neg_lo:[1,0,0] neg_hi:[1,0,0]
	ds_read_b128 v[106:109], v0 offset:3296
	s_waitcnt lgkmcnt(6)
	v_pk_fma_f32 v[180:181], v[114:115], v[160:161], v[180:181] op_sel_hi:[1,0,1] neg_lo:[1,0,0] neg_hi:[1,0,0]
	v_pk_fma_f32 v[182:183], v[116:117], v[160:161], v[182:183] op_sel_hi:[1,0,1] neg_lo:[1,0,0] neg_hi:[1,0,0]
	ds_read_b128 v[110:113], v0 offset:3312
	s_waitcnt lgkmcnt(6)
	v_pk_fma_f32 v[184:185], v[118:119], v[160:161], v[184:185] op_sel_hi:[1,0,1] neg_lo:[1,0,0] neg_hi:[1,0,0]
	v_pk_fma_f32 v[186:187], v[120:121], v[160:161], v[186:187] op_sel_hi:[1,0,1] neg_lo:[1,0,0] neg_hi:[1,0,0]
	ds_read_b128 v[114:117], v0 offset:3376
	s_waitcnt lgkmcnt(6)
	v_pk_fma_f32 v[188:189], v[90:91], v[160:161], v[188:189] op_sel_hi:[1,0,1] neg_lo:[1,0,0] neg_hi:[1,0,0]
	v_pk_fma_f32 v[190:191], v[92:93], v[160:161], v[190:191] op_sel_hi:[1,0,1] neg_lo:[1,0,0] neg_hi:[1,0,0]
	ds_read_b128 v[118:121], v0 offset:3392
	s_waitcnt lgkmcnt(6)
	v_pk_fma_f32 v[192:193], v[94:95], v[160:161], v[192:193] op_sel_hi:[1,0,1] neg_lo:[1,0,0] neg_hi:[1,0,0]
	v_pk_fma_f32 v[198:199], v[96:97], v[160:161], v[198:199] op_sel_hi:[1,0,1] neg_lo:[1,0,0] neg_hi:[1,0,0]
	ds_read_b128 v[90:93], v0 offset:3408
	s_waitcnt lgkmcnt(6)
	v_pk_fma_f32 v[200:201], v[98:99], v[160:161], v[200:201] op_sel_hi:[1,0,1] neg_lo:[1,0,0] neg_hi:[1,0,0]
	v_pk_fma_f32 v[202:203], v[100:101], v[160:161], v[202:203] op_sel_hi:[1,0,1] neg_lo:[1,0,0] neg_hi:[1,0,0]
	ds_read_b128 v[94:97], v0 offset:3424
	s_waitcnt lgkmcnt(6)
	v_pk_fma_f32 v[204:205], v[102:103], v[160:161], v[204:205] op_sel_hi:[1,0,1] neg_lo:[1,0,0] neg_hi:[1,0,0]
	v_pk_fma_f32 v[208:209], v[104:105], v[160:161], v[208:209] op_sel_hi:[1,0,1] neg_lo:[1,0,0] neg_hi:[1,0,0]
	ds_read_b128 v[98:101], v0 offset:3440
	s_waitcnt lgkmcnt(6)
; #define LAS __attribute__((address_space(3)))
; #define PIN16(o) asm volatile("" : "+v"(xr[o]), "+v"(xr[o + 1]), "+v"(xr[o + 2]), "+v"(xr[o + 3]), "+v"(xr[o + 4]), "+v"(xr[o + 5]), "+v"(xr[o + 6]), "+v"(xr[o + 7]), "+v"(xr[o + 8]), "+v"(xr[o + 9]), "+v"(xr[o + 10]), "+v"(xr[o + 11]), "+v"(xr[o + 12]), "+v"(xr[o + 13]), "+v"(xr[o + 14]), "+v"(xr[o + 15]) :: "memory")
; DI void gdn_prep_item(LAS unsigned char* lds, const Ctx& c, int l, int item) {
;     ...
; #pragma unroll
;         for (int j = 0; j < 63; ++j) {
;             const float xj = xr[j];
; #pragma unroll
;             for (int i4 = (j + 1) / 4; i4 < 16; ++i4) { const f32x4 Lv = *(const LAS f32x4*)(Lb + j * 64 + 4 * i4);
; #pragma unroll
;                 for (int q = 0; q < 4; ++q) xr[4 * i4 + q] -= Lv[q] * xj; }
;     ...
;             PIN16(0); PIN16(16); PIN16(32); PIN16(48);
	v_pk_fma_f32 v[210:211], v[106:107], v[160:161], v[210:211] op_sel_hi:[1,0,1] neg_lo:[1,0,0] neg_hi:[1,0,0]
	v_pk_fma_f32 v[212:213], v[108:109], v[160:161], v[212:213] op_sel_hi:[1,0,1] neg_lo:[1,0,0] neg_hi:[1,0,0]
	ds_read_b128 v[102:105], v0 offset:3456
	s_waitcnt lgkmcnt(6)
	v_pk_fma_f32 v[214:215], v[110:111], v[160:161], v[214:215] op_sel_hi:[1,0,1] neg_lo:[1,0,0] neg_hi:[1,0,0]
	v_pk_fma_f32 v[216:217], v[112:113], v[160:161], v[216:217] op_sel_hi:[1,0,1] neg_lo:[1,0,0] neg_hi:[1,0,0]
	ds_read_b128 v[106:109], v0 offset:3472
	s_waitcnt lgkmcnt(6)
	v_pk_fma_f32 v[162:163], v[116:117], v[160:161], v[162:163] op_sel:[0,1,0] neg_lo:[1,0,0] neg_hi:[1,0,0]
	ds_read_b128 v[110:113], v0 offset:3488
	s_waitcnt lgkmcnt(6)
	v_pk_fma_f32 v[164:165], v[118:119], v[160:161], v[164:165] op_sel:[0,1,0] neg_lo:[1,0,0] neg_hi:[1,0,0]
	v_pk_fma_f32 v[166:167], v[120:121], v[160:161], v[166:167] op_sel:[0,1,0] neg_lo:[1,0,0] neg_hi:[1,0,0]
	ds_read_b128 v[114:117], v0 offset:3504
	s_waitcnt lgkmcnt(6)
	v_pk_fma_f32 v[168:169], v[90:91], v[160:161], v[168:169] op_sel:[0,1,0] neg_lo:[1,0,0] neg_hi:[1,0,0]
	v_pk_fma_f32 v[170:171], v[92:93], v[160:161], v[170:171] op_sel:[0,1,0] neg_lo:[1,0,0] neg_hi:[1,0,0]
	ds_read_b128 v[118:121], v0 offset:3520
	s_waitcnt lgkmcnt(6)
	v_pk_fma_f32 v[172:173], v[94:95], v[160:161], v[172:173] op_sel:[0,1,0] neg_lo:[1,0,0] neg_hi:[1,0,0]
	v_pk_fma_f32 v[174:175], v[96:97], v[160:161], v[174:175] op_sel:[0,1,0] neg_lo:[1,0,0] neg_hi:[1,0,0]
	ds_read_b128 v[90:93], v0 offset:3536
	s_waitcnt lgkmcnt(6)
	v_pk_fma_f32 v[176:177], v[98:99], v[160:161], v[176:177] op_sel:[0,1,0] neg_lo:[1,0,0] neg_hi:[1,0,0]
	v_pk_fma_f32 v[178:179], v[100:101], v[160:161], v[178:179] op_sel:[0,1,0] neg_lo:[1,0,0] neg_hi:[1,0,0]
	ds_read_b128 v[94:97], v0 offset:3552
	s_waitcnt lgkmcnt(6)
	v_pk_fma_f32 v[180:181], v[102:103], v[160:161], v[180:181] op_sel:[0,1,0] neg_lo:[1,0,0] neg_hi:[1,0,0]
	v_pk_fma_f32 v[182:183], v[104:105], v[160:161], v[182:183] op_sel:[0,1,0] neg_lo:[1,0,0] neg_hi:[1,0,0]
	ds_read_b128 v[98:101], v0 offset:3568
	s_waitcnt lgkmcnt(6)
	v_pk_fma_f32 v[184:185], v[106:107], v[160:161], v[184:185] op_sel:[0,1,0] neg_lo:[1,0,0] neg_hi:[1,0,0]
	v_pk_fma_f32 v[186:187], v[108:109], v[160:161], v[186:187] op_sel:[0,1,0] neg_lo:[1,0,0] neg_hi:[1,0,0]
	ds_read_b128 v[102:105], v0 offset:3632
	s_waitcnt lgkmcnt(6)
	v_pk_fma_f32 v[188:189], v[110:111], v[160:161], v[188:189] op_sel:[0,1,0] neg_lo:[1,0,0] neg_hi:[1,0,0]
	v_pk_fma_f32 v[190:191], v[112:113], v[160:161], v[190:191] op_sel:[0,1,0] neg_lo:[1,0,0] neg_hi:[1,0,0]
	ds_read_b128 v[106:109], v0 offset:3648
	s_waitcnt lgkmcnt(6)
	v_pk_fma_f32 v[192:193], v[114:115], v[160:161], v[192:193] op_sel:[0,1,0] neg_lo:[1,0,0] neg_hi:[1,0,0]
	v_pk_fma_f32 v[198:199], v[116:117], v[160:161], v[198:199] op_sel:[0,1,0] neg_lo:[1,0,0] neg_hi:[1,0,0]
	ds_read_b128 v[110:113], v0 offset:3664
	s_waitcnt lgkmcnt(6)
	v_pk_fma_f32 v[200:201], v[118:119], v[160:161], v[200:201] op_sel:[0,1,0] neg_lo:[1,0,0] neg_hi:[1,0,0]
	v_pk_fma_f32 v[202:203], v[120:121], v[160:161], v[202:203] op_sel:[0,1,0] neg_lo:[1,0,0] neg_hi:[1,0,0]
	ds_read_b128 v[114:117], v0 offset:3680
	s_waitcnt lgkmcnt(6)
	v_pk_fma_f32 v[204:205], v[90:91], v[160:161], v[204:205] op_sel:[0,1,0] neg_lo:[1,0,0] neg_hi:[1,0,0]
	v_pk_fma_f32 v[208:209], v[92:93], v[160:161], v[208:209] op_sel:[0,1,0] neg_lo:[1,0,0] neg_hi:[1,0,0]
	ds_read_b128 v[118:121], v0 offset:3696
	s_waitcnt lgkmcnt(6)
	v_pk_fma_f32 v[210:211], v[94:95], v[160:161], v[210:211] op_sel:[0,1,0] neg_lo:[1,0,0] neg_hi:[1,0,0]
	v_pk_fma_f32 v[212:213], v[96:97], v[160:161], v[212:213] op_sel:[0,1,0] neg_lo:[1,0,0] neg_hi:[1,0,0]
	ds_read_b128 v[90:93], v0 offset:3712
	s_waitcnt lgkmcnt(6)
	v_pk_fma_f32 v[214:215], v[98:99], v[160:161], v[214:215] op_sel:[0,1,0] neg_lo:[1,0,0] neg_hi:[1,0,0]
	v_pk_fma_f32 v[216:217], v[100:101], v[160:161], v[216:217] op_sel:[0,1,0] neg_lo:[1,0,0] neg_hi:[1,0,0]
	ds_read_b128 v[94:97], v0 offset:3728
	s_waitcnt lgkmcnt(6)
	v_pk_fma_f32 v[162:163], v[104:105], v[162:163], v[162:163] op_sel_hi:[1,0,1] neg_lo:[1,0,0] neg_hi:[1,0,0]
	ds_read_b128 v[98:101], v0 offset:3744
	s_waitcnt lgkmcnt(6)
	v_pk_fma_f32 v[164:165], v[106:107], v[162:163], v[164:165] op_sel_hi:[1,0,1] neg_lo:[1,0,0] neg_hi:[1,0,0]
	v_pk_fma_f32 v[166:167], v[108:109], v[162:163], v[166:167] op_sel_hi:[1,0,1] neg_lo:[1,0,0] neg_hi:[1,0,0]
	ds_read_b128 v[102:105], v0 offset:3760
	s_waitcnt lgkmcnt(6)
	v_pk_fma_f32 v[168:169], v[110:111], v[162:163], v[168:169] op_sel_hi:[1,0,1] neg_lo:[1,0,0] neg_hi:[1,0,0]
	v_pk_fma_f32 v[170:171], v[112:113], v[162:163], v[170:171] op_sel_hi:[1,0,1] neg_lo:[1,0,0] neg_hi:[1,0,0]
	ds_read_b128 v[106:109], v0 offset:3776
	s_waitcnt lgkmcnt(6)
	v_pk_fma_f32 v[172:173], v[114:115], v[162:163], v[172:173] op_sel_hi:[1,0,1] neg_lo:[1,0,0] neg_hi:[1,0,0]
	v_pk_fma_f32 v[174:175], v[116:117], v[162:163], v[174:175] op_sel_hi:[1,0,1] neg_lo:[1,0,0] neg_hi:[1,0,0]
	ds_read_b128 v[110:113], v0 offset:3792
	s_waitcnt lgkmcnt(6)
	v_pk_fma_f32 v[176:177], v[118:119], v[162:163], v[176:177] op_sel_hi:[1,0,1] neg_lo:[1,0,0] neg_hi:[1,0,0]
	v_pk_fma_f32 v[178:179], v[120:121], v[162:163], v[178:179] op_sel_hi:[1,0,1] neg_lo:[1,0,0] neg_hi:[1,0,0]
	ds_read_b128 v[114:117], v0 offset:3808
	s_waitcnt lgkmcnt(6)
	v_pk_fma_f32 v[180:181], v[90:91], v[162:163], v[180:181] op_sel_hi:[1,0,1] neg_lo:[1,0,0] neg_hi:[1,0,0]
	v_pk_fma_f32 v[182:183], v[92:93], v[162:163], v[182:183] op_sel_hi:[1,0,1] neg_lo:[1,0,0] neg_hi:[1,0,0]
	ds_read_b128 v[118:121], v0 offset:3824
	s_waitcnt lgkmcnt(6)
; #define LAS __attribute__((address_space(3)))
; #define PIN16(o) asm volatile("" : "+v"(xr[o]), "+v"(xr[o + 1]), "+v"(xr[o + 2]), "+v"(xr[o + 3]), "+v"(xr[o + 4]), "+v"(xr[o + 5]), "+v"(xr[o + 6]), "+v"(xr[o + 7]), "+v"(xr[o + 8]), "+v"(xr[o + 9]), "+v"(xr[o + 10]), "+v"(xr[o + 11]), "+v"(xr[o + 12]), "+v"(xr[o + 13]), "+v"(xr[o + 14]), "+v"(xr[o + 15]) :: "memory")
; DI void gdn_prep_item(LAS unsigned char* lds, const Ctx& c, int l, int item) {
;     ...
; #pragma unroll
;         for (int j = 0; j < 63; ++j) {
;             const float xj = xr[j];
; #pragma unroll
;             for (int i4 = (j + 1) / 4; i4 < 16; ++i4) { const f32x4 Lv = *(const LAS f32x4*)(Lb + j * 64 + 4 * i4);
; #pragma unroll
;                 for (int q = 0; q < 4; ++q) xr[4 * i4 + q] -= Lv[q] * xj; }
;     ...
;             PIN16(0); PIN16(16); PIN16(32); PIN16(48);
	v_pk_fma_f32 v[184:185], v[94:95], v[162:163], v[184:185] op_sel_hi:[1,0,1] neg_lo:[1,0,0] neg_hi:[1,0,0]
	v_pk_fma_f32 v[186:187], v[96:97], v[162:163], v[186:187] op_sel_hi:[1,0,1] neg_lo:[1,0,0] neg_hi:[1,0,0]
	ds_read_b128 v[90:93], v0 offset:3904
	s_waitcnt lgkmcnt(6)
	v_pk_fma_f32 v[188:189], v[98:99], v[162:163], v[188:189] op_sel_hi:[1,0,1] neg_lo:[1,0,0] neg_hi:[1,0,0]
	v_pk_fma_f32 v[190:191], v[100:101], v[162:163], v[190:191] op_sel_hi:[1,0,1] neg_lo:[1,0,0] neg_hi:[1,0,0]
	ds_read_b128 v[94:97], v0 offset:3920
	s_waitcnt lgkmcnt(6)
	v_pk_fma_f32 v[192:193], v[102:103], v[162:163], v[192:193] op_sel_hi:[1,0,1] neg_lo:[1,0,0] neg_hi:[1,0,0]
	v_pk_fma_f32 v[198:199], v[104:105], v[162:163], v[198:199] op_sel_hi:[1,0,1] neg_lo:[1,0,0] neg_hi:[1,0,0]
	ds_read_b128 v[98:101], v0 offset:3936
	s_waitcnt lgkmcnt(6)
	v_pk_fma_f32 v[200:201], v[106:107], v[162:163], v[200:201] op_sel_hi:[1,0,1] neg_lo:[1,0,0] neg_hi:[1,0,0]
	v_pk_fma_f32 v[202:203], v[108:109], v[162:163], v[202:203] op_sel_hi:[1,0,1] neg_lo:[1,0,0] neg_hi:[1,0,0]
	ds_read_b128 v[102:105], v0 offset:3952
	s_waitcnt lgkmcnt(6)
	v_pk_fma_f32 v[204:205], v[110:111], v[162:163], v[204:205] op_sel_hi:[1,0,1] neg_lo:[1,0,0] neg_hi:[1,0,0]
	v_pk_fma_f32 v[208:209], v[112:113], v[162:163], v[208:209] op_sel_hi:[1,0,1] neg_lo:[1,0,0] neg_hi:[1,0,0]
	ds_read_b128 v[106:109], v0 offset:3968
	s_waitcnt lgkmcnt(6)
	v_pk_fma_f32 v[210:211], v[114:115], v[162:163], v[210:211] op_sel_hi:[1,0,1] neg_lo:[1,0,0] neg_hi:[1,0,0]
	v_pk_fma_f32 v[212:213], v[116:117], v[162:163], v[212:213] op_sel_hi:[1,0,1] neg_lo:[1,0,0] neg_hi:[1,0,0]
	ds_read_b128 v[110:113], v0 offset:3984
	s_waitcnt lgkmcnt(6)
	v_pk_fma_f32 v[214:215], v[118:119], v[162:163], v[214:215] op_sel_hi:[1,0,1] neg_lo:[1,0,0] neg_hi:[1,0,0]
	v_pk_fma_f32 v[216:217], v[120:121], v[162:163], v[216:217] op_sel_hi:[1,0,1] neg_lo:[1,0,0] neg_hi:[1,0,0]
	ds_read_b128 v[114:117], v0 offset:4000
	s_waitcnt lgkmcnt(6)
	v_pk_fma_f32 v[164:165], v[90:91], v[162:163], v[164:165] op_sel:[0,1,0] neg_lo:[1,0,0] neg_hi:[1,0,0]
	v_pk_fma_f32 v[166:167], v[92:93], v[162:163], v[166:167] op_sel:[0,1,0] neg_lo:[1,0,0] neg_hi:[1,0,0]
	ds_read_b128 v[118:121], v0 offset:4016
	s_waitcnt lgkmcnt(6)
	v_pk_fma_f32 v[168:169], v[94:95], v[162:163], v[168:169] op_sel:[0,1,0] neg_lo:[1,0,0] neg_hi:[1,0,0]
	v_pk_fma_f32 v[170:171], v[96:97], v[162:163], v[170:171] op_sel:[0,1,0] neg_lo:[1,0,0] neg_hi:[1,0,0]
	ds_read_b128 v[90:93], v0 offset:4032
	s_waitcnt lgkmcnt(6)
	v_pk_fma_f32 v[172:173], v[98:99], v[162:163], v[172:173] op_sel:[0,1,0] neg_lo:[1,0,0] neg_hi:[1,0,0]
	v_pk_fma_f32 v[174:175], v[100:101], v[162:163], v[174:175] op_sel:[0,1,0] neg_lo:[1,0,0] neg_hi:[1,0,0]
	ds_read_b128 v[94:97], v0 offset:4048
	s_waitcnt lgkmcnt(6)
	v_pk_fma_f32 v[176:177], v[102:103], v[162:163], v[176:177] op_sel:[0,1,0] neg_lo:[1,0,0] neg_hi:[1,0,0]
	v_pk_fma_f32 v[178:179], v[104:105], v[162:163], v[178:179] op_sel:[0,1,0] neg_lo:[1,0,0] neg_hi:[1,0,0]
	ds_read_b128 v[98:101], v0 offset:4064
	s_waitcnt lgkmcnt(6)
	v_pk_fma_f32 v[180:181], v[106:107], v[162:163], v[180:181] op_sel:[0,1,0] neg_lo:[1,0,0] neg_hi:[1,0,0]
	v_pk_fma_f32 v[182:183], v[108:109], v[162:163], v[182:183] op_sel:[0,1,0] neg_lo:[1,0,0] neg_hi:[1,0,0]
	ds_read_b128 v[102:105], v0 offset:4080
	s_waitcnt lgkmcnt(6)
	v_pk_fma_f32 v[184:185], v[110:111], v[162:163], v[184:185] op_sel:[0,1,0] neg_lo:[1,0,0] neg_hi:[1,0,0]
	v_pk_fma_f32 v[186:187], v[112:113], v[162:163], v[186:187] op_sel:[0,1,0] neg_lo:[1,0,0] neg_hi:[1,0,0]
	ds_read_b128 v[106:109], v0 offset:4160
	s_waitcnt lgkmcnt(6)
	v_pk_fma_f32 v[188:189], v[114:115], v[162:163], v[188:189] op_sel:[0,1,0] neg_lo:[1,0,0] neg_hi:[1,0,0]
	v_pk_fma_f32 v[190:191], v[116:117], v[162:163], v[190:191] op_sel:[0,1,0] neg_lo:[1,0,0] neg_hi:[1,0,0]
	ds_read_b128 v[110:113], v0 offset:4176
	s_waitcnt lgkmcnt(6)
	v_pk_fma_f32 v[192:193], v[118:119], v[162:163], v[192:193] op_sel:[0,1,0] neg_lo:[1,0,0] neg_hi:[1,0,0]
	v_pk_fma_f32 v[198:199], v[120:121], v[162:163], v[198:199] op_sel:[0,1,0] neg_lo:[1,0,0] neg_hi:[1,0,0]
	ds_read_b128 v[114:117], v0 offset:4192
	s_waitcnt lgkmcnt(6)
	v_pk_fma_f32 v[200:201], v[90:91], v[162:163], v[200:201] op_sel:[0,1,0] neg_lo:[1,0,0] neg_hi:[1,0,0]
	v_pk_fma_f32 v[202:203], v[92:93], v[162:163], v[202:203] op_sel:[0,1,0] neg_lo:[1,0,0] neg_hi:[1,0,0]
	ds_read_b128 v[118:121], v0 offset:4208
	s_waitcnt lgkmcnt(6)
	v_pk_fma_f32 v[204:205], v[94:95], v[162:163], v[204:205] op_sel:[0,1,0] neg_lo:[1,0,0] neg_hi:[1,0,0]
	v_pk_fma_f32 v[208:209], v[96:97], v[162:163], v[208:209] op_sel:[0,1,0] neg_lo:[1,0,0] neg_hi:[1,0,0]
	ds_read_b128 v[90:93], v0 offset:4224
	s_waitcnt lgkmcnt(6)
	v_pk_fma_f32 v[210:211], v[98:99], v[162:163], v[210:211] op_sel:[0,1,0] neg_lo:[1,0,0] neg_hi:[1,0,0]
	v_pk_fma_f32 v[212:213], v[100:101], v[162:163], v[212:213] op_sel:[0,1,0] neg_lo:[1,0,0] neg_hi:[1,0,0]
	ds_read_b128 v[94:97], v0 offset:4240
	s_waitcnt lgkmcnt(6)
	v_pk_fma_f32 v[214:215], v[102:103], v[162:163], v[214:215] op_sel:[0,1,0] neg_lo:[1,0,0] neg_hi:[1,0,0]
	v_pk_fma_f32 v[216:217], v[104:105], v[162:163], v[216:217] op_sel:[0,1,0] neg_lo:[1,0,0] neg_hi:[1,0,0]
	ds_read_b128 v[98:101], v0 offset:4256
	s_waitcnt lgkmcnt(6)
	v_pk_fma_f32 v[164:165], v[106:107], v[164:165], v[164:165] op_sel_hi:[1,0,1] neg_lo:[1,0,0] neg_hi:[1,0,0]
	v_pk_fma_f32 v[166:167], v[108:109], v[164:165], v[166:167] op_sel_hi:[1,0,1] neg_lo:[1,0,0] neg_hi:[1,0,0]
	ds_read_b128 v[102:105], v0 offset:4272
	s_waitcnt lgkmcnt(6)
; #define LAS __attribute__((address_space(3)))
; #define PIN16(o) asm volatile("" : "+v"(xr[o]), "+v"(xr[o + 1]), "+v"(xr[o + 2]), "+v"(xr[o + 3]), "+v"(xr[o + 4]), "+v"(xr[o + 5]), "+v"(xr[o + 6]), "+v"(xr[o + 7]), "+v"(xr[o + 8]), "+v"(xr[o + 9]), "+v"(xr[o + 10]), "+v"(xr[o + 11]), "+v"(xr[o + 12]), "+v"(xr[o + 13]), "+v"(xr[o + 14]), "+v"(xr[o + 15]) :: "memory")
; DI void gdn_prep_item(LAS unsigned char* lds, const Ctx& c, int l, int item) {
;     ...
; #pragma unroll
;         for (int j = 0; j < 63; ++j) {
;             const float xj = xr[j];
; #pragma unroll
;             for (int i4 = (j + 1) / 4; i4 < 16; ++i4) { const f32x4 Lv = *(const LAS f32x4*)(Lb + j * 64 + 4 * i4);
; #pragma unroll
;                 for (int q = 0; q < 4; ++q) xr[4 * i4 + q] -= Lv[q] * xj; }
;     ...
;             PIN16(0); PIN16(16); PIN16(32); PIN16(48);
	v_pk_fma_f32 v[168:169], v[110:111], v[164:165], v[168:169] op_sel_hi:[1,0,1] neg_lo:[1,0,0] neg_hi:[1,0,0]
	v_pk_fma_f32 v[170:171], v[112:113], v[164:165], v[170:171] op_sel_hi:[1,0,1] neg_lo:[1,0,0] neg_hi:[1,0,0]
	ds_read_b128 v[106:109], v0 offset:4288
	s_waitcnt lgkmcnt(6)
	v_pk_fma_f32 v[172:173], v[114:115], v[164:165], v[172:173] op_sel_hi:[1,0,1] neg_lo:[1,0,0] neg_hi:[1,0,0]
	v_pk_fma_f32 v[174:175], v[116:117], v[164:165], v[174:175] op_sel_hi:[1,0,1] neg_lo:[1,0,0] neg_hi:[1,0,0]
	ds_read_b128 v[110:113], v0 offset:4304
	s_waitcnt lgkmcnt(6)
	v_pk_fma_f32 v[176:177], v[118:119], v[164:165], v[176:177] op_sel_hi:[1,0,1] neg_lo:[1,0,0] neg_hi:[1,0,0]
	v_pk_fma_f32 v[178:179], v[120:121], v[164:165], v[178:179] op_sel_hi:[1,0,1] neg_lo:[1,0,0] neg_hi:[1,0,0]
	ds_read_b128 v[114:117], v0 offset:4320
	s_waitcnt lgkmcnt(6)
	v_pk_fma_f32 v[180:181], v[90:91], v[164:165], v[180:181] op_sel_hi:[1,0,1] neg_lo:[1,0,0] neg_hi:[1,0,0]
	v_pk_fma_f32 v[182:183], v[92:93], v[164:165], v[182:183] op_sel_hi:[1,0,1] neg_lo:[1,0,0] neg_hi:[1,0,0]
	ds_read_b128 v[118:121], v0 offset:4336
	s_waitcnt lgkmcnt(6)
	v_pk_fma_f32 v[184:185], v[94:95], v[164:165], v[184:185] op_sel_hi:[1,0,1] neg_lo:[1,0,0] neg_hi:[1,0,0]
	v_pk_fma_f32 v[186:187], v[96:97], v[164:165], v[186:187] op_sel_hi:[1,0,1] neg_lo:[1,0,0] neg_hi:[1,0,0]
	ds_read_b128 v[90:93], v0 offset:4416
	s_waitcnt lgkmcnt(6)
	v_pk_fma_f32 v[188:189], v[98:99], v[164:165], v[188:189] op_sel_hi:[1,0,1] neg_lo:[1,0,0] neg_hi:[1,0,0]
	v_pk_fma_f32 v[190:191], v[100:101], v[164:165], v[190:191] op_sel_hi:[1,0,1] neg_lo:[1,0,0] neg_hi:[1,0,0]
	ds_read_b128 v[94:97], v0 offset:4432
	s_waitcnt lgkmcnt(6)
	v_pk_fma_f32 v[192:193], v[102:103], v[164:165], v[192:193] op_sel_hi:[1,0,1] neg_lo:[1,0,0] neg_hi:[1,0,0]
	v_pk_fma_f32 v[198:199], v[104:105], v[164:165], v[198:199] op_sel_hi:[1,0,1] neg_lo:[1,0,0] neg_hi:[1,0,0]
	ds_read_b128 v[98:101], v0 offset:4448
	s_waitcnt lgkmcnt(6)
	v_pk_fma_f32 v[200:201], v[106:107], v[164:165], v[200:201] op_sel_hi:[1,0,1] neg_lo:[1,0,0] neg_hi:[1,0,0]
	v_pk_fma_f32 v[202:203], v[108:109], v[164:165], v[202:203] op_sel_hi:[1,0,1] neg_lo:[1,0,0] neg_hi:[1,0,0]
	ds_read_b128 v[102:105], v0 offset:4464
	s_waitcnt lgkmcnt(6)
	v_pk_fma_f32 v[204:205], v[110:111], v[164:165], v[204:205] op_sel_hi:[1,0,1] neg_lo:[1,0,0] neg_hi:[1,0,0]
	v_pk_fma_f32 v[208:209], v[112:113], v[164:165], v[208:209] op_sel_hi:[1,0,1] neg_lo:[1,0,0] neg_hi:[1,0,0]
	ds_read_b128 v[106:109], v0 offset:4480
	s_waitcnt lgkmcnt(6)
	v_pk_fma_f32 v[210:211], v[114:115], v[164:165], v[210:211] op_sel_hi:[1,0,1] neg_lo:[1,0,0] neg_hi:[1,0,0]
	v_pk_fma_f32 v[212:213], v[116:117], v[164:165], v[212:213] op_sel_hi:[1,0,1] neg_lo:[1,0,0] neg_hi:[1,0,0]
	ds_read_b128 v[110:113], v0 offset:4496
	s_waitcnt lgkmcnt(6)
	v_pk_fma_f32 v[214:215], v[118:119], v[164:165], v[214:215] op_sel_hi:[1,0,1] neg_lo:[1,0,0] neg_hi:[1,0,0]
	v_pk_fma_f32 v[216:217], v[120:121], v[164:165], v[216:217] op_sel_hi:[1,0,1] neg_lo:[1,0,0] neg_hi:[1,0,0]
	ds_read_b128 v[114:117], v0 offset:4512
	s_waitcnt lgkmcnt(6)
	v_pk_fma_f32 v[166:167], v[92:93], v[164:165], v[166:167] op_sel:[0,1,0] neg_lo:[1,0,0] neg_hi:[1,0,0]
	ds_read_b128 v[118:121], v0 offset:4528
	s_waitcnt lgkmcnt(6)
	v_pk_fma_f32 v[168:169], v[94:95], v[164:165], v[168:169] op_sel:[0,1,0] neg_lo:[1,0,0] neg_hi:[1,0,0]
	v_pk_fma_f32 v[170:171], v[96:97], v[164:165], v[170:171] op_sel:[0,1,0] neg_lo:[1,0,0] neg_hi:[1,0,0]
	ds_read_b128 v[90:93], v0 offset:4544
	s_waitcnt lgkmcnt(6)
	v_pk_fma_f32 v[172:173], v[98:99], v[164:165], v[172:173] op_sel:[0,1,0] neg_lo:[1,0,0] neg_hi:[1,0,0]
	v_pk_fma_f32 v[174:175], v[100:101], v[164:165], v[174:175] op_sel:[0,1,0] neg_lo:[1,0,0] neg_hi:[1,0,0]
	ds_read_b128 v[94:97], v0 offset:4560
	s_waitcnt lgkmcnt(6)
	v_pk_fma_f32 v[176:177], v[102:103], v[164:165], v[176:177] op_sel:[0,1,0] neg_lo:[1,0,0] neg_hi:[1,0,0]
	v_pk_fma_f32 v[178:179], v[104:105], v[164:165], v[178:179] op_sel:[0,1,0] neg_lo:[1,0,0] neg_hi:[1,0,0]
	ds_read_b128 v[98:101], v0 offset:4576
	s_waitcnt lgkmcnt(6)
	v_pk_fma_f32 v[180:181], v[106:107], v[164:165], v[180:181] op_sel:[0,1,0] neg_lo:[1,0,0] neg_hi:[1,0,0]
	v_pk_fma_f32 v[182:183], v[108:109], v[164:165], v[182:183] op_sel:[0,1,0] neg_lo:[1,0,0] neg_hi:[1,0,0]
	ds_read_b128 v[102:105], v0 offset:4592
	s_waitcnt lgkmcnt(6)
	v_pk_fma_f32 v[184:185], v[110:111], v[164:165], v[184:185] op_sel:[0,1,0] neg_lo:[1,0,0] neg_hi:[1,0,0]
	v_pk_fma_f32 v[186:187], v[112:113], v[164:165], v[186:187] op_sel:[0,1,0] neg_lo:[1,0,0] neg_hi:[1,0,0]
	ds_read_b128 v[106:109], v0 offset:4672
	s_waitcnt lgkmcnt(6)
	v_pk_fma_f32 v[188:189], v[114:115], v[164:165], v[188:189] op_sel:[0,1,0] neg_lo:[1,0,0] neg_hi:[1,0,0]
	v_pk_fma_f32 v[190:191], v[116:117], v[164:165], v[190:191] op_sel:[0,1,0] neg_lo:[1,0,0] neg_hi:[1,0,0]
	ds_read_b128 v[110:113], v0 offset:4688
	s_waitcnt lgkmcnt(6)
	v_pk_fma_f32 v[192:193], v[118:119], v[164:165], v[192:193] op_sel:[0,1,0] neg_lo:[1,0,0] neg_hi:[1,0,0]
	v_pk_fma_f32 v[198:199], v[120:121], v[164:165], v[198:199] op_sel:[0,1,0] neg_lo:[1,0,0] neg_hi:[1,0,0]
	ds_read_b128 v[114:117], v0 offset:4704
	s_waitcnt lgkmcnt(6)
	v_pk_fma_f32 v[200:201], v[90:91], v[164:165], v[200:201] op_sel:[0,1,0] neg_lo:[1,0,0] neg_hi:[1,0,0]
	v_pk_fma_f32 v[202:203], v[92:93], v[164:165], v[202:203] op_sel:[0,1,0] neg_lo:[1,0,0] neg_hi:[1,0,0]
	ds_read_b128 v[118:121], v0 offset:4720
	s_waitcnt lgkmcnt(6)
	v_pk_fma_f32 v[204:205], v[94:95], v[164:165], v[204:205] op_sel:[0,1,0] neg_lo:[1,0,0] neg_hi:[1,0,0]
	v_pk_fma_f32 v[208:209], v[96:97], v[164:165], v[208:209] op_sel:[0,1,0] neg_lo:[1,0,0] neg_hi:[1,0,0]
	ds_read_b128 v[90:93], v0 offset:4736
	s_waitcnt lgkmcnt(6)
; #define LAS __attribute__((address_space(3)))
; #define PIN16(o) asm volatile("" : "+v"(xr[o]), "+v"(xr[o + 1]), "+v"(xr[o + 2]), "+v"(xr[o + 3]), "+v"(xr[o + 4]), "+v"(xr[o + 5]), "+v"(xr[o + 6]), "+v"(xr[o + 7]), "+v"(xr[o + 8]), "+v"(xr[o + 9]), "+v"(xr[o + 10]), "+v"(xr[o + 11]), "+v"(xr[o + 12]), "+v"(xr[o + 13]), "+v"(xr[o + 14]), "+v"(xr[o + 15]) :: "memory")
; DI void gdn_prep_item(LAS unsigned char* lds, const Ctx& c, int l, int item) {
;     ...
; #pragma unroll
;         for (int j = 0; j < 63; ++j) {
;             const float xj = xr[j];
; #pragma unroll
;             for (int i4 = (j + 1) / 4; i4 < 16; ++i4) { const f32x4 Lv = *(const LAS f32x4*)(Lb + j * 64 + 4 * i4);
; #pragma unroll
;                 for (int q = 0; q < 4; ++q) xr[4 * i4 + q] -= Lv[q] * xj; }
;     ...
;             PIN16(0); PIN16(16); PIN16(32); PIN16(48);
	v_pk_fma_f32 v[210:211], v[98:99], v[164:165], v[210:211] op_sel:[0,1,0] neg_lo:[1,0,0] neg_hi:[1,0,0]
	v_pk_fma_f32 v[212:213], v[100:101], v[164:165], v[212:213] op_sel:[0,1,0] neg_lo:[1,0,0] neg_hi:[1,0,0]
	ds_read_b128 v[94:97], v0 offset:4752
	s_waitcnt lgkmcnt(6)
	v_pk_fma_f32 v[214:215], v[102:103], v[164:165], v[214:215] op_sel:[0,1,0] neg_lo:[1,0,0] neg_hi:[1,0,0]
	v_pk_fma_f32 v[216:217], v[104:105], v[164:165], v[216:217] op_sel:[0,1,0] neg_lo:[1,0,0] neg_hi:[1,0,0]
	ds_read_b128 v[98:101], v0 offset:4768
	s_waitcnt lgkmcnt(6)
	v_pk_fma_f32 v[166:167], v[108:109], v[166:167], v[166:167] op_sel_hi:[1,0,1] neg_lo:[1,0,0] neg_hi:[1,0,0]
	ds_read_b128 v[102:105], v0 offset:4784
	s_waitcnt lgkmcnt(6)
	v_pk_fma_f32 v[168:169], v[110:111], v[166:167], v[168:169] op_sel_hi:[1,0,1] neg_lo:[1,0,0] neg_hi:[1,0,0]
	v_pk_fma_f32 v[170:171], v[112:113], v[166:167], v[170:171] op_sel_hi:[1,0,1] neg_lo:[1,0,0] neg_hi:[1,0,0]
	ds_read_b128 v[106:109], v0 offset:4800
	s_waitcnt lgkmcnt(6)
	v_pk_fma_f32 v[172:173], v[114:115], v[166:167], v[172:173] op_sel_hi:[1,0,1] neg_lo:[1,0,0] neg_hi:[1,0,0]
	v_pk_fma_f32 v[174:175], v[116:117], v[166:167], v[174:175] op_sel_hi:[1,0,1] neg_lo:[1,0,0] neg_hi:[1,0,0]
	ds_read_b128 v[110:113], v0 offset:4816
	s_waitcnt lgkmcnt(6)
	v_pk_fma_f32 v[176:177], v[118:119], v[166:167], v[176:177] op_sel_hi:[1,0,1] neg_lo:[1,0,0] neg_hi:[1,0,0]
	v_pk_fma_f32 v[178:179], v[120:121], v[166:167], v[178:179] op_sel_hi:[1,0,1] neg_lo:[1,0,0] neg_hi:[1,0,0]
	ds_read_b128 v[114:117], v0 offset:4832
	s_waitcnt lgkmcnt(6)
	v_pk_fma_f32 v[180:181], v[90:91], v[166:167], v[180:181] op_sel_hi:[1,0,1] neg_lo:[1,0,0] neg_hi:[1,0,0]
	v_pk_fma_f32 v[182:183], v[92:93], v[166:167], v[182:183] op_sel_hi:[1,0,1] neg_lo:[1,0,0] neg_hi:[1,0,0]
	ds_read_b128 v[118:121], v0 offset:4848
	s_waitcnt lgkmcnt(6)
	v_pk_fma_f32 v[184:185], v[94:95], v[166:167], v[184:185] op_sel_hi:[1,0,1] neg_lo:[1,0,0] neg_hi:[1,0,0]
	v_pk_fma_f32 v[186:187], v[96:97], v[166:167], v[186:187] op_sel_hi:[1,0,1] neg_lo:[1,0,0] neg_hi:[1,0,0]
	ds_read_b128 v[90:93], v0 offset:4944
	s_waitcnt lgkmcnt(6)
	v_pk_fma_f32 v[188:189], v[98:99], v[166:167], v[188:189] op_sel_hi:[1,0,1] neg_lo:[1,0,0] neg_hi:[1,0,0]
	v_pk_fma_f32 v[190:191], v[100:101], v[166:167], v[190:191] op_sel_hi:[1,0,1] neg_lo:[1,0,0] neg_hi:[1,0,0]
	ds_read_b128 v[94:97], v0 offset:4960
	s_waitcnt lgkmcnt(6)
	v_pk_fma_f32 v[192:193], v[102:103], v[166:167], v[192:193] op_sel_hi:[1,0,1] neg_lo:[1,0,0] neg_hi:[1,0,0]
	v_pk_fma_f32 v[198:199], v[104:105], v[166:167], v[198:199] op_sel_hi:[1,0,1] neg_lo:[1,0,0] neg_hi:[1,0,0]
	ds_read_b128 v[98:101], v0 offset:4976
	s_waitcnt lgkmcnt(6)
	v_pk_fma_f32 v[200:201], v[106:107], v[166:167], v[200:201] op_sel_hi:[1,0,1] neg_lo:[1,0,0] neg_hi:[1,0,0]
	v_pk_fma_f32 v[202:203], v[108:109], v[166:167], v[202:203] op_sel_hi:[1,0,1] neg_lo:[1,0,0] neg_hi:[1,0,0]
	ds_read_b128 v[102:105], v0 offset:4992
	s_waitcnt lgkmcnt(6)
	v_pk_fma_f32 v[204:205], v[110:111], v[166:167], v[204:205] op_sel_hi:[1,0,1] neg_lo:[1,0,0] neg_hi:[1,0,0]
	v_pk_fma_f32 v[208:209], v[112:113], v[166:167], v[208:209] op_sel_hi:[1,0,1] neg_lo:[1,0,0] neg_hi:[1,0,0]
	ds_read_b128 v[106:109], v0 offset:5008
	s_waitcnt lgkmcnt(6)
	v_pk_fma_f32 v[210:211], v[114:115], v[166:167], v[210:211] op_sel_hi:[1,0,1] neg_lo:[1,0,0] neg_hi:[1,0,0]
	v_pk_fma_f32 v[212:213], v[116:117], v[166:167], v[212:213] op_sel_hi:[1,0,1] neg_lo:[1,0,0] neg_hi:[1,0,0]
	ds_read_b128 v[110:113], v0 offset:5024
	s_waitcnt lgkmcnt(6)
	v_pk_fma_f32 v[214:215], v[118:119], v[166:167], v[214:215] op_sel_hi:[1,0,1] neg_lo:[1,0,0] neg_hi:[1,0,0]
	v_pk_fma_f32 v[216:217], v[120:121], v[166:167], v[216:217] op_sel_hi:[1,0,1] neg_lo:[1,0,0] neg_hi:[1,0,0]
	ds_read_b128 v[114:117], v0 offset:5040
	s_waitcnt lgkmcnt(6)
	v_pk_fma_f32 v[168:169], v[90:91], v[166:167], v[168:169] op_sel:[0,1,0] neg_lo:[1,0,0] neg_hi:[1,0,0]
	v_pk_fma_f32 v[170:171], v[92:93], v[166:167], v[170:171] op_sel:[0,1,0] neg_lo:[1,0,0] neg_hi:[1,0,0]
	ds_read_b128 v[118:121], v0 offset:5056
	s_waitcnt lgkmcnt(6)
	v_pk_fma_f32 v[172:173], v[94:95], v[166:167], v[172:173] op_sel:[0,1,0] neg_lo:[1,0,0] neg_hi:[1,0,0]
	v_pk_fma_f32 v[174:175], v[96:97], v[166:167], v[174:175] op_sel:[0,1,0] neg_lo:[1,0,0] neg_hi:[1,0,0]
	ds_read_b128 v[90:93], v0 offset:5072
	s_waitcnt lgkmcnt(6)
	v_pk_fma_f32 v[176:177], v[98:99], v[166:167], v[176:177] op_sel:[0,1,0] neg_lo:[1,0,0] neg_hi:[1,0,0]
	v_pk_fma_f32 v[178:179], v[100:101], v[166:167], v[178:179] op_sel:[0,1,0] neg_lo:[1,0,0] neg_hi:[1,0,0]
	ds_read_b128 v[94:97], v0 offset:5088
	s_waitcnt lgkmcnt(6)
	v_pk_fma_f32 v[180:181], v[102:103], v[166:167], v[180:181] op_sel:[0,1,0] neg_lo:[1,0,0] neg_hi:[1,0,0]
	v_pk_fma_f32 v[182:183], v[104:105], v[166:167], v[182:183] op_sel:[0,1,0] neg_lo:[1,0,0] neg_hi:[1,0,0]
	ds_read_b128 v[98:101], v0 offset:5104
	s_waitcnt lgkmcnt(6)
	v_pk_fma_f32 v[184:185], v[106:107], v[166:167], v[184:185] op_sel:[0,1,0] neg_lo:[1,0,0] neg_hi:[1,0,0]
	v_pk_fma_f32 v[186:187], v[108:109], v[166:167], v[186:187] op_sel:[0,1,0] neg_lo:[1,0,0] neg_hi:[1,0,0]
	ds_read_b128 v[102:105], v0 offset:5200
	s_waitcnt lgkmcnt(6)
	v_pk_fma_f32 v[188:189], v[110:111], v[166:167], v[188:189] op_sel:[0,1,0] neg_lo:[1,0,0] neg_hi:[1,0,0]
	v_pk_fma_f32 v[190:191], v[112:113], v[166:167], v[190:191] op_sel:[0,1,0] neg_lo:[1,0,0] neg_hi:[1,0,0]
	ds_read_b128 v[106:109], v0 offset:5216
	s_waitcnt lgkmcnt(6)
	v_pk_fma_f32 v[192:193], v[114:115], v[166:167], v[192:193] op_sel:[0,1,0] neg_lo:[1,0,0] neg_hi:[1,0,0]
	v_pk_fma_f32 v[198:199], v[116:117], v[166:167], v[198:199] op_sel:[0,1,0] neg_lo:[1,0,0] neg_hi:[1,0,0]
	ds_read_b128 v[110:113], v0 offset:5232
	s_waitcnt lgkmcnt(6)
; #define LAS __attribute__((address_space(3)))
; #define PIN16(o) asm volatile("" : "+v"(xr[o]), "+v"(xr[o + 1]), "+v"(xr[o + 2]), "+v"(xr[o + 3]), "+v"(xr[o + 4]), "+v"(xr[o + 5]), "+v"(xr[o + 6]), "+v"(xr[o + 7]), "+v"(xr[o + 8]), "+v"(xr[o + 9]), "+v"(xr[o + 10]), "+v"(xr[o + 11]), "+v"(xr[o + 12]), "+v"(xr[o + 13]), "+v"(xr[o + 14]), "+v"(xr[o + 15]) :: "memory")
; DI void gdn_prep_item(LAS unsigned char* lds, const Ctx& c, int l, int item) {
;     ...
; #pragma unroll
;         for (int j = 0; j < 63; ++j) {
;             const float xj = xr[j];
; #pragma unroll
;             for (int i4 = (j + 1) / 4; i4 < 16; ++i4) { const f32x4 Lv = *(const LAS f32x4*)(Lb + j * 64 + 4 * i4);
; #pragma unroll
;                 for (int q = 0; q < 4; ++q) xr[4 * i4 + q] -= Lv[q] * xj; }
;     ...
;             PIN16(0); PIN16(16); PIN16(32); PIN16(48);
	v_pk_fma_f32 v[200:201], v[118:119], v[166:167], v[200:201] op_sel:[0,1,0] neg_lo:[1,0,0] neg_hi:[1,0,0]
	v_pk_fma_f32 v[202:203], v[120:121], v[166:167], v[202:203] op_sel:[0,1,0] neg_lo:[1,0,0] neg_hi:[1,0,0]
	ds_read_b128 v[114:117], v0 offset:5248
	s_waitcnt lgkmcnt(6)
	v_pk_fma_f32 v[204:205], v[90:91], v[166:167], v[204:205] op_sel:[0,1,0] neg_lo:[1,0,0] neg_hi:[1,0,0]
	v_pk_fma_f32 v[208:209], v[92:93], v[166:167], v[208:209] op_sel:[0,1,0] neg_lo:[1,0,0] neg_hi:[1,0,0]
	ds_read_b128 v[118:121], v0 offset:5264
	s_waitcnt lgkmcnt(6)
	v_pk_fma_f32 v[210:211], v[94:95], v[166:167], v[210:211] op_sel:[0,1,0] neg_lo:[1,0,0] neg_hi:[1,0,0]
	v_pk_fma_f32 v[212:213], v[96:97], v[166:167], v[212:213] op_sel:[0,1,0] neg_lo:[1,0,0] neg_hi:[1,0,0]
	ds_read_b128 v[90:93], v0 offset:5280
	s_waitcnt lgkmcnt(6)
	v_pk_fma_f32 v[214:215], v[98:99], v[166:167], v[214:215] op_sel:[0,1,0] neg_lo:[1,0,0] neg_hi:[1,0,0]
	v_pk_fma_f32 v[216:217], v[100:101], v[166:167], v[216:217] op_sel:[0,1,0] neg_lo:[1,0,0] neg_hi:[1,0,0]
	ds_read_b128 v[94:97], v0 offset:5296
	s_waitcnt lgkmcnt(6)
	v_pk_fma_f32 v[168:169], v[102:103], v[168:169], v[168:169] op_sel_hi:[1,0,1] neg_lo:[1,0,0] neg_hi:[1,0,0]
	v_pk_fma_f32 v[170:171], v[104:105], v[168:169], v[170:171] op_sel_hi:[1,0,1] neg_lo:[1,0,0] neg_hi:[1,0,0]
	ds_read_b128 v[98:101], v0 offset:5312
	s_waitcnt lgkmcnt(6)
	v_pk_fma_f32 v[172:173], v[106:107], v[168:169], v[172:173] op_sel_hi:[1,0,1] neg_lo:[1,0,0] neg_hi:[1,0,0]
	v_pk_fma_f32 v[174:175], v[108:109], v[168:169], v[174:175] op_sel_hi:[1,0,1] neg_lo:[1,0,0] neg_hi:[1,0,0]
	ds_read_b128 v[102:105], v0 offset:5328
	s_waitcnt lgkmcnt(6)
	v_pk_fma_f32 v[176:177], v[110:111], v[168:169], v[176:177] op_sel_hi:[1,0,1] neg_lo:[1,0,0] neg_hi:[1,0,0]
	v_pk_fma_f32 v[178:179], v[112:113], v[168:169], v[178:179] op_sel_hi:[1,0,1] neg_lo:[1,0,0] neg_hi:[1,0,0]
	ds_read_b128 v[106:109], v0 offset:5344
	s_waitcnt lgkmcnt(6)
	v_pk_fma_f32 v[180:181], v[114:115], v[168:169], v[180:181] op_sel_hi:[1,0,1] neg_lo:[1,0,0] neg_hi:[1,0,0]
	v_pk_fma_f32 v[182:183], v[116:117], v[168:169], v[182:183] op_sel_hi:[1,0,1] neg_lo:[1,0,0] neg_hi:[1,0,0]
	ds_read_b128 v[110:113], v0 offset:5360
	s_waitcnt lgkmcnt(6)
	v_pk_fma_f32 v[184:185], v[118:119], v[168:169], v[184:185] op_sel_hi:[1,0,1] neg_lo:[1,0,0] neg_hi:[1,0,0]
	v_pk_fma_f32 v[186:187], v[120:121], v[168:169], v[186:187] op_sel_hi:[1,0,1] neg_lo:[1,0,0] neg_hi:[1,0,0]
	ds_read_b128 v[114:117], v0 offset:5456
	s_waitcnt lgkmcnt(6)
	v_pk_fma_f32 v[188:189], v[90:91], v[168:169], v[188:189] op_sel_hi:[1,0,1] neg_lo:[1,0,0] neg_hi:[1,0,0]
	v_pk_fma_f32 v[190:191], v[92:93], v[168:169], v[190:191] op_sel_hi:[1,0,1] neg_lo:[1,0,0] neg_hi:[1,0,0]
	ds_read_b128 v[118:121], v0 offset:5472
	s_waitcnt lgkmcnt(6)
	v_pk_fma_f32 v[192:193], v[94:95], v[168:169], v[192:193] op_sel_hi:[1,0,1] neg_lo:[1,0,0] neg_hi:[1,0,0]
	v_pk_fma_f32 v[198:199], v[96:97], v[168:169], v[198:199] op_sel_hi:[1,0,1] neg_lo:[1,0,0] neg_hi:[1,0,0]
	ds_read_b128 v[90:93], v0 offset:5488
	s_waitcnt lgkmcnt(6)
	v_pk_fma_f32 v[200:201], v[98:99], v[168:169], v[200:201] op_sel_hi:[1,0,1] neg_lo:[1,0,0] neg_hi:[1,0,0]
	v_pk_fma_f32 v[202:203], v[100:101], v[168:169], v[202:203] op_sel_hi:[1,0,1] neg_lo:[1,0,0] neg_hi:[1,0,0]
	ds_read_b128 v[94:97], v0 offset:5504
	s_waitcnt lgkmcnt(6)
	v_pk_fma_f32 v[204:205], v[102:103], v[168:169], v[204:205] op_sel_hi:[1,0,1] neg_lo:[1,0,0] neg_hi:[1,0,0]
	v_pk_fma_f32 v[208:209], v[104:105], v[168:169], v[208:209] op_sel_hi:[1,0,1] neg_lo:[1,0,0] neg_hi:[1,0,0]
	ds_read_b128 v[98:101], v0 offset:5520
	s_waitcnt lgkmcnt(6)
	v_pk_fma_f32 v[210:211], v[106:107], v[168:169], v[210:211] op_sel_hi:[1,0,1] neg_lo:[1,0,0] neg_hi:[1,0,0]
	v_pk_fma_f32 v[212:213], v[108:109], v[168:169], v[212:213] op_sel_hi:[1,0,1] neg_lo:[1,0,0] neg_hi:[1,0,0]
	ds_read_b128 v[102:105], v0 offset:5536
	s_waitcnt lgkmcnt(6)
	v_pk_fma_f32 v[214:215], v[110:111], v[168:169], v[214:215] op_sel_hi:[1,0,1] neg_lo:[1,0,0] neg_hi:[1,0,0]
	v_pk_fma_f32 v[216:217], v[112:113], v[168:169], v[216:217] op_sel_hi:[1,0,1] neg_lo:[1,0,0] neg_hi:[1,0,0]
	ds_read_b128 v[106:109], v0 offset:5552
	s_waitcnt lgkmcnt(6)
	v_pk_fma_f32 v[170:171], v[116:117], v[168:169], v[170:171] op_sel:[0,1,0] neg_lo:[1,0,0] neg_hi:[1,0,0]
	ds_read_b128 v[110:113], v0 offset:5568
	s_waitcnt lgkmcnt(6)
	v_pk_fma_f32 v[172:173], v[118:119], v[168:169], v[172:173] op_sel:[0,1,0] neg_lo:[1,0,0] neg_hi:[1,0,0]
	v_pk_fma_f32 v[174:175], v[120:121], v[168:169], v[174:175] op_sel:[0,1,0] neg_lo:[1,0,0] neg_hi:[1,0,0]
	ds_read_b128 v[114:117], v0 offset:5584
	s_waitcnt lgkmcnt(6)
	v_pk_fma_f32 v[176:177], v[90:91], v[168:169], v[176:177] op_sel:[0,1,0] neg_lo:[1,0,0] neg_hi:[1,0,0]
	v_pk_fma_f32 v[178:179], v[92:93], v[168:169], v[178:179] op_sel:[0,1,0] neg_lo:[1,0,0] neg_hi:[1,0,0]
	ds_read_b128 v[118:121], v0 offset:5600
	s_waitcnt lgkmcnt(6)
	v_pk_fma_f32 v[180:181], v[94:95], v[168:169], v[180:181] op_sel:[0,1,0] neg_lo:[1,0,0] neg_hi:[1,0,0]
	v_pk_fma_f32 v[182:183], v[96:97], v[168:169], v[182:183] op_sel:[0,1,0] neg_lo:[1,0,0] neg_hi:[1,0,0]
	ds_read_b128 v[90:93], v0 offset:5616
	s_waitcnt lgkmcnt(6)
	v_pk_fma_f32 v[184:185], v[98:99], v[168:169], v[184:185] op_sel:[0,1,0] neg_lo:[1,0,0] neg_hi:[1,0,0]
	v_pk_fma_f32 v[186:187], v[100:101], v[168:169], v[186:187] op_sel:[0,1,0] neg_lo:[1,0,0] neg_hi:[1,0,0]
	ds_read_b128 v[94:97], v0 offset:5712
	s_waitcnt lgkmcnt(6)
	v_pk_fma_f32 v[188:189], v[102:103], v[168:169], v[188:189] op_sel:[0,1,0] neg_lo:[1,0,0] neg_hi:[1,0,0]
	v_pk_fma_f32 v[190:191], v[104:105], v[168:169], v[190:191] op_sel:[0,1,0] neg_lo:[1,0,0] neg_hi:[1,0,0]
	ds_read_b128 v[98:101], v0 offset:5728
	s_waitcnt lgkmcnt(6)
; #define LAS __attribute__((address_space(3)))
; #define PIN16(o) asm volatile("" : "+v"(xr[o]), "+v"(xr[o + 1]), "+v"(xr[o + 2]), "+v"(xr[o + 3]), "+v"(xr[o + 4]), "+v"(xr[o + 5]), "+v"(xr[o + 6]), "+v"(xr[o + 7]), "+v"(xr[o + 8]), "+v"(xr[o + 9]), "+v"(xr[o + 10]), "+v"(xr[o + 11]), "+v"(xr[o + 12]), "+v"(xr[o + 13]), "+v"(xr[o + 14]), "+v"(xr[o + 15]) :: "memory")
; DI void gdn_prep_item(LAS unsigned char* lds, const Ctx& c, int l, int item) {
;     ...
; #pragma unroll
;         for (int j = 0; j < 63; ++j) {
;             const float xj = xr[j];
; #pragma unroll
;             for (int i4 = (j + 1) / 4; i4 < 16; ++i4) { const f32x4 Lv = *(const LAS f32x4*)(Lb + j * 64 + 4 * i4);
; #pragma unroll
;                 for (int q = 0; q < 4; ++q) xr[4 * i4 + q] -= Lv[q] * xj; }
;     ...
;             PIN16(0); PIN16(16); PIN16(32); PIN16(48);
;         }
	v_pk_fma_f32 v[192:193], v[106:107], v[168:169], v[192:193] op_sel:[0,1,0] neg_lo:[1,0,0] neg_hi:[1,0,0]
	v_pk_fma_f32 v[198:199], v[108:109], v[168:169], v[198:199] op_sel:[0,1,0] neg_lo:[1,0,0] neg_hi:[1,0,0]
	ds_read_b128 v[102:105], v0 offset:5744
	s_waitcnt lgkmcnt(6)
	v_pk_fma_f32 v[200:201], v[110:111], v[168:169], v[200:201] op_sel:[0,1,0] neg_lo:[1,0,0] neg_hi:[1,0,0]
	v_pk_fma_f32 v[202:203], v[112:113], v[168:169], v[202:203] op_sel:[0,1,0] neg_lo:[1,0,0] neg_hi:[1,0,0]
	ds_read_b128 v[106:109], v0 offset:5760
	s_waitcnt lgkmcnt(6)
	v_pk_fma_f32 v[204:205], v[114:115], v[168:169], v[204:205] op_sel:[0,1,0] neg_lo:[1,0,0] neg_hi:[1,0,0]
	v_pk_fma_f32 v[208:209], v[116:117], v[168:169], v[208:209] op_sel:[0,1,0] neg_lo:[1,0,0] neg_hi:[1,0,0]
	ds_read_b128 v[110:113], v0 offset:5776
	s_waitcnt lgkmcnt(6)
	v_pk_fma_f32 v[210:211], v[118:119], v[168:169], v[210:211] op_sel:[0,1,0] neg_lo:[1,0,0] neg_hi:[1,0,0]
	v_pk_fma_f32 v[212:213], v[120:121], v[168:169], v[212:213] op_sel:[0,1,0] neg_lo:[1,0,0] neg_hi:[1,0,0]
	ds_read_b128 v[114:117], v0 offset:5792
	s_waitcnt lgkmcnt(6)
	v_pk_fma_f32 v[214:215], v[90:91], v[168:169], v[214:215] op_sel:[0,1,0] neg_lo:[1,0,0] neg_hi:[1,0,0]
	v_pk_fma_f32 v[216:217], v[92:93], v[168:169], v[216:217] op_sel:[0,1,0] neg_lo:[1,0,0] neg_hi:[1,0,0]
	ds_read_b128 v[118:121], v0 offset:5808
	s_waitcnt lgkmcnt(6)
	v_pk_fma_f32 v[170:171], v[96:97], v[170:171], v[170:171] op_sel_hi:[1,0,1] neg_lo:[1,0,0] neg_hi:[1,0,0]
	ds_read_b128 v[90:93], v0 offset:5824
	s_waitcnt lgkmcnt(6)
	v_pk_fma_f32 v[172:173], v[98:99], v[170:171], v[172:173] op_sel_hi:[1,0,1] neg_lo:[1,0,0] neg_hi:[1,0,0]
	v_pk_fma_f32 v[174:175], v[100:101], v[170:171], v[174:175] op_sel_hi:[1,0,1] neg_lo:[1,0,0] neg_hi:[1,0,0]
	ds_read_b128 v[94:97], v0 offset:5840
	s_waitcnt lgkmcnt(6)
	v_pk_fma_f32 v[176:177], v[102:103], v[170:171], v[176:177] op_sel_hi:[1,0,1] neg_lo:[1,0,0] neg_hi:[1,0,0]
	v_pk_fma_f32 v[178:179], v[104:105], v[170:171], v[178:179] op_sel_hi:[1,0,1] neg_lo:[1,0,0] neg_hi:[1,0,0]
	ds_read_b128 v[98:101], v0 offset:5856
	s_waitcnt lgkmcnt(6)
	v_pk_fma_f32 v[180:181], v[106:107], v[170:171], v[180:181] op_sel_hi:[1,0,1] neg_lo:[1,0,0] neg_hi:[1,0,0]
	v_pk_fma_f32 v[182:183], v[108:109], v[170:171], v[182:183] op_sel_hi:[1,0,1] neg_lo:[1,0,0] neg_hi:[1,0,0]
	ds_read_b128 v[102:105], v0 offset:5872
	s_waitcnt lgkmcnt(6)
	v_pk_fma_f32 v[184:185], v[110:111], v[170:171], v[184:185] op_sel_hi:[1,0,1] neg_lo:[1,0,0] neg_hi:[1,0,0]
	v_pk_fma_f32 v[186:187], v[112:113], v[170:171], v[186:187] op_sel_hi:[1,0,1] neg_lo:[1,0,0] neg_hi:[1,0,0]
	ds_read_b128 v[106:109], v0 offset:5984
	s_waitcnt lgkmcnt(6)
	v_pk_fma_f32 v[188:189], v[114:115], v[170:171], v[188:189] op_sel_hi:[1,0,1] neg_lo:[1,0,0] neg_hi:[1,0,0]
	v_pk_fma_f32 v[190:191], v[116:117], v[170:171], v[190:191] op_sel_hi:[1,0,1] neg_lo:[1,0,0] neg_hi:[1,0,0]
	ds_read_b128 v[110:113], v0 offset:6000
	s_waitcnt lgkmcnt(6)
	v_pk_fma_f32 v[192:193], v[118:119], v[170:171], v[192:193] op_sel_hi:[1,0,1] neg_lo:[1,0,0] neg_hi:[1,0,0]
	v_pk_fma_f32 v[198:199], v[120:121], v[170:171], v[198:199] op_sel_hi:[1,0,1] neg_lo:[1,0,0] neg_hi:[1,0,0]
	ds_read_b128 v[114:117], v0 offset:6016
	s_waitcnt lgkmcnt(6)
	v_pk_fma_f32 v[200:201], v[90:91], v[170:171], v[200:201] op_sel_hi:[1,0,1] neg_lo:[1,0,0] neg_hi:[1,0,0]
	v_pk_fma_f32 v[202:203], v[92:93], v[170:171], v[202:203] op_sel_hi:[1,0,1] neg_lo:[1,0,0] neg_hi:[1,0,0]
	ds_read_b128 v[118:121], v0 offset:6032
	s_waitcnt lgkmcnt(6)
	v_pk_fma_f32 v[204:205], v[94:95], v[170:171], v[204:205] op_sel_hi:[1,0,1] neg_lo:[1,0,0] neg_hi:[1,0,0]
	v_pk_fma_f32 v[208:209], v[96:97], v[170:171], v[208:209] op_sel_hi:[1,0,1] neg_lo:[1,0,0] neg_hi:[1,0,0]
	ds_read_b128 v[90:93], v0 offset:6048
	s_waitcnt lgkmcnt(6)
	v_pk_fma_f32 v[210:211], v[98:99], v[170:171], v[210:211] op_sel_hi:[1,0,1] neg_lo:[1,0,0] neg_hi:[1,0,0]
	v_pk_fma_f32 v[212:213], v[100:101], v[170:171], v[212:213] op_sel_hi:[1,0,1] neg_lo:[1,0,0] neg_hi:[1,0,0]
	ds_read_b128 v[94:97], v0 offset:6064
	s_waitcnt lgkmcnt(6)
	v_pk_fma_f32 v[214:215], v[102:103], v[170:171], v[214:215] op_sel_hi:[1,0,1] neg_lo:[1,0,0] neg_hi:[1,0,0]
	v_pk_fma_f32 v[216:217], v[104:105], v[170:171], v[216:217] op_sel_hi:[1,0,1] neg_lo:[1,0,0] neg_hi:[1,0,0]
	ds_read_b128 v[98:101], v0 offset:6080
	s_waitcnt lgkmcnt(6)
	v_pk_fma_f32 v[172:173], v[106:107], v[170:171], v[172:173] op_sel:[0,1,0] neg_lo:[1,0,0] neg_hi:[1,0,0]
	v_pk_fma_f32 v[174:175], v[108:109], v[170:171], v[174:175] op_sel:[0,1,0] neg_lo:[1,0,0] neg_hi:[1,0,0]
	ds_read_b128 v[102:105], v0 offset:6096
	s_waitcnt lgkmcnt(6)
	v_pk_fma_f32 v[176:177], v[110:111], v[170:171], v[176:177] op_sel:[0,1,0] neg_lo:[1,0,0] neg_hi:[1,0,0]
	v_pk_fma_f32 v[178:179], v[112:113], v[170:171], v[178:179] op_sel:[0,1,0] neg_lo:[1,0,0] neg_hi:[1,0,0]
	ds_read_b128 v[106:109], v0 offset:6112
	s_waitcnt lgkmcnt(6)
	v_pk_fma_f32 v[180:181], v[114:115], v[170:171], v[180:181] op_sel:[0,1,0] neg_lo:[1,0,0] neg_hi:[1,0,0]
	v_pk_fma_f32 v[182:183], v[116:117], v[170:171], v[182:183] op_sel:[0,1,0] neg_lo:[1,0,0] neg_hi:[1,0,0]
	ds_read_b128 v[110:113], v0 offset:6128
	s_waitcnt lgkmcnt(6)
	v_pk_fma_f32 v[184:185], v[118:119], v[170:171], v[184:185] op_sel:[0,1,0] neg_lo:[1,0,0] neg_hi:[1,0,0]
	v_pk_fma_f32 v[186:187], v[120:121], v[170:171], v[186:187] op_sel:[0,1,0] neg_lo:[1,0,0] neg_hi:[1,0,0]
	ds_read_b128 v[114:117], v0 offset:6240
	s_waitcnt lgkmcnt(6)
	v_pk_fma_f32 v[188:189], v[90:91], v[170:171], v[188:189] op_sel:[0,1,0] neg_lo:[1,0,0] neg_hi:[1,0,0]
	v_pk_fma_f32 v[190:191], v[92:93], v[170:171], v[190:191] op_sel:[0,1,0] neg_lo:[1,0,0] neg_hi:[1,0,0]
	ds_read_b128 v[118:121], v0 offset:6256
	s_waitcnt lgkmcnt(6)
; #define LAS __attribute__((address_space(3)))
; #define PIN16(o) asm volatile("" : "+v"(xr[o]), "+v"(xr[o + 1]), "+v"(xr[o + 2]), "+v"(xr[o + 3]), "+v"(xr[o + 4]), "+v"(xr[o + 5]), "+v"(xr[o + 6]), "+v"(xr[o + 7]), "+v"(xr[o + 8]), "+v"(xr[o + 9]), "+v"(xr[o + 10]), "+v"(xr[o + 11]), "+v"(xr[o + 12]), "+v"(xr[o + 13]), "+v"(xr[o + 14]), "+v"(xr[o + 15]) :: "memory")
; DI void gdn_prep_item(LAS unsigned char* lds, const Ctx& c, int l, int item) {
;     ...
; #pragma unroll
;         for (int j = 0; j < 63; ++j) {
;             const float xj = xr[j];
; #pragma unroll
;             for (int i4 = (j + 1) / 4; i4 < 16; ++i4) { const f32x4 Lv = *(const LAS f32x4*)(Lb + j * 64 + 4 * i4);
; #pragma unroll
;                 for (int q = 0; q < 4; ++q) xr[4 * i4 + q] -= Lv[q] * xj; }
;     ...
;             PIN16(0); PIN16(16); PIN16(32); PIN16(48);
;         }
	v_pk_fma_f32 v[192:193], v[94:95], v[170:171], v[192:193] op_sel:[0,1,0] neg_lo:[1,0,0] neg_hi:[1,0,0]
	v_pk_fma_f32 v[198:199], v[96:97], v[170:171], v[198:199] op_sel:[0,1,0] neg_lo:[1,0,0] neg_hi:[1,0,0]
	ds_read_b128 v[90:93], v0 offset:6272
	s_waitcnt lgkmcnt(6)
	v_pk_fma_f32 v[200:201], v[98:99], v[170:171], v[200:201] op_sel:[0,1,0] neg_lo:[1,0,0] neg_hi:[1,0,0]
	v_pk_fma_f32 v[202:203], v[100:101], v[170:171], v[202:203] op_sel:[0,1,0] neg_lo:[1,0,0] neg_hi:[1,0,0]
	ds_read_b128 v[94:97], v0 offset:6288
	s_waitcnt lgkmcnt(6)
	v_pk_fma_f32 v[204:205], v[102:103], v[170:171], v[204:205] op_sel:[0,1,0] neg_lo:[1,0,0] neg_hi:[1,0,0]
	v_pk_fma_f32 v[208:209], v[104:105], v[170:171], v[208:209] op_sel:[0,1,0] neg_lo:[1,0,0] neg_hi:[1,0,0]
	ds_read_b128 v[98:101], v0 offset:6304
	s_waitcnt lgkmcnt(6)
	v_pk_fma_f32 v[210:211], v[106:107], v[170:171], v[210:211] op_sel:[0,1,0] neg_lo:[1,0,0] neg_hi:[1,0,0]
	v_pk_fma_f32 v[212:213], v[108:109], v[170:171], v[212:213] op_sel:[0,1,0] neg_lo:[1,0,0] neg_hi:[1,0,0]
	ds_read_b128 v[102:105], v0 offset:6320
	s_waitcnt lgkmcnt(6)
	v_pk_fma_f32 v[214:215], v[110:111], v[170:171], v[214:215] op_sel:[0,1,0] neg_lo:[1,0,0] neg_hi:[1,0,0]
	v_pk_fma_f32 v[216:217], v[112:113], v[170:171], v[216:217] op_sel:[0,1,0] neg_lo:[1,0,0] neg_hi:[1,0,0]
	ds_read_b128 v[106:109], v0 offset:6336
	s_waitcnt lgkmcnt(6)
	v_pk_fma_f32 v[172:173], v[114:115], v[172:173], v[172:173] op_sel_hi:[1,0,1] neg_lo:[1,0,0] neg_hi:[1,0,0]
	v_pk_fma_f32 v[174:175], v[116:117], v[172:173], v[174:175] op_sel_hi:[1,0,1] neg_lo:[1,0,0] neg_hi:[1,0,0]
	ds_read_b128 v[110:113], v0 offset:6352
	s_waitcnt lgkmcnt(6)
	v_pk_fma_f32 v[176:177], v[118:119], v[172:173], v[176:177] op_sel_hi:[1,0,1] neg_lo:[1,0,0] neg_hi:[1,0,0]
	v_pk_fma_f32 v[178:179], v[120:121], v[172:173], v[178:179] op_sel_hi:[1,0,1] neg_lo:[1,0,0] neg_hi:[1,0,0]
	ds_read_b128 v[114:117], v0 offset:6368
	s_waitcnt lgkmcnt(6)
	v_pk_fma_f32 v[180:181], v[90:91], v[172:173], v[180:181] op_sel_hi:[1,0,1] neg_lo:[1,0,0] neg_hi:[1,0,0]
	v_pk_fma_f32 v[182:183], v[92:93], v[172:173], v[182:183] op_sel_hi:[1,0,1] neg_lo:[1,0,0] neg_hi:[1,0,0]
	ds_read_b128 v[118:121], v0 offset:6384
	s_waitcnt lgkmcnt(6)
	v_pk_fma_f32 v[184:185], v[94:95], v[172:173], v[184:185] op_sel_hi:[1,0,1] neg_lo:[1,0,0] neg_hi:[1,0,0]
	v_pk_fma_f32 v[186:187], v[96:97], v[172:173], v[186:187] op_sel_hi:[1,0,1] neg_lo:[1,0,0] neg_hi:[1,0,0]
	ds_read_b128 v[90:93], v0 offset:6496
	s_waitcnt lgkmcnt(6)
	v_pk_fma_f32 v[188:189], v[98:99], v[172:173], v[188:189] op_sel_hi:[1,0,1] neg_lo:[1,0,0] neg_hi:[1,0,0]
	v_pk_fma_f32 v[190:191], v[100:101], v[172:173], v[190:191] op_sel_hi:[1,0,1] neg_lo:[1,0,0] neg_hi:[1,0,0]
	ds_read_b128 v[94:97], v0 offset:6512
	s_waitcnt lgkmcnt(6)
	v_pk_fma_f32 v[192:193], v[102:103], v[172:173], v[192:193] op_sel_hi:[1,0,1] neg_lo:[1,0,0] neg_hi:[1,0,0]
	v_pk_fma_f32 v[198:199], v[104:105], v[172:173], v[198:199] op_sel_hi:[1,0,1] neg_lo:[1,0,0] neg_hi:[1,0,0]
	ds_read_b128 v[98:101], v0 offset:6528
	s_waitcnt lgkmcnt(6)
	v_pk_fma_f32 v[200:201], v[106:107], v[172:173], v[200:201] op_sel_hi:[1,0,1] neg_lo:[1,0,0] neg_hi:[1,0,0]
	v_pk_fma_f32 v[202:203], v[108:109], v[172:173], v[202:203] op_sel_hi:[1,0,1] neg_lo:[1,0,0] neg_hi:[1,0,0]
	ds_read_b128 v[102:105], v0 offset:6544
	s_waitcnt lgkmcnt(6)
	v_pk_fma_f32 v[204:205], v[110:111], v[172:173], v[204:205] op_sel_hi:[1,0,1] neg_lo:[1,0,0] neg_hi:[1,0,0]
	v_pk_fma_f32 v[208:209], v[112:113], v[172:173], v[208:209] op_sel_hi:[1,0,1] neg_lo:[1,0,0] neg_hi:[1,0,0]
	ds_read_b128 v[106:109], v0 offset:6560
	s_waitcnt lgkmcnt(6)
	v_pk_fma_f32 v[210:211], v[114:115], v[172:173], v[210:211] op_sel_hi:[1,0,1] neg_lo:[1,0,0] neg_hi:[1,0,0]
	v_pk_fma_f32 v[212:213], v[116:117], v[172:173], v[212:213] op_sel_hi:[1,0,1] neg_lo:[1,0,0] neg_hi:[1,0,0]
	ds_read_b128 v[110:113], v0 offset:6576
	s_waitcnt lgkmcnt(6)
	v_pk_fma_f32 v[214:215], v[118:119], v[172:173], v[214:215] op_sel_hi:[1,0,1] neg_lo:[1,0,0] neg_hi:[1,0,0]
	v_pk_fma_f32 v[216:217], v[120:121], v[172:173], v[216:217] op_sel_hi:[1,0,1] neg_lo:[1,0,0] neg_hi:[1,0,0]
	ds_read_b128 v[114:117], v0 offset:6592
	s_waitcnt lgkmcnt(6)
	v_pk_fma_f32 v[174:175], v[92:93], v[172:173], v[174:175] op_sel:[0,1,0] neg_lo:[1,0,0] neg_hi:[1,0,0]
	ds_read_b128 v[118:121], v0 offset:6608
	s_waitcnt lgkmcnt(6)
	v_pk_fma_f32 v[176:177], v[94:95], v[172:173], v[176:177] op_sel:[0,1,0] neg_lo:[1,0,0] neg_hi:[1,0,0]
	v_pk_fma_f32 v[178:179], v[96:97], v[172:173], v[178:179] op_sel:[0,1,0] neg_lo:[1,0,0] neg_hi:[1,0,0]
	ds_read_b128 v[90:93], v0 offset:6624
	s_waitcnt lgkmcnt(6)
	v_pk_fma_f32 v[180:181], v[98:99], v[172:173], v[180:181] op_sel:[0,1,0] neg_lo:[1,0,0] neg_hi:[1,0,0]
	v_pk_fma_f32 v[182:183], v[100:101], v[172:173], v[182:183] op_sel:[0,1,0] neg_lo:[1,0,0] neg_hi:[1,0,0]
	ds_read_b128 v[94:97], v0 offset:6640
	s_waitcnt lgkmcnt(6)
	v_pk_fma_f32 v[184:185], v[102:103], v[172:173], v[184:185] op_sel:[0,1,0] neg_lo:[1,0,0] neg_hi:[1,0,0]
	v_pk_fma_f32 v[186:187], v[104:105], v[172:173], v[186:187] op_sel:[0,1,0] neg_lo:[1,0,0] neg_hi:[1,0,0]
	ds_read_b128 v[98:101], v0 offset:6752
	s_waitcnt lgkmcnt(6)
	v_pk_fma_f32 v[188:189], v[106:107], v[172:173], v[188:189] op_sel:[0,1,0] neg_lo:[1,0,0] neg_hi:[1,0,0]
	v_pk_fma_f32 v[190:191], v[108:109], v[172:173], v[190:191] op_sel:[0,1,0] neg_lo:[1,0,0] neg_hi:[1,0,0]
	ds_read_b128 v[102:105], v0 offset:6768
	s_waitcnt lgkmcnt(6)
	v_pk_fma_f32 v[192:193], v[110:111], v[172:173], v[192:193] op_sel:[0,1,0] neg_lo:[1,0,0] neg_hi:[1,0,0]
	v_pk_fma_f32 v[198:199], v[112:113], v[172:173], v[198:199] op_sel:[0,1,0] neg_lo:[1,0,0] neg_hi:[1,0,0]
	ds_read_b128 v[106:109], v0 offset:6784
	s_waitcnt lgkmcnt(6)
; #define LAS __attribute__((address_space(3)))
; #define PIN16(o) asm volatile("" : "+v"(xr[o]), "+v"(xr[o + 1]), "+v"(xr[o + 2]), "+v"(xr[o + 3]), "+v"(xr[o + 4]), "+v"(xr[o + 5]), "+v"(xr[o + 6]), "+v"(xr[o + 7]), "+v"(xr[o + 8]), "+v"(xr[o + 9]), "+v"(xr[o + 10]), "+v"(xr[o + 11]), "+v"(xr[o + 12]), "+v"(xr[o + 13]), "+v"(xr[o + 14]), "+v"(xr[o + 15]) :: "memory")
; DI void gdn_prep_item(LAS unsigned char* lds, const Ctx& c, int l, int item) {
;     ...
; #pragma unroll
;         for (int j = 0; j < 63; ++j) {
;             const float xj = xr[j];
; #pragma unroll
;             for (int i4 = (j + 1) / 4; i4 < 16; ++i4) { const f32x4 Lv = *(const LAS f32x4*)(Lb + j * 64 + 4 * i4);
; #pragma unroll
;                 for (int q = 0; q < 4; ++q) xr[4 * i4 + q] -= Lv[q] * xj; }
;     ...
;             PIN16(0); PIN16(16); PIN16(32); PIN16(48);
;         }
	v_pk_fma_f32 v[200:201], v[114:115], v[172:173], v[200:201] op_sel:[0,1,0] neg_lo:[1,0,0] neg_hi:[1,0,0]
	v_pk_fma_f32 v[202:203], v[116:117], v[172:173], v[202:203] op_sel:[0,1,0] neg_lo:[1,0,0] neg_hi:[1,0,0]
	ds_read_b128 v[110:113], v0 offset:6800
	s_waitcnt lgkmcnt(6)
	v_pk_fma_f32 v[204:205], v[118:119], v[172:173], v[204:205] op_sel:[0,1,0] neg_lo:[1,0,0] neg_hi:[1,0,0]
	v_pk_fma_f32 v[208:209], v[120:121], v[172:173], v[208:209] op_sel:[0,1,0] neg_lo:[1,0,0] neg_hi:[1,0,0]
	ds_read_b128 v[114:117], v0 offset:6816
	s_waitcnt lgkmcnt(6)
	v_pk_fma_f32 v[210:211], v[90:91], v[172:173], v[210:211] op_sel:[0,1,0] neg_lo:[1,0,0] neg_hi:[1,0,0]
	v_pk_fma_f32 v[212:213], v[92:93], v[172:173], v[212:213] op_sel:[0,1,0] neg_lo:[1,0,0] neg_hi:[1,0,0]
	ds_read_b128 v[118:121], v0 offset:6832
	s_waitcnt lgkmcnt(6)
	v_pk_fma_f32 v[214:215], v[94:95], v[172:173], v[214:215] op_sel:[0,1,0] neg_lo:[1,0,0] neg_hi:[1,0,0]
	v_pk_fma_f32 v[216:217], v[96:97], v[172:173], v[216:217] op_sel:[0,1,0] neg_lo:[1,0,0] neg_hi:[1,0,0]
	ds_read_b128 v[90:93], v0 offset:6848
	s_waitcnt lgkmcnt(6)
	v_pk_fma_f32 v[174:175], v[100:101], v[174:175], v[174:175] op_sel_hi:[1,0,1] neg_lo:[1,0,0] neg_hi:[1,0,0]
	ds_read_b128 v[94:97], v0 offset:6864
	s_waitcnt lgkmcnt(6)
	v_pk_fma_f32 v[176:177], v[102:103], v[174:175], v[176:177] op_sel_hi:[1,0,1] neg_lo:[1,0,0] neg_hi:[1,0,0]
	v_pk_fma_f32 v[178:179], v[104:105], v[174:175], v[178:179] op_sel_hi:[1,0,1] neg_lo:[1,0,0] neg_hi:[1,0,0]
	ds_read_b128 v[98:101], v0 offset:6880
	s_waitcnt lgkmcnt(6)
	v_pk_fma_f32 v[180:181], v[106:107], v[174:175], v[180:181] op_sel_hi:[1,0,1] neg_lo:[1,0,0] neg_hi:[1,0,0]
	v_pk_fma_f32 v[182:183], v[108:109], v[174:175], v[182:183] op_sel_hi:[1,0,1] neg_lo:[1,0,0] neg_hi:[1,0,0]
	ds_read_b128 v[102:105], v0 offset:6896
	s_waitcnt lgkmcnt(6)
	v_pk_fma_f32 v[184:185], v[110:111], v[174:175], v[184:185] op_sel_hi:[1,0,1] neg_lo:[1,0,0] neg_hi:[1,0,0]
	v_pk_fma_f32 v[186:187], v[112:113], v[174:175], v[186:187] op_sel_hi:[1,0,1] neg_lo:[1,0,0] neg_hi:[1,0,0]
	ds_read_b128 v[106:109], v0 offset:7024
	s_waitcnt lgkmcnt(6)
	v_pk_fma_f32 v[188:189], v[114:115], v[174:175], v[188:189] op_sel_hi:[1,0,1] neg_lo:[1,0,0] neg_hi:[1,0,0]
	v_pk_fma_f32 v[190:191], v[116:117], v[174:175], v[190:191] op_sel_hi:[1,0,1] neg_lo:[1,0,0] neg_hi:[1,0,0]
	ds_read_b128 v[110:113], v0 offset:7040
	s_waitcnt lgkmcnt(6)
	v_pk_fma_f32 v[192:193], v[118:119], v[174:175], v[192:193] op_sel_hi:[1,0,1] neg_lo:[1,0,0] neg_hi:[1,0,0]
	v_pk_fma_f32 v[198:199], v[120:121], v[174:175], v[198:199] op_sel_hi:[1,0,1] neg_lo:[1,0,0] neg_hi:[1,0,0]
	ds_read_b128 v[114:117], v0 offset:7056
	s_waitcnt lgkmcnt(6)
	v_pk_fma_f32 v[200:201], v[90:91], v[174:175], v[200:201] op_sel_hi:[1,0,1] neg_lo:[1,0,0] neg_hi:[1,0,0]
	v_pk_fma_f32 v[202:203], v[92:93], v[174:175], v[202:203] op_sel_hi:[1,0,1] neg_lo:[1,0,0] neg_hi:[1,0,0]
	ds_read_b128 v[118:121], v0 offset:7072
	s_waitcnt lgkmcnt(6)
	v_pk_fma_f32 v[204:205], v[94:95], v[174:175], v[204:205] op_sel_hi:[1,0,1] neg_lo:[1,0,0] neg_hi:[1,0,0]
	v_pk_fma_f32 v[208:209], v[96:97], v[174:175], v[208:209] op_sel_hi:[1,0,1] neg_lo:[1,0,0] neg_hi:[1,0,0]
	ds_read_b128 v[90:93], v0 offset:7088
	s_waitcnt lgkmcnt(6)
	v_pk_fma_f32 v[210:211], v[98:99], v[174:175], v[210:211] op_sel_hi:[1,0,1] neg_lo:[1,0,0] neg_hi:[1,0,0]
	v_pk_fma_f32 v[212:213], v[100:101], v[174:175], v[212:213] op_sel_hi:[1,0,1] neg_lo:[1,0,0] neg_hi:[1,0,0]
	ds_read_b128 v[94:97], v0 offset:7104
	s_waitcnt lgkmcnt(6)
	v_pk_fma_f32 v[214:215], v[102:103], v[174:175], v[214:215] op_sel_hi:[1,0,1] neg_lo:[1,0,0] neg_hi:[1,0,0]
	v_pk_fma_f32 v[216:217], v[104:105], v[174:175], v[216:217] op_sel_hi:[1,0,1] neg_lo:[1,0,0] neg_hi:[1,0,0]
	ds_read_b128 v[98:101], v0 offset:7120
	s_waitcnt lgkmcnt(6)
	v_pk_fma_f32 v[176:177], v[106:107], v[174:175], v[176:177] op_sel:[0,1,0] neg_lo:[1,0,0] neg_hi:[1,0,0]
	v_pk_fma_f32 v[178:179], v[108:109], v[174:175], v[178:179] op_sel:[0,1,0] neg_lo:[1,0,0] neg_hi:[1,0,0]
	ds_read_b128 v[102:105], v0 offset:7136
	s_waitcnt lgkmcnt(6)
	v_pk_fma_f32 v[180:181], v[110:111], v[174:175], v[180:181] op_sel:[0,1,0] neg_lo:[1,0,0] neg_hi:[1,0,0]
	v_pk_fma_f32 v[182:183], v[112:113], v[174:175], v[182:183] op_sel:[0,1,0] neg_lo:[1,0,0] neg_hi:[1,0,0]
	ds_read_b128 v[106:109], v0 offset:7152
	s_waitcnt lgkmcnt(6)
	v_pk_fma_f32 v[184:185], v[114:115], v[174:175], v[184:185] op_sel:[0,1,0] neg_lo:[1,0,0] neg_hi:[1,0,0]
	v_pk_fma_f32 v[186:187], v[116:117], v[174:175], v[186:187] op_sel:[0,1,0] neg_lo:[1,0,0] neg_hi:[1,0,0]
	ds_read_b128 v[110:113], v0 offset:7280
	s_waitcnt lgkmcnt(6)
	v_pk_fma_f32 v[188:189], v[118:119], v[174:175], v[188:189] op_sel:[0,1,0] neg_lo:[1,0,0] neg_hi:[1,0,0]
	v_pk_fma_f32 v[190:191], v[120:121], v[174:175], v[190:191] op_sel:[0,1,0] neg_lo:[1,0,0] neg_hi:[1,0,0]
	ds_read_b128 v[114:117], v0 offset:7296
	s_waitcnt lgkmcnt(6)
	v_pk_fma_f32 v[192:193], v[90:91], v[174:175], v[192:193] op_sel:[0,1,0] neg_lo:[1,0,0] neg_hi:[1,0,0]
	v_pk_fma_f32 v[198:199], v[92:93], v[174:175], v[198:199] op_sel:[0,1,0] neg_lo:[1,0,0] neg_hi:[1,0,0]
	ds_read_b128 v[118:121], v0 offset:7312
	s_waitcnt lgkmcnt(6)
	v_pk_fma_f32 v[200:201], v[94:95], v[174:175], v[200:201] op_sel:[0,1,0] neg_lo:[1,0,0] neg_hi:[1,0,0]
	v_pk_fma_f32 v[202:203], v[96:97], v[174:175], v[202:203] op_sel:[0,1,0] neg_lo:[1,0,0] neg_hi:[1,0,0]
	ds_read_b128 v[90:93], v0 offset:7328
	s_waitcnt lgkmcnt(6)
	v_pk_fma_f32 v[204:205], v[98:99], v[174:175], v[204:205] op_sel:[0,1,0] neg_lo:[1,0,0] neg_hi:[1,0,0]
	v_pk_fma_f32 v[208:209], v[100:101], v[174:175], v[208:209] op_sel:[0,1,0] neg_lo:[1,0,0] neg_hi:[1,0,0]
	ds_read_b128 v[94:97], v0 offset:7344
	s_waitcnt lgkmcnt(6)
; #define LAS __attribute__((address_space(3)))
; #define PIN16(o) asm volatile("" : "+v"(xr[o]), "+v"(xr[o + 1]), "+v"(xr[o + 2]), "+v"(xr[o + 3]), "+v"(xr[o + 4]), "+v"(xr[o + 5]), "+v"(xr[o + 6]), "+v"(xr[o + 7]), "+v"(xr[o + 8]), "+v"(xr[o + 9]), "+v"(xr[o + 10]), "+v"(xr[o + 11]), "+v"(xr[o + 12]), "+v"(xr[o + 13]), "+v"(xr[o + 14]), "+v"(xr[o + 15]) :: "memory")
; DI void gdn_prep_item(LAS unsigned char* lds, const Ctx& c, int l, int item) {
;     ...
; #pragma unroll
;         for (int j = 0; j < 63; ++j) {
;             const float xj = xr[j];
; #pragma unroll
;             for (int i4 = (j + 1) / 4; i4 < 16; ++i4) { const f32x4 Lv = *(const LAS f32x4*)(Lb + j * 64 + 4 * i4);
; #pragma unroll
;                 for (int q = 0; q < 4; ++q) xr[4 * i4 + q] -= Lv[q] * xj; }
;     ...
;             PIN16(0); PIN16(16); PIN16(32); PIN16(48);
;         }
	v_pk_fma_f32 v[210:211], v[102:103], v[174:175], v[210:211] op_sel:[0,1,0] neg_lo:[1,0,0] neg_hi:[1,0,0]
	v_pk_fma_f32 v[212:213], v[104:105], v[174:175], v[212:213] op_sel:[0,1,0] neg_lo:[1,0,0] neg_hi:[1,0,0]
	ds_read_b128 v[98:101], v0 offset:7360
	s_waitcnt lgkmcnt(6)
	v_pk_fma_f32 v[214:215], v[106:107], v[174:175], v[214:215] op_sel:[0,1,0] neg_lo:[1,0,0] neg_hi:[1,0,0]
	v_pk_fma_f32 v[216:217], v[108:109], v[174:175], v[216:217] op_sel:[0,1,0] neg_lo:[1,0,0] neg_hi:[1,0,0]
	ds_read_b128 v[102:105], v0 offset:7376
	s_waitcnt lgkmcnt(6)
	v_pk_fma_f32 v[176:177], v[110:111], v[176:177], v[176:177] op_sel_hi:[1,0,1] neg_lo:[1,0,0] neg_hi:[1,0,0]
	v_pk_fma_f32 v[178:179], v[112:113], v[176:177], v[178:179] op_sel_hi:[1,0,1] neg_lo:[1,0,0] neg_hi:[1,0,0]
	ds_read_b128 v[106:109], v0 offset:7392
	s_waitcnt lgkmcnt(6)
	v_pk_fma_f32 v[180:181], v[114:115], v[176:177], v[180:181] op_sel_hi:[1,0,1] neg_lo:[1,0,0] neg_hi:[1,0,0]
	v_pk_fma_f32 v[182:183], v[116:117], v[176:177], v[182:183] op_sel_hi:[1,0,1] neg_lo:[1,0,0] neg_hi:[1,0,0]
	ds_read_b128 v[110:113], v0 offset:7408
	s_waitcnt lgkmcnt(6)
	v_pk_fma_f32 v[184:185], v[118:119], v[176:177], v[184:185] op_sel_hi:[1,0,1] neg_lo:[1,0,0] neg_hi:[1,0,0]
	v_pk_fma_f32 v[186:187], v[120:121], v[176:177], v[186:187] op_sel_hi:[1,0,1] neg_lo:[1,0,0] neg_hi:[1,0,0]
	ds_read_b128 v[114:117], v0 offset:7536
	s_waitcnt lgkmcnt(6)
	v_pk_fma_f32 v[188:189], v[90:91], v[176:177], v[188:189] op_sel_hi:[1,0,1] neg_lo:[1,0,0] neg_hi:[1,0,0]
	v_pk_fma_f32 v[190:191], v[92:93], v[176:177], v[190:191] op_sel_hi:[1,0,1] neg_lo:[1,0,0] neg_hi:[1,0,0]
	ds_read_b128 v[118:121], v0 offset:7552
	s_waitcnt lgkmcnt(6)
	v_pk_fma_f32 v[192:193], v[94:95], v[176:177], v[192:193] op_sel_hi:[1,0,1] neg_lo:[1,0,0] neg_hi:[1,0,0]
	v_pk_fma_f32 v[198:199], v[96:97], v[176:177], v[198:199] op_sel_hi:[1,0,1] neg_lo:[1,0,0] neg_hi:[1,0,0]
	ds_read_b128 v[90:93], v0 offset:7568
	s_waitcnt lgkmcnt(6)
	v_pk_fma_f32 v[200:201], v[98:99], v[176:177], v[200:201] op_sel_hi:[1,0,1] neg_lo:[1,0,0] neg_hi:[1,0,0]
	v_pk_fma_f32 v[202:203], v[100:101], v[176:177], v[202:203] op_sel_hi:[1,0,1] neg_lo:[1,0,0] neg_hi:[1,0,0]
	ds_read_b128 v[94:97], v0 offset:7584
	s_waitcnt lgkmcnt(6)
	v_pk_fma_f32 v[204:205], v[102:103], v[176:177], v[204:205] op_sel_hi:[1,0,1] neg_lo:[1,0,0] neg_hi:[1,0,0]
	v_pk_fma_f32 v[208:209], v[104:105], v[176:177], v[208:209] op_sel_hi:[1,0,1] neg_lo:[1,0,0] neg_hi:[1,0,0]
	ds_read_b128 v[98:101], v0 offset:7600
	s_waitcnt lgkmcnt(6)
	v_pk_fma_f32 v[210:211], v[106:107], v[176:177], v[210:211] op_sel_hi:[1,0,1] neg_lo:[1,0,0] neg_hi:[1,0,0]
	v_pk_fma_f32 v[212:213], v[108:109], v[176:177], v[212:213] op_sel_hi:[1,0,1] neg_lo:[1,0,0] neg_hi:[1,0,0]
	ds_read_b128 v[102:105], v0 offset:7616
	s_waitcnt lgkmcnt(6)
	v_pk_fma_f32 v[214:215], v[110:111], v[176:177], v[214:215] op_sel_hi:[1,0,1] neg_lo:[1,0,0] neg_hi:[1,0,0]
	v_pk_fma_f32 v[216:217], v[112:113], v[176:177], v[216:217] op_sel_hi:[1,0,1] neg_lo:[1,0,0] neg_hi:[1,0,0]
	ds_read_b128 v[106:109], v0 offset:7632
	s_waitcnt lgkmcnt(6)
	v_pk_fma_f32 v[178:179], v[116:117], v[176:177], v[178:179] op_sel:[0,1,0] neg_lo:[1,0,0] neg_hi:[1,0,0]
	ds_read_b128 v[110:113], v0 offset:7648
	s_waitcnt lgkmcnt(6)
	v_pk_fma_f32 v[180:181], v[118:119], v[176:177], v[180:181] op_sel:[0,1,0] neg_lo:[1,0,0] neg_hi:[1,0,0]
	v_pk_fma_f32 v[182:183], v[120:121], v[176:177], v[182:183] op_sel:[0,1,0] neg_lo:[1,0,0] neg_hi:[1,0,0]
	ds_read_b128 v[114:117], v0 offset:7664
	s_waitcnt lgkmcnt(6)
	v_pk_fma_f32 v[184:185], v[90:91], v[176:177], v[184:185] op_sel:[0,1,0] neg_lo:[1,0,0] neg_hi:[1,0,0]
	v_pk_fma_f32 v[186:187], v[92:93], v[176:177], v[186:187] op_sel:[0,1,0] neg_lo:[1,0,0] neg_hi:[1,0,0]
	ds_read_b128 v[118:121], v0 offset:7792
	s_waitcnt lgkmcnt(6)
	v_pk_fma_f32 v[188:189], v[94:95], v[176:177], v[188:189] op_sel:[0,1,0] neg_lo:[1,0,0] neg_hi:[1,0,0]
	v_pk_fma_f32 v[190:191], v[96:97], v[176:177], v[190:191] op_sel:[0,1,0] neg_lo:[1,0,0] neg_hi:[1,0,0]
	ds_read_b128 v[90:93], v0 offset:7808
	s_waitcnt lgkmcnt(6)
	v_pk_fma_f32 v[192:193], v[98:99], v[176:177], v[192:193] op_sel:[0,1,0] neg_lo:[1,0,0] neg_hi:[1,0,0]
	v_pk_fma_f32 v[198:199], v[100:101], v[176:177], v[198:199] op_sel:[0,1,0] neg_lo:[1,0,0] neg_hi:[1,0,0]
	ds_read_b128 v[94:97], v0 offset:7824
	s_waitcnt lgkmcnt(6)
	v_pk_fma_f32 v[200:201], v[102:103], v[176:177], v[200:201] op_sel:[0,1,0] neg_lo:[1,0,0] neg_hi:[1,0,0]
	v_pk_fma_f32 v[202:203], v[104:105], v[176:177], v[202:203] op_sel:[0,1,0] neg_lo:[1,0,0] neg_hi:[1,0,0]
	ds_read_b128 v[98:101], v0 offset:7840
	s_waitcnt lgkmcnt(6)
	v_pk_fma_f32 v[204:205], v[106:107], v[176:177], v[204:205] op_sel:[0,1,0] neg_lo:[1,0,0] neg_hi:[1,0,0]
	v_pk_fma_f32 v[208:209], v[108:109], v[176:177], v[208:209] op_sel:[0,1,0] neg_lo:[1,0,0] neg_hi:[1,0,0]
	ds_read_b128 v[102:105], v0 offset:7856
	s_waitcnt lgkmcnt(6)
	v_pk_fma_f32 v[210:211], v[110:111], v[176:177], v[210:211] op_sel:[0,1,0] neg_lo:[1,0,0] neg_hi:[1,0,0]
	v_pk_fma_f32 v[212:213], v[112:113], v[176:177], v[212:213] op_sel:[0,1,0] neg_lo:[1,0,0] neg_hi:[1,0,0]
	ds_read_b128 v[106:109], v0 offset:7872
	s_waitcnt lgkmcnt(6)
	v_pk_fma_f32 v[214:215], v[114:115], v[176:177], v[214:215] op_sel:[0,1,0] neg_lo:[1,0,0] neg_hi:[1,0,0]
	v_pk_fma_f32 v[216:217], v[116:117], v[176:177], v[216:217] op_sel:[0,1,0] neg_lo:[1,0,0] neg_hi:[1,0,0]
	ds_read_b128 v[110:113], v0 offset:7888
	s_waitcnt lgkmcnt(6)
	v_pk_fma_f32 v[178:179], v[120:121], v[178:179], v[178:179] op_sel_hi:[1,0,1] neg_lo:[1,0,0] neg_hi:[1,0,0]
	ds_read_b128 v[114:117], v0 offset:7904
	s_waitcnt lgkmcnt(6)
; #define LAS __attribute__((address_space(3)))
; #define PIN16(o) asm volatile("" : "+v"(xr[o]), "+v"(xr[o + 1]), "+v"(xr[o + 2]), "+v"(xr[o + 3]), "+v"(xr[o + 4]), "+v"(xr[o + 5]), "+v"(xr[o + 6]), "+v"(xr[o + 7]), "+v"(xr[o + 8]), "+v"(xr[o + 9]), "+v"(xr[o + 10]), "+v"(xr[o + 11]), "+v"(xr[o + 12]), "+v"(xr[o + 13]), "+v"(xr[o + 14]), "+v"(xr[o + 15]) :: "memory")
; DI void gdn_prep_item(LAS unsigned char* lds, const Ctx& c, int l, int item) {
;     ...
; #pragma unroll
;         for (int j = 0; j < 63; ++j) {
;             const float xj = xr[j];
; #pragma unroll
;             for (int i4 = (j + 1) / 4; i4 < 16; ++i4) { const f32x4 Lv = *(const LAS f32x4*)(Lb + j * 64 + 4 * i4);
; #pragma unroll
;                 for (int q = 0; q < 4; ++q) xr[4 * i4 + q] -= Lv[q] * xj; }
;     ...
;             PIN16(0); PIN16(16); PIN16(32); PIN16(48);
;         }
	v_pk_fma_f32 v[180:181], v[90:91], v[178:179], v[180:181] op_sel_hi:[1,0,1] neg_lo:[1,0,0] neg_hi:[1,0,0]
	v_pk_fma_f32 v[182:183], v[92:93], v[178:179], v[182:183] op_sel_hi:[1,0,1] neg_lo:[1,0,0] neg_hi:[1,0,0]
	ds_read_b128 v[118:121], v0 offset:7920
	s_waitcnt lgkmcnt(6)
	v_pk_fma_f32 v[184:185], v[94:95], v[178:179], v[184:185] op_sel_hi:[1,0,1] neg_lo:[1,0,0] neg_hi:[1,0,0]
	v_pk_fma_f32 v[186:187], v[96:97], v[178:179], v[186:187] op_sel_hi:[1,0,1] neg_lo:[1,0,0] neg_hi:[1,0,0]
	ds_read_b128 v[90:93], v0 offset:8064
	s_waitcnt lgkmcnt(6)
	v_pk_fma_f32 v[188:189], v[98:99], v[178:179], v[188:189] op_sel_hi:[1,0,1] neg_lo:[1,0,0] neg_hi:[1,0,0]
	v_pk_fma_f32 v[190:191], v[100:101], v[178:179], v[190:191] op_sel_hi:[1,0,1] neg_lo:[1,0,0] neg_hi:[1,0,0]
	ds_read_b128 v[94:97], v0 offset:8080
	s_waitcnt lgkmcnt(6)
	v_pk_fma_f32 v[192:193], v[102:103], v[178:179], v[192:193] op_sel_hi:[1,0,1] neg_lo:[1,0,0] neg_hi:[1,0,0]
	v_pk_fma_f32 v[198:199], v[104:105], v[178:179], v[198:199] op_sel_hi:[1,0,1] neg_lo:[1,0,0] neg_hi:[1,0,0]
	ds_read_b128 v[98:101], v0 offset:8096
	s_waitcnt lgkmcnt(6)
	v_pk_fma_f32 v[200:201], v[106:107], v[178:179], v[200:201] op_sel_hi:[1,0,1] neg_lo:[1,0,0] neg_hi:[1,0,0]
	v_pk_fma_f32 v[202:203], v[108:109], v[178:179], v[202:203] op_sel_hi:[1,0,1] neg_lo:[1,0,0] neg_hi:[1,0,0]
	ds_read_b128 v[102:105], v0 offset:8112
	s_waitcnt lgkmcnt(6)
	v_pk_fma_f32 v[204:205], v[110:111], v[178:179], v[204:205] op_sel_hi:[1,0,1] neg_lo:[1,0,0] neg_hi:[1,0,0]
	v_pk_fma_f32 v[208:209], v[112:113], v[178:179], v[208:209] op_sel_hi:[1,0,1] neg_lo:[1,0,0] neg_hi:[1,0,0]
	ds_read_b128 v[106:109], v0 offset:8128
	s_waitcnt lgkmcnt(6)
	v_pk_fma_f32 v[210:211], v[114:115], v[178:179], v[210:211] op_sel_hi:[1,0,1] neg_lo:[1,0,0] neg_hi:[1,0,0]
	v_pk_fma_f32 v[212:213], v[116:117], v[178:179], v[212:213] op_sel_hi:[1,0,1] neg_lo:[1,0,0] neg_hi:[1,0,0]
	ds_read_b128 v[110:113], v0 offset:8144
	s_waitcnt lgkmcnt(6)
	v_pk_fma_f32 v[214:215], v[118:119], v[178:179], v[214:215] op_sel_hi:[1,0,1] neg_lo:[1,0,0] neg_hi:[1,0,0]
	v_pk_fma_f32 v[216:217], v[120:121], v[178:179], v[216:217] op_sel_hi:[1,0,1] neg_lo:[1,0,0] neg_hi:[1,0,0]
	ds_read_b128 v[114:117], v0 offset:8160
	s_waitcnt lgkmcnt(6)
	v_pk_fma_f32 v[180:181], v[90:91], v[178:179], v[180:181] op_sel:[0,1,0] neg_lo:[1,0,0] neg_hi:[1,0,0]
	v_pk_fma_f32 v[182:183], v[92:93], v[178:179], v[182:183] op_sel:[0,1,0] neg_lo:[1,0,0] neg_hi:[1,0,0]
	ds_read_b128 v[118:121], v0 offset:8176
	s_waitcnt lgkmcnt(6)
	v_pk_fma_f32 v[184:185], v[94:95], v[178:179], v[184:185] op_sel:[0,1,0] neg_lo:[1,0,0] neg_hi:[1,0,0]
	v_pk_fma_f32 v[186:187], v[96:97], v[178:179], v[186:187] op_sel:[0,1,0] neg_lo:[1,0,0] neg_hi:[1,0,0]
	ds_read_b128 v[90:93], v0 offset:8320
	s_waitcnt lgkmcnt(6)
	v_pk_fma_f32 v[188:189], v[98:99], v[178:179], v[188:189] op_sel:[0,1,0] neg_lo:[1,0,0] neg_hi:[1,0,0]
	v_pk_fma_f32 v[190:191], v[100:101], v[178:179], v[190:191] op_sel:[0,1,0] neg_lo:[1,0,0] neg_hi:[1,0,0]
	ds_read_b128 v[94:97], v0 offset:8336
	s_waitcnt lgkmcnt(6)
	v_pk_fma_f32 v[192:193], v[102:103], v[178:179], v[192:193] op_sel:[0,1,0] neg_lo:[1,0,0] neg_hi:[1,0,0]
	v_pk_fma_f32 v[198:199], v[104:105], v[178:179], v[198:199] op_sel:[0,1,0] neg_lo:[1,0,0] neg_hi:[1,0,0]
	ds_read_b128 v[98:101], v0 offset:8352
	s_waitcnt lgkmcnt(6)
	v_pk_fma_f32 v[200:201], v[106:107], v[178:179], v[200:201] op_sel:[0,1,0] neg_lo:[1,0,0] neg_hi:[1,0,0]
	v_pk_fma_f32 v[202:203], v[108:109], v[178:179], v[202:203] op_sel:[0,1,0] neg_lo:[1,0,0] neg_hi:[1,0,0]
	ds_read_b128 v[102:105], v0 offset:8368
	s_waitcnt lgkmcnt(6)
	v_pk_fma_f32 v[204:205], v[110:111], v[178:179], v[204:205] op_sel:[0,1,0] neg_lo:[1,0,0] neg_hi:[1,0,0]
	v_pk_fma_f32 v[208:209], v[112:113], v[178:179], v[208:209] op_sel:[0,1,0] neg_lo:[1,0,0] neg_hi:[1,0,0]
	ds_read_b128 v[106:109], v0 offset:8384
	s_waitcnt lgkmcnt(6)
	v_pk_fma_f32 v[210:211], v[114:115], v[178:179], v[210:211] op_sel:[0,1,0] neg_lo:[1,0,0] neg_hi:[1,0,0]
	v_pk_fma_f32 v[212:213], v[116:117], v[178:179], v[212:213] op_sel:[0,1,0] neg_lo:[1,0,0] neg_hi:[1,0,0]
	ds_read_b128 v[110:113], v0 offset:8400
	s_waitcnt lgkmcnt(6)
	v_pk_fma_f32 v[214:215], v[118:119], v[178:179], v[214:215] op_sel:[0,1,0] neg_lo:[1,0,0] neg_hi:[1,0,0]
	v_pk_fma_f32 v[216:217], v[120:121], v[178:179], v[216:217] op_sel:[0,1,0] neg_lo:[1,0,0] neg_hi:[1,0,0]
	ds_read_b128 v[114:117], v0 offset:8416
	s_waitcnt lgkmcnt(6)
	v_pk_fma_f32 v[180:181], v[90:91], v[180:181], v[180:181] op_sel_hi:[1,0,1] neg_lo:[1,0,0] neg_hi:[1,0,0]
	v_pk_fma_f32 v[182:183], v[92:93], v[180:181], v[182:183] op_sel_hi:[1,0,1] neg_lo:[1,0,0] neg_hi:[1,0,0]
	ds_read_b128 v[118:121], v0 offset:8432
	s_waitcnt lgkmcnt(6)
	v_pk_fma_f32 v[184:185], v[94:95], v[180:181], v[184:185] op_sel_hi:[1,0,1] neg_lo:[1,0,0] neg_hi:[1,0,0]
	v_pk_fma_f32 v[186:187], v[96:97], v[180:181], v[186:187] op_sel_hi:[1,0,1] neg_lo:[1,0,0] neg_hi:[1,0,0]
	ds_read_b128 v[90:93], v0 offset:8576
	s_waitcnt lgkmcnt(6)
	v_pk_fma_f32 v[188:189], v[98:99], v[180:181], v[188:189] op_sel_hi:[1,0,1] neg_lo:[1,0,0] neg_hi:[1,0,0]
	v_pk_fma_f32 v[190:191], v[100:101], v[180:181], v[190:191] op_sel_hi:[1,0,1] neg_lo:[1,0,0] neg_hi:[1,0,0]
	ds_read_b128 v[94:97], v0 offset:8592
	s_waitcnt lgkmcnt(6)
	v_pk_fma_f32 v[192:193], v[102:103], v[180:181], v[192:193] op_sel_hi:[1,0,1] neg_lo:[1,0,0] neg_hi:[1,0,0]
	v_pk_fma_f32 v[198:199], v[104:105], v[180:181], v[198:199] op_sel_hi:[1,0,1] neg_lo:[1,0,0] neg_hi:[1,0,0]
	ds_read_b128 v[98:101], v0 offset:8608
	s_waitcnt lgkmcnt(6)
; #define LAS __attribute__((address_space(3)))
; #define PIN16(o) asm volatile("" : "+v"(xr[o]), "+v"(xr[o + 1]), "+v"(xr[o + 2]), "+v"(xr[o + 3]), "+v"(xr[o + 4]), "+v"(xr[o + 5]), "+v"(xr[o + 6]), "+v"(xr[o + 7]), "+v"(xr[o + 8]), "+v"(xr[o + 9]), "+v"(xr[o + 10]), "+v"(xr[o + 11]), "+v"(xr[o + 12]), "+v"(xr[o + 13]), "+v"(xr[o + 14]), "+v"(xr[o + 15]) :: "memory")
; DI void gdn_prep_item(LAS unsigned char* lds, const Ctx& c, int l, int item) {
;     ...
; #pragma unroll
;         for (int j = 0; j < 63; ++j) {
;             const float xj = xr[j];
; #pragma unroll
;             for (int i4 = (j + 1) / 4; i4 < 16; ++i4) { const f32x4 Lv = *(const LAS f32x4*)(Lb + j * 64 + 4 * i4);
; #pragma unroll
;                 for (int q = 0; q < 4; ++q) xr[4 * i4 + q] -= Lv[q] * xj; }
;     ...
;             PIN16(0); PIN16(16); PIN16(32); PIN16(48);
;         }
	v_pk_fma_f32 v[200:201], v[106:107], v[180:181], v[200:201] op_sel_hi:[1,0,1] neg_lo:[1,0,0] neg_hi:[1,0,0]
	v_pk_fma_f32 v[202:203], v[108:109], v[180:181], v[202:203] op_sel_hi:[1,0,1] neg_lo:[1,0,0] neg_hi:[1,0,0]
	ds_read_b128 v[102:105], v0 offset:8624
	s_waitcnt lgkmcnt(6)
	v_pk_fma_f32 v[204:205], v[110:111], v[180:181], v[204:205] op_sel_hi:[1,0,1] neg_lo:[1,0,0] neg_hi:[1,0,0]
	v_pk_fma_f32 v[208:209], v[112:113], v[180:181], v[208:209] op_sel_hi:[1,0,1] neg_lo:[1,0,0] neg_hi:[1,0,0]
	ds_read_b128 v[106:109], v0 offset:8640
	s_waitcnt lgkmcnt(6)
	v_pk_fma_f32 v[210:211], v[114:115], v[180:181], v[210:211] op_sel_hi:[1,0,1] neg_lo:[1,0,0] neg_hi:[1,0,0]
	v_pk_fma_f32 v[212:213], v[116:117], v[180:181], v[212:213] op_sel_hi:[1,0,1] neg_lo:[1,0,0] neg_hi:[1,0,0]
	ds_read_b128 v[110:113], v0 offset:8656
	s_waitcnt lgkmcnt(6)
	v_pk_fma_f32 v[214:215], v[118:119], v[180:181], v[214:215] op_sel_hi:[1,0,1] neg_lo:[1,0,0] neg_hi:[1,0,0]
	v_pk_fma_f32 v[216:217], v[120:121], v[180:181], v[216:217] op_sel_hi:[1,0,1] neg_lo:[1,0,0] neg_hi:[1,0,0]
	ds_read_b128 v[114:117], v0 offset:8672
	s_waitcnt lgkmcnt(6)
	v_pk_fma_f32 v[182:183], v[92:93], v[180:181], v[182:183] op_sel:[0,1,0] neg_lo:[1,0,0] neg_hi:[1,0,0]
	ds_read_b128 v[118:121], v0 offset:8688
	s_waitcnt lgkmcnt(6)
	v_pk_fma_f32 v[184:185], v[94:95], v[180:181], v[184:185] op_sel:[0,1,0] neg_lo:[1,0,0] neg_hi:[1,0,0]
	v_pk_fma_f32 v[186:187], v[96:97], v[180:181], v[186:187] op_sel:[0,1,0] neg_lo:[1,0,0] neg_hi:[1,0,0]
	ds_read_b128 v[90:93], v0 offset:8832
	s_waitcnt lgkmcnt(6)
	v_pk_fma_f32 v[188:189], v[98:99], v[180:181], v[188:189] op_sel:[0,1,0] neg_lo:[1,0,0] neg_hi:[1,0,0]
	v_pk_fma_f32 v[190:191], v[100:101], v[180:181], v[190:191] op_sel:[0,1,0] neg_lo:[1,0,0] neg_hi:[1,0,0]
	ds_read_b128 v[94:97], v0 offset:8848
	s_waitcnt lgkmcnt(6)
	v_pk_fma_f32 v[192:193], v[102:103], v[180:181], v[192:193] op_sel:[0,1,0] neg_lo:[1,0,0] neg_hi:[1,0,0]
	v_pk_fma_f32 v[198:199], v[104:105], v[180:181], v[198:199] op_sel:[0,1,0] neg_lo:[1,0,0] neg_hi:[1,0,0]
	ds_read_b128 v[98:101], v0 offset:8864
	s_waitcnt lgkmcnt(6)
	v_pk_fma_f32 v[200:201], v[106:107], v[180:181], v[200:201] op_sel:[0,1,0] neg_lo:[1,0,0] neg_hi:[1,0,0]
	v_pk_fma_f32 v[202:203], v[108:109], v[180:181], v[202:203] op_sel:[0,1,0] neg_lo:[1,0,0] neg_hi:[1,0,0]
	ds_read_b128 v[102:105], v0 offset:8880
	s_waitcnt lgkmcnt(6)
	v_pk_fma_f32 v[204:205], v[110:111], v[180:181], v[204:205] op_sel:[0,1,0] neg_lo:[1,0,0] neg_hi:[1,0,0]
	v_pk_fma_f32 v[208:209], v[112:113], v[180:181], v[208:209] op_sel:[0,1,0] neg_lo:[1,0,0] neg_hi:[1,0,0]
	ds_read_b128 v[106:109], v0 offset:8896
	s_waitcnt lgkmcnt(6)
	v_pk_fma_f32 v[210:211], v[114:115], v[180:181], v[210:211] op_sel:[0,1,0] neg_lo:[1,0,0] neg_hi:[1,0,0]
	v_pk_fma_f32 v[212:213], v[116:117], v[180:181], v[212:213] op_sel:[0,1,0] neg_lo:[1,0,0] neg_hi:[1,0,0]
	ds_read_b128 v[110:113], v0 offset:8912
	s_waitcnt lgkmcnt(6)
	v_pk_fma_f32 v[214:215], v[118:119], v[180:181], v[214:215] op_sel:[0,1,0] neg_lo:[1,0,0] neg_hi:[1,0,0]
	v_pk_fma_f32 v[216:217], v[120:121], v[180:181], v[216:217] op_sel:[0,1,0] neg_lo:[1,0,0] neg_hi:[1,0,0]
	ds_read_b128 v[114:117], v0 offset:8928
	s_waitcnt lgkmcnt(6)
	v_pk_fma_f32 v[182:183], v[92:93], v[182:183], v[182:183] op_sel_hi:[1,0,1] neg_lo:[1,0,0] neg_hi:[1,0,0]
	ds_read_b128 v[118:121], v0 offset:8944
	s_waitcnt lgkmcnt(6)
	v_pk_fma_f32 v[184:185], v[94:95], v[182:183], v[184:185] op_sel_hi:[1,0,1] neg_lo:[1,0,0] neg_hi:[1,0,0]
	v_pk_fma_f32 v[186:187], v[96:97], v[182:183], v[186:187] op_sel_hi:[1,0,1] neg_lo:[1,0,0] neg_hi:[1,0,0]
	ds_read_b128 v[90:93], v0 offset:9104
	s_waitcnt lgkmcnt(6)
	v_pk_fma_f32 v[188:189], v[98:99], v[182:183], v[188:189] op_sel_hi:[1,0,1] neg_lo:[1,0,0] neg_hi:[1,0,0]
	v_pk_fma_f32 v[190:191], v[100:101], v[182:183], v[190:191] op_sel_hi:[1,0,1] neg_lo:[1,0,0] neg_hi:[1,0,0]
	ds_read_b128 v[94:97], v0 offset:9120
	s_waitcnt lgkmcnt(6)
	v_pk_fma_f32 v[192:193], v[102:103], v[182:183], v[192:193] op_sel_hi:[1,0,1] neg_lo:[1,0,0] neg_hi:[1,0,0]
	v_pk_fma_f32 v[198:199], v[104:105], v[182:183], v[198:199] op_sel_hi:[1,0,1] neg_lo:[1,0,0] neg_hi:[1,0,0]
	ds_read_b128 v[98:101], v0 offset:9136
	s_waitcnt lgkmcnt(6)
	v_pk_fma_f32 v[200:201], v[106:107], v[182:183], v[200:201] op_sel_hi:[1,0,1] neg_lo:[1,0,0] neg_hi:[1,0,0]
	v_pk_fma_f32 v[202:203], v[108:109], v[182:183], v[202:203] op_sel_hi:[1,0,1] neg_lo:[1,0,0] neg_hi:[1,0,0]
	ds_read_b128 v[102:105], v0 offset:9152
	s_waitcnt lgkmcnt(6)
	v_pk_fma_f32 v[204:205], v[110:111], v[182:183], v[204:205] op_sel_hi:[1,0,1] neg_lo:[1,0,0] neg_hi:[1,0,0]
	v_pk_fma_f32 v[208:209], v[112:113], v[182:183], v[208:209] op_sel_hi:[1,0,1] neg_lo:[1,0,0] neg_hi:[1,0,0]
	ds_read_b128 v[106:109], v0 offset:9168
	s_waitcnt lgkmcnt(6)
	v_pk_fma_f32 v[210:211], v[114:115], v[182:183], v[210:211] op_sel_hi:[1,0,1] neg_lo:[1,0,0] neg_hi:[1,0,0]
	v_pk_fma_f32 v[212:213], v[116:117], v[182:183], v[212:213] op_sel_hi:[1,0,1] neg_lo:[1,0,0] neg_hi:[1,0,0]
	ds_read_b128 v[110:113], v0 offset:9184
	s_waitcnt lgkmcnt(6)
	v_pk_fma_f32 v[214:215], v[118:119], v[182:183], v[214:215] op_sel_hi:[1,0,1] neg_lo:[1,0,0] neg_hi:[1,0,0]
	v_pk_fma_f32 v[216:217], v[120:121], v[182:183], v[216:217] op_sel_hi:[1,0,1] neg_lo:[1,0,0] neg_hi:[1,0,0]
	ds_read_b128 v[114:117], v0 offset:9200
	s_waitcnt lgkmcnt(6)
	v_pk_fma_f32 v[184:185], v[90:91], v[182:183], v[184:185] op_sel:[0,1,0] neg_lo:[1,0,0] neg_hi:[1,0,0]
	v_pk_fma_f32 v[186:187], v[92:93], v[182:183], v[186:187] op_sel:[0,1,0] neg_lo:[1,0,0] neg_hi:[1,0,0]
	ds_read_b128 v[118:121], v0 offset:9360
	s_waitcnt lgkmcnt(6)
; #define LAS __attribute__((address_space(3)))
; #define PIN16(o) asm volatile("" : "+v"(xr[o]), "+v"(xr[o + 1]), "+v"(xr[o + 2]), "+v"(xr[o + 3]), "+v"(xr[o + 4]), "+v"(xr[o + 5]), "+v"(xr[o + 6]), "+v"(xr[o + 7]), "+v"(xr[o + 8]), "+v"(xr[o + 9]), "+v"(xr[o + 10]), "+v"(xr[o + 11]), "+v"(xr[o + 12]), "+v"(xr[o + 13]), "+v"(xr[o + 14]), "+v"(xr[o + 15]) :: "memory")
; DI void gdn_prep_item(LAS unsigned char* lds, const Ctx& c, int l, int item) {
;     ...
; #pragma unroll
;         for (int j = 0; j < 63; ++j) {
;             const float xj = xr[j];
; #pragma unroll
;             for (int i4 = (j + 1) / 4; i4 < 16; ++i4) { const f32x4 Lv = *(const LAS f32x4*)(Lb + j * 64 + 4 * i4);
; #pragma unroll
;                 for (int q = 0; q < 4; ++q) xr[4 * i4 + q] -= Lv[q] * xj; }
;     ...
;             PIN16(0); PIN16(16); PIN16(32); PIN16(48);
;         }
	v_pk_fma_f32 v[188:189], v[94:95], v[182:183], v[188:189] op_sel:[0,1,0] neg_lo:[1,0,0] neg_hi:[1,0,0]
	v_pk_fma_f32 v[190:191], v[96:97], v[182:183], v[190:191] op_sel:[0,1,0] neg_lo:[1,0,0] neg_hi:[1,0,0]
	ds_read_b128 v[90:93], v0 offset:9376
	s_waitcnt lgkmcnt(6)
	v_pk_fma_f32 v[192:193], v[98:99], v[182:183], v[192:193] op_sel:[0,1,0] neg_lo:[1,0,0] neg_hi:[1,0,0]
	v_pk_fma_f32 v[198:199], v[100:101], v[182:183], v[198:199] op_sel:[0,1,0] neg_lo:[1,0,0] neg_hi:[1,0,0]
	ds_read_b128 v[94:97], v0 offset:9392
	s_waitcnt lgkmcnt(6)
	v_pk_fma_f32 v[200:201], v[102:103], v[182:183], v[200:201] op_sel:[0,1,0] neg_lo:[1,0,0] neg_hi:[1,0,0]
	v_pk_fma_f32 v[202:203], v[104:105], v[182:183], v[202:203] op_sel:[0,1,0] neg_lo:[1,0,0] neg_hi:[1,0,0]
	ds_read_b128 v[98:101], v0 offset:9408
	s_waitcnt lgkmcnt(6)
	v_pk_fma_f32 v[204:205], v[106:107], v[182:183], v[204:205] op_sel:[0,1,0] neg_lo:[1,0,0] neg_hi:[1,0,0]
	v_pk_fma_f32 v[208:209], v[108:109], v[182:183], v[208:209] op_sel:[0,1,0] neg_lo:[1,0,0] neg_hi:[1,0,0]
	ds_read_b128 v[102:105], v0 offset:9424
	s_waitcnt lgkmcnt(6)
	v_pk_fma_f32 v[210:211], v[110:111], v[182:183], v[210:211] op_sel:[0,1,0] neg_lo:[1,0,0] neg_hi:[1,0,0]
	v_pk_fma_f32 v[212:213], v[112:113], v[182:183], v[212:213] op_sel:[0,1,0] neg_lo:[1,0,0] neg_hi:[1,0,0]
	ds_read_b128 v[106:109], v0 offset:9440
	s_waitcnt lgkmcnt(6)
	v_pk_fma_f32 v[214:215], v[114:115], v[182:183], v[214:215] op_sel:[0,1,0] neg_lo:[1,0,0] neg_hi:[1,0,0]
	v_pk_fma_f32 v[216:217], v[116:117], v[182:183], v[216:217] op_sel:[0,1,0] neg_lo:[1,0,0] neg_hi:[1,0,0]
	ds_read_b128 v[110:113], v0 offset:9456
	s_waitcnt lgkmcnt(6)
	v_pk_fma_f32 v[184:185], v[118:119], v[184:185], v[184:185] op_sel_hi:[1,0,1] neg_lo:[1,0,0] neg_hi:[1,0,0]
	v_pk_fma_f32 v[186:187], v[120:121], v[184:185], v[186:187] op_sel_hi:[1,0,1] neg_lo:[1,0,0] neg_hi:[1,0,0]
	ds_read_b128 v[114:117], v0 offset:9616
	s_waitcnt lgkmcnt(6)
	v_pk_fma_f32 v[188:189], v[90:91], v[184:185], v[188:189] op_sel_hi:[1,0,1] neg_lo:[1,0,0] neg_hi:[1,0,0]
	v_pk_fma_f32 v[190:191], v[92:93], v[184:185], v[190:191] op_sel_hi:[1,0,1] neg_lo:[1,0,0] neg_hi:[1,0,0]
	ds_read_b128 v[118:121], v0 offset:9632
	s_waitcnt lgkmcnt(6)
	v_pk_fma_f32 v[192:193], v[94:95], v[184:185], v[192:193] op_sel_hi:[1,0,1] neg_lo:[1,0,0] neg_hi:[1,0,0]
	v_pk_fma_f32 v[198:199], v[96:97], v[184:185], v[198:199] op_sel_hi:[1,0,1] neg_lo:[1,0,0] neg_hi:[1,0,0]
	ds_read_b128 v[90:93], v0 offset:9648
	s_waitcnt lgkmcnt(6)
	v_pk_fma_f32 v[200:201], v[98:99], v[184:185], v[200:201] op_sel_hi:[1,0,1] neg_lo:[1,0,0] neg_hi:[1,0,0]
	v_pk_fma_f32 v[202:203], v[100:101], v[184:185], v[202:203] op_sel_hi:[1,0,1] neg_lo:[1,0,0] neg_hi:[1,0,0]
	ds_read_b128 v[94:97], v0 offset:9664
	s_waitcnt lgkmcnt(6)
	v_pk_fma_f32 v[204:205], v[102:103], v[184:185], v[204:205] op_sel_hi:[1,0,1] neg_lo:[1,0,0] neg_hi:[1,0,0]
	v_pk_fma_f32 v[208:209], v[104:105], v[184:185], v[208:209] op_sel_hi:[1,0,1] neg_lo:[1,0,0] neg_hi:[1,0,0]
	ds_read_b128 v[98:101], v0 offset:9680
	s_waitcnt lgkmcnt(6)
	v_pk_fma_f32 v[210:211], v[106:107], v[184:185], v[210:211] op_sel_hi:[1,0,1] neg_lo:[1,0,0] neg_hi:[1,0,0]
	v_pk_fma_f32 v[212:213], v[108:109], v[184:185], v[212:213] op_sel_hi:[1,0,1] neg_lo:[1,0,0] neg_hi:[1,0,0]
	ds_read_b128 v[102:105], v0 offset:9696
	s_waitcnt lgkmcnt(6)
	v_pk_fma_f32 v[214:215], v[110:111], v[184:185], v[214:215] op_sel_hi:[1,0,1] neg_lo:[1,0,0] neg_hi:[1,0,0]
	v_pk_fma_f32 v[216:217], v[112:113], v[184:185], v[216:217] op_sel_hi:[1,0,1] neg_lo:[1,0,0] neg_hi:[1,0,0]
	ds_read_b128 v[106:109], v0 offset:9712
	s_waitcnt lgkmcnt(6)
	v_pk_fma_f32 v[186:187], v[116:117], v[184:185], v[186:187] op_sel:[0,1,0] neg_lo:[1,0,0] neg_hi:[1,0,0]
	ds_read_b128 v[110:113], v0 offset:9872
	s_waitcnt lgkmcnt(6)
	v_pk_fma_f32 v[188:189], v[118:119], v[184:185], v[188:189] op_sel:[0,1,0] neg_lo:[1,0,0] neg_hi:[1,0,0]
	v_pk_fma_f32 v[190:191], v[120:121], v[184:185], v[190:191] op_sel:[0,1,0] neg_lo:[1,0,0] neg_hi:[1,0,0]
	ds_read_b128 v[114:117], v0 offset:9888
	s_waitcnt lgkmcnt(6)
	v_pk_fma_f32 v[192:193], v[90:91], v[184:185], v[192:193] op_sel:[0,1,0] neg_lo:[1,0,0] neg_hi:[1,0,0]
	v_pk_fma_f32 v[198:199], v[92:93], v[184:185], v[198:199] op_sel:[0,1,0] neg_lo:[1,0,0] neg_hi:[1,0,0]
	ds_read_b128 v[118:121], v0 offset:9904
	s_waitcnt lgkmcnt(6)
	v_pk_fma_f32 v[200:201], v[94:95], v[184:185], v[200:201] op_sel:[0,1,0] neg_lo:[1,0,0] neg_hi:[1,0,0]
	v_pk_fma_f32 v[202:203], v[96:97], v[184:185], v[202:203] op_sel:[0,1,0] neg_lo:[1,0,0] neg_hi:[1,0,0]
	ds_read_b128 v[90:93], v0 offset:9920
	s_waitcnt lgkmcnt(6)
	v_pk_fma_f32 v[204:205], v[98:99], v[184:185], v[204:205] op_sel:[0,1,0] neg_lo:[1,0,0] neg_hi:[1,0,0]
	v_pk_fma_f32 v[208:209], v[100:101], v[184:185], v[208:209] op_sel:[0,1,0] neg_lo:[1,0,0] neg_hi:[1,0,0]
	ds_read_b128 v[94:97], v0 offset:9936
	s_waitcnt lgkmcnt(6)
	v_pk_fma_f32 v[210:211], v[102:103], v[184:185], v[210:211] op_sel:[0,1,0] neg_lo:[1,0,0] neg_hi:[1,0,0]
	v_pk_fma_f32 v[212:213], v[104:105], v[184:185], v[212:213] op_sel:[0,1,0] neg_lo:[1,0,0] neg_hi:[1,0,0]
	ds_read_b128 v[98:101], v0 offset:9952
	s_waitcnt lgkmcnt(6)
	v_pk_fma_f32 v[214:215], v[106:107], v[184:185], v[214:215] op_sel:[0,1,0] neg_lo:[1,0,0] neg_hi:[1,0,0]
	v_pk_fma_f32 v[216:217], v[108:109], v[184:185], v[216:217] op_sel:[0,1,0] neg_lo:[1,0,0] neg_hi:[1,0,0]
	ds_read_b128 v[102:105], v0 offset:9968
	s_waitcnt lgkmcnt(6)
	v_pk_fma_f32 v[186:187], v[112:113], v[186:187], v[186:187] op_sel_hi:[1,0,1] neg_lo:[1,0,0] neg_hi:[1,0,0]
	ds_read_b128 v[106:109], v0 offset:10144
	s_waitcnt lgkmcnt(6)
; #define LAS __attribute__((address_space(3)))
; #define PIN16(o) asm volatile("" : "+v"(xr[o]), "+v"(xr[o + 1]), "+v"(xr[o + 2]), "+v"(xr[o + 3]), "+v"(xr[o + 4]), "+v"(xr[o + 5]), "+v"(xr[o + 6]), "+v"(xr[o + 7]), "+v"(xr[o + 8]), "+v"(xr[o + 9]), "+v"(xr[o + 10]), "+v"(xr[o + 11]), "+v"(xr[o + 12]), "+v"(xr[o + 13]), "+v"(xr[o + 14]), "+v"(xr[o + 15]) :: "memory")
; DI void gdn_prep_item(LAS unsigned char* lds, const Ctx& c, int l, int item) {
;     ...
; #pragma unroll
;         for (int j = 0; j < 63; ++j) {
;             const float xj = xr[j];
; #pragma unroll
;             for (int i4 = (j + 1) / 4; i4 < 16; ++i4) { const f32x4 Lv = *(const LAS f32x4*)(Lb + j * 64 + 4 * i4);
; #pragma unroll
;                 for (int q = 0; q < 4; ++q) xr[4 * i4 + q] -= Lv[q] * xj; }
;     ...
;             PIN16(0); PIN16(16); PIN16(32); PIN16(48);
;         }
	v_pk_fma_f32 v[188:189], v[114:115], v[186:187], v[188:189] op_sel_hi:[1,0,1] neg_lo:[1,0,0] neg_hi:[1,0,0]
	v_pk_fma_f32 v[190:191], v[116:117], v[186:187], v[190:191] op_sel_hi:[1,0,1] neg_lo:[1,0,0] neg_hi:[1,0,0]
	ds_read_b128 v[110:113], v0 offset:10160
	s_waitcnt lgkmcnt(6)
	v_pk_fma_f32 v[192:193], v[118:119], v[186:187], v[192:193] op_sel_hi:[1,0,1] neg_lo:[1,0,0] neg_hi:[1,0,0]
	v_pk_fma_f32 v[198:199], v[120:121], v[186:187], v[198:199] op_sel_hi:[1,0,1] neg_lo:[1,0,0] neg_hi:[1,0,0]
	ds_read_b128 v[114:117], v0 offset:10176
	s_waitcnt lgkmcnt(6)
	v_pk_fma_f32 v[200:201], v[90:91], v[186:187], v[200:201] op_sel_hi:[1,0,1] neg_lo:[1,0,0] neg_hi:[1,0,0]
	v_pk_fma_f32 v[202:203], v[92:93], v[186:187], v[202:203] op_sel_hi:[1,0,1] neg_lo:[1,0,0] neg_hi:[1,0,0]
	ds_read_b128 v[118:121], v0 offset:10192
	s_waitcnt lgkmcnt(6)
	v_pk_fma_f32 v[204:205], v[94:95], v[186:187], v[204:205] op_sel_hi:[1,0,1] neg_lo:[1,0,0] neg_hi:[1,0,0]
	v_pk_fma_f32 v[208:209], v[96:97], v[186:187], v[208:209] op_sel_hi:[1,0,1] neg_lo:[1,0,0] neg_hi:[1,0,0]
	ds_read_b128 v[90:93], v0 offset:10208
	s_waitcnt lgkmcnt(6)
	v_pk_fma_f32 v[210:211], v[98:99], v[186:187], v[210:211] op_sel_hi:[1,0,1] neg_lo:[1,0,0] neg_hi:[1,0,0]
	v_pk_fma_f32 v[212:213], v[100:101], v[186:187], v[212:213] op_sel_hi:[1,0,1] neg_lo:[1,0,0] neg_hi:[1,0,0]
	ds_read_b128 v[94:97], v0 offset:10224
	s_waitcnt lgkmcnt(6)
	v_pk_fma_f32 v[214:215], v[102:103], v[186:187], v[214:215] op_sel_hi:[1,0,1] neg_lo:[1,0,0] neg_hi:[1,0,0]
	v_pk_fma_f32 v[216:217], v[104:105], v[186:187], v[216:217] op_sel_hi:[1,0,1] neg_lo:[1,0,0] neg_hi:[1,0,0]
	ds_read_b128 v[98:101], v0 offset:10400
	s_waitcnt lgkmcnt(6)
	v_pk_fma_f32 v[188:189], v[106:107], v[186:187], v[188:189] op_sel:[0,1,0] neg_lo:[1,0,0] neg_hi:[1,0,0]
	v_pk_fma_f32 v[190:191], v[108:109], v[186:187], v[190:191] op_sel:[0,1,0] neg_lo:[1,0,0] neg_hi:[1,0,0]
	ds_read_b128 v[102:105], v0 offset:10416
	s_waitcnt lgkmcnt(6)
	v_pk_fma_f32 v[192:193], v[110:111], v[186:187], v[192:193] op_sel:[0,1,0] neg_lo:[1,0,0] neg_hi:[1,0,0]
	v_pk_fma_f32 v[198:199], v[112:113], v[186:187], v[198:199] op_sel:[0,1,0] neg_lo:[1,0,0] neg_hi:[1,0,0]
	ds_read_b128 v[106:109], v0 offset:10432
	s_waitcnt lgkmcnt(6)
	v_pk_fma_f32 v[200:201], v[114:115], v[186:187], v[200:201] op_sel:[0,1,0] neg_lo:[1,0,0] neg_hi:[1,0,0]
	v_pk_fma_f32 v[202:203], v[116:117], v[186:187], v[202:203] op_sel:[0,1,0] neg_lo:[1,0,0] neg_hi:[1,0,0]
	ds_read_b128 v[110:113], v0 offset:10448
	s_waitcnt lgkmcnt(6)
	v_pk_fma_f32 v[204:205], v[118:119], v[186:187], v[204:205] op_sel:[0,1,0] neg_lo:[1,0,0] neg_hi:[1,0,0]
	v_pk_fma_f32 v[208:209], v[120:121], v[186:187], v[208:209] op_sel:[0,1,0] neg_lo:[1,0,0] neg_hi:[1,0,0]
	ds_read_b128 v[114:117], v0 offset:10464
	s_waitcnt lgkmcnt(6)
	v_pk_fma_f32 v[210:211], v[90:91], v[186:187], v[210:211] op_sel:[0,1,0] neg_lo:[1,0,0] neg_hi:[1,0,0]
	v_pk_fma_f32 v[212:213], v[92:93], v[186:187], v[212:213] op_sel:[0,1,0] neg_lo:[1,0,0] neg_hi:[1,0,0]
	ds_read_b128 v[118:121], v0 offset:10480
	s_waitcnt lgkmcnt(6)
	v_pk_fma_f32 v[214:215], v[94:95], v[186:187], v[214:215] op_sel:[0,1,0] neg_lo:[1,0,0] neg_hi:[1,0,0]
	v_pk_fma_f32 v[216:217], v[96:97], v[186:187], v[216:217] op_sel:[0,1,0] neg_lo:[1,0,0] neg_hi:[1,0,0]
	ds_read_b128 v[90:93], v0 offset:10656
	s_waitcnt lgkmcnt(6)
	v_pk_fma_f32 v[188:189], v[98:99], v[188:189], v[188:189] op_sel_hi:[1,0,1] neg_lo:[1,0,0] neg_hi:[1,0,0]
	v_pk_fma_f32 v[190:191], v[100:101], v[188:189], v[190:191] op_sel_hi:[1,0,1] neg_lo:[1,0,0] neg_hi:[1,0,0]
	ds_read_b128 v[94:97], v0 offset:10672
	s_waitcnt lgkmcnt(6)
	v_pk_fma_f32 v[192:193], v[102:103], v[188:189], v[192:193] op_sel_hi:[1,0,1] neg_lo:[1,0,0] neg_hi:[1,0,0]
	v_pk_fma_f32 v[198:199], v[104:105], v[188:189], v[198:199] op_sel_hi:[1,0,1] neg_lo:[1,0,0] neg_hi:[1,0,0]
	ds_read_b128 v[98:101], v0 offset:10688
	s_waitcnt lgkmcnt(6)
	v_pk_fma_f32 v[200:201], v[106:107], v[188:189], v[200:201] op_sel_hi:[1,0,1] neg_lo:[1,0,0] neg_hi:[1,0,0]
	v_pk_fma_f32 v[202:203], v[108:109], v[188:189], v[202:203] op_sel_hi:[1,0,1] neg_lo:[1,0,0] neg_hi:[1,0,0]
	ds_read_b128 v[102:105], v0 offset:10704
	s_waitcnt lgkmcnt(6)
	v_pk_fma_f32 v[204:205], v[110:111], v[188:189], v[204:205] op_sel_hi:[1,0,1] neg_lo:[1,0,0] neg_hi:[1,0,0]
	v_pk_fma_f32 v[208:209], v[112:113], v[188:189], v[208:209] op_sel_hi:[1,0,1] neg_lo:[1,0,0] neg_hi:[1,0,0]
	ds_read_b128 v[106:109], v0 offset:10720
	s_waitcnt lgkmcnt(6)
	v_pk_fma_f32 v[210:211], v[114:115], v[188:189], v[210:211] op_sel_hi:[1,0,1] neg_lo:[1,0,0] neg_hi:[1,0,0]
	v_pk_fma_f32 v[212:213], v[116:117], v[188:189], v[212:213] op_sel_hi:[1,0,1] neg_lo:[1,0,0] neg_hi:[1,0,0]
	ds_read_b128 v[110:113], v0 offset:10736
	s_waitcnt lgkmcnt(6)
	v_pk_fma_f32 v[214:215], v[118:119], v[188:189], v[214:215] op_sel_hi:[1,0,1] neg_lo:[1,0,0] neg_hi:[1,0,0]
	v_pk_fma_f32 v[216:217], v[120:121], v[188:189], v[216:217] op_sel_hi:[1,0,1] neg_lo:[1,0,0] neg_hi:[1,0,0]
	ds_read_b128 v[114:117], v0 offset:10912
	s_waitcnt lgkmcnt(6)
	v_pk_fma_f32 v[190:191], v[92:93], v[188:189], v[190:191] op_sel:[0,1,0] neg_lo:[1,0,0] neg_hi:[1,0,0]
	ds_read_b128 v[118:121], v0 offset:10928
	s_waitcnt lgkmcnt(6)
	v_pk_fma_f32 v[192:193], v[94:95], v[188:189], v[192:193] op_sel:[0,1,0] neg_lo:[1,0,0] neg_hi:[1,0,0]
	v_pk_fma_f32 v[198:199], v[96:97], v[188:189], v[198:199] op_sel:[0,1,0] neg_lo:[1,0,0] neg_hi:[1,0,0]
	ds_read_b128 v[90:93], v0 offset:10944
	s_waitcnt lgkmcnt(6)
	v_pk_fma_f32 v[200:201], v[98:99], v[188:189], v[200:201] op_sel:[0,1,0] neg_lo:[1,0,0] neg_hi:[1,0,0]
	v_pk_fma_f32 v[202:203], v[100:101], v[188:189], v[202:203] op_sel:[0,1,0] neg_lo:[1,0,0] neg_hi:[1,0,0]
	ds_read_b128 v[94:97], v0 offset:10960
	s_waitcnt lgkmcnt(6)
; #define LAS __attribute__((address_space(3)))
; #define PIN16(o) asm volatile("" : "+v"(xr[o]), "+v"(xr[o + 1]), "+v"(xr[o + 2]), "+v"(xr[o + 3]), "+v"(xr[o + 4]), "+v"(xr[o + 5]), "+v"(xr[o + 6]), "+v"(xr[o + 7]), "+v"(xr[o + 8]), "+v"(xr[o + 9]), "+v"(xr[o + 10]), "+v"(xr[o + 11]), "+v"(xr[o + 12]), "+v"(xr[o + 13]), "+v"(xr[o + 14]), "+v"(xr[o + 15]) :: "memory")
; DI void gdn_prep_item(LAS unsigned char* lds, const Ctx& c, int l, int item) {
;     ...
; #pragma unroll
;         for (int j = 0; j < 63; ++j) {
;             const float xj = xr[j];
; #pragma unroll
;             for (int i4 = (j + 1) / 4; i4 < 16; ++i4) { const f32x4 Lv = *(const LAS f32x4*)(Lb + j * 64 + 4 * i4);
; #pragma unroll
;                 for (int q = 0; q < 4; ++q) xr[4 * i4 + q] -= Lv[q] * xj; }
;     ...
;             PIN16(0); PIN16(16); PIN16(32); PIN16(48);
;         }
	v_pk_fma_f32 v[204:205], v[102:103], v[188:189], v[204:205] op_sel:[0,1,0] neg_lo:[1,0,0] neg_hi:[1,0,0]
	v_pk_fma_f32 v[208:209], v[104:105], v[188:189], v[208:209] op_sel:[0,1,0] neg_lo:[1,0,0] neg_hi:[1,0,0]
	ds_read_b128 v[98:101], v0 offset:10976
	s_waitcnt lgkmcnt(6)
	v_pk_fma_f32 v[210:211], v[106:107], v[188:189], v[210:211] op_sel:[0,1,0] neg_lo:[1,0,0] neg_hi:[1,0,0]
	v_pk_fma_f32 v[212:213], v[108:109], v[188:189], v[212:213] op_sel:[0,1,0] neg_lo:[1,0,0] neg_hi:[1,0,0]
	ds_read_b128 v[102:105], v0 offset:10992
	s_waitcnt lgkmcnt(6)
	v_pk_fma_f32 v[214:215], v[110:111], v[188:189], v[214:215] op_sel:[0,1,0] neg_lo:[1,0,0] neg_hi:[1,0,0]
	v_pk_fma_f32 v[216:217], v[112:113], v[188:189], v[216:217] op_sel:[0,1,0] neg_lo:[1,0,0] neg_hi:[1,0,0]
	ds_read_b128 v[106:109], v0 offset:11184
	s_waitcnt lgkmcnt(6)
	v_pk_fma_f32 v[190:191], v[116:117], v[190:191], v[190:191] op_sel_hi:[1,0,1] neg_lo:[1,0,0] neg_hi:[1,0,0]
	ds_read_b128 v[110:113], v0 offset:11200
	s_waitcnt lgkmcnt(6)
	v_pk_fma_f32 v[192:193], v[118:119], v[190:191], v[192:193] op_sel_hi:[1,0,1] neg_lo:[1,0,0] neg_hi:[1,0,0]
	v_pk_fma_f32 v[198:199], v[120:121], v[190:191], v[198:199] op_sel_hi:[1,0,1] neg_lo:[1,0,0] neg_hi:[1,0,0]
	ds_read_b128 v[114:117], v0 offset:11216
	s_waitcnt lgkmcnt(6)
	v_pk_fma_f32 v[200:201], v[90:91], v[190:191], v[200:201] op_sel_hi:[1,0,1] neg_lo:[1,0,0] neg_hi:[1,0,0]
	v_pk_fma_f32 v[202:203], v[92:93], v[190:191], v[202:203] op_sel_hi:[1,0,1] neg_lo:[1,0,0] neg_hi:[1,0,0]
	ds_read_b128 v[118:121], v0 offset:11232
	s_waitcnt lgkmcnt(6)
	v_pk_fma_f32 v[204:205], v[94:95], v[190:191], v[204:205] op_sel_hi:[1,0,1] neg_lo:[1,0,0] neg_hi:[1,0,0]
	v_pk_fma_f32 v[208:209], v[96:97], v[190:191], v[208:209] op_sel_hi:[1,0,1] neg_lo:[1,0,0] neg_hi:[1,0,0]
	ds_read_b128 v[90:93], v0 offset:11248
	s_waitcnt lgkmcnt(6)
	v_pk_fma_f32 v[210:211], v[98:99], v[190:191], v[210:211] op_sel_hi:[1,0,1] neg_lo:[1,0,0] neg_hi:[1,0,0]
	v_pk_fma_f32 v[212:213], v[100:101], v[190:191], v[212:213] op_sel_hi:[1,0,1] neg_lo:[1,0,0] neg_hi:[1,0,0]
	ds_read_b128 v[94:97], v0 offset:11440
	s_waitcnt lgkmcnt(6)
	v_pk_fma_f32 v[214:215], v[102:103], v[190:191], v[214:215] op_sel_hi:[1,0,1] neg_lo:[1,0,0] neg_hi:[1,0,0]
	v_pk_fma_f32 v[216:217], v[104:105], v[190:191], v[216:217] op_sel_hi:[1,0,1] neg_lo:[1,0,0] neg_hi:[1,0,0]
	ds_read_b128 v[98:101], v0 offset:11456
	s_waitcnt lgkmcnt(6)
	v_pk_fma_f32 v[192:193], v[106:107], v[190:191], v[192:193] op_sel:[0,1,0] neg_lo:[1,0,0] neg_hi:[1,0,0]
	v_pk_fma_f32 v[198:199], v[108:109], v[190:191], v[198:199] op_sel:[0,1,0] neg_lo:[1,0,0] neg_hi:[1,0,0]
	ds_read_b128 v[102:105], v0 offset:11472
	s_waitcnt lgkmcnt(6)
	v_pk_fma_f32 v[200:201], v[110:111], v[190:191], v[200:201] op_sel:[0,1,0] neg_lo:[1,0,0] neg_hi:[1,0,0]
	v_pk_fma_f32 v[202:203], v[112:113], v[190:191], v[202:203] op_sel:[0,1,0] neg_lo:[1,0,0] neg_hi:[1,0,0]
	ds_read_b128 v[106:109], v0 offset:11488
	s_waitcnt lgkmcnt(6)
	v_pk_fma_f32 v[204:205], v[114:115], v[190:191], v[204:205] op_sel:[0,1,0] neg_lo:[1,0,0] neg_hi:[1,0,0]
	v_pk_fma_f32 v[208:209], v[116:117], v[190:191], v[208:209] op_sel:[0,1,0] neg_lo:[1,0,0] neg_hi:[1,0,0]
	ds_read_b128 v[110:113], v0 offset:11504
	s_waitcnt lgkmcnt(6)
	v_pk_fma_f32 v[210:211], v[118:119], v[190:191], v[210:211] op_sel:[0,1,0] neg_lo:[1,0,0] neg_hi:[1,0,0]
	v_pk_fma_f32 v[212:213], v[120:121], v[190:191], v[212:213] op_sel:[0,1,0] neg_lo:[1,0,0] neg_hi:[1,0,0]
	ds_read_b128 v[114:117], v0 offset:11696
	s_waitcnt lgkmcnt(6)
	v_pk_fma_f32 v[214:215], v[90:91], v[190:191], v[214:215] op_sel:[0,1,0] neg_lo:[1,0,0] neg_hi:[1,0,0]
	v_pk_fma_f32 v[216:217], v[92:93], v[190:191], v[216:217] op_sel:[0,1,0] neg_lo:[1,0,0] neg_hi:[1,0,0]
	ds_read_b128 v[118:121], v0 offset:11712
	s_waitcnt lgkmcnt(6)
	v_pk_fma_f32 v[192:193], v[94:95], v[192:193], v[192:193] op_sel_hi:[1,0,1] neg_lo:[1,0,0] neg_hi:[1,0,0]
	v_pk_fma_f32 v[198:199], v[96:97], v[192:193], v[198:199] op_sel_hi:[1,0,1] neg_lo:[1,0,0] neg_hi:[1,0,0]
	ds_read_b128 v[90:93], v0 offset:11728
	s_waitcnt lgkmcnt(6)
	v_pk_fma_f32 v[200:201], v[98:99], v[192:193], v[200:201] op_sel_hi:[1,0,1] neg_lo:[1,0,0] neg_hi:[1,0,0]
	v_pk_fma_f32 v[202:203], v[100:101], v[192:193], v[202:203] op_sel_hi:[1,0,1] neg_lo:[1,0,0] neg_hi:[1,0,0]
	ds_read_b128 v[94:97], v0 offset:11744
	s_waitcnt lgkmcnt(6)
	v_pk_fma_f32 v[204:205], v[102:103], v[192:193], v[204:205] op_sel_hi:[1,0,1] neg_lo:[1,0,0] neg_hi:[1,0,0]
	v_pk_fma_f32 v[208:209], v[104:105], v[192:193], v[208:209] op_sel_hi:[1,0,1] neg_lo:[1,0,0] neg_hi:[1,0,0]
	ds_read_b128 v[98:101], v0 offset:11760
	s_waitcnt lgkmcnt(6)
	v_pk_fma_f32 v[210:211], v[106:107], v[192:193], v[210:211] op_sel_hi:[1,0,1] neg_lo:[1,0,0] neg_hi:[1,0,0]
	v_pk_fma_f32 v[212:213], v[108:109], v[192:193], v[212:213] op_sel_hi:[1,0,1] neg_lo:[1,0,0] neg_hi:[1,0,0]
	ds_read_b128 v[102:105], v0 offset:11952
	s_waitcnt lgkmcnt(6)
	v_pk_fma_f32 v[214:215], v[110:111], v[192:193], v[214:215] op_sel_hi:[1,0,1] neg_lo:[1,0,0] neg_hi:[1,0,0]
	v_pk_fma_f32 v[216:217], v[112:113], v[192:193], v[216:217] op_sel_hi:[1,0,1] neg_lo:[1,0,0] neg_hi:[1,0,0]
	ds_read_b128 v[106:109], v0 offset:11968
	s_waitcnt lgkmcnt(6)
	v_pk_fma_f32 v[198:199], v[116:117], v[192:193], v[198:199] op_sel:[0,1,0] neg_lo:[1,0,0] neg_hi:[1,0,0]
	ds_read_b128 v[110:113], v0 offset:11984
	s_waitcnt lgkmcnt(6)
	v_pk_fma_f32 v[200:201], v[118:119], v[192:193], v[200:201] op_sel:[0,1,0] neg_lo:[1,0,0] neg_hi:[1,0,0]
	v_pk_fma_f32 v[202:203], v[120:121], v[192:193], v[202:203] op_sel:[0,1,0] neg_lo:[1,0,0] neg_hi:[1,0,0]
	ds_read_b128 v[114:117], v0 offset:12000
	s_waitcnt lgkmcnt(6)
; #define LAS __attribute__((address_space(3)))
; #define PIN16(o) asm volatile("" : "+v"(xr[o]), "+v"(xr[o + 1]), "+v"(xr[o + 2]), "+v"(xr[o + 3]), "+v"(xr[o + 4]), "+v"(xr[o + 5]), "+v"(xr[o + 6]), "+v"(xr[o + 7]), "+v"(xr[o + 8]), "+v"(xr[o + 9]), "+v"(xr[o + 10]), "+v"(xr[o + 11]), "+v"(xr[o + 12]), "+v"(xr[o + 13]), "+v"(xr[o + 14]), "+v"(xr[o + 15]) :: "memory")
; DI void gdn_prep_item(LAS unsigned char* lds, const Ctx& c, int l, int item) {
;     ...
; #pragma unroll
;         for (int j = 0; j < 63; ++j) {
;             const float xj = xr[j];
; #pragma unroll
;             for (int i4 = (j + 1) / 4; i4 < 16; ++i4) { const f32x4 Lv = *(const LAS f32x4*)(Lb + j * 64 + 4 * i4);
; #pragma unroll
;                 for (int q = 0; q < 4; ++q) xr[4 * i4 + q] -= Lv[q] * xj; }
;     ...
;             PIN16(0); PIN16(16); PIN16(32); PIN16(48);
;         }
	v_pk_fma_f32 v[204:205], v[90:91], v[192:193], v[204:205] op_sel:[0,1,0] neg_lo:[1,0,0] neg_hi:[1,0,0]
	v_pk_fma_f32 v[208:209], v[92:93], v[192:193], v[208:209] op_sel:[0,1,0] neg_lo:[1,0,0] neg_hi:[1,0,0]
	ds_read_b128 v[118:121], v0 offset:12016
	s_waitcnt lgkmcnt(6)
	v_pk_fma_f32 v[210:211], v[94:95], v[192:193], v[210:211] op_sel:[0,1,0] neg_lo:[1,0,0] neg_hi:[1,0,0]
	v_pk_fma_f32 v[212:213], v[96:97], v[192:193], v[212:213] op_sel:[0,1,0] neg_lo:[1,0,0] neg_hi:[1,0,0]
	ds_read_b128 v[90:93], v0 offset:12224
	s_waitcnt lgkmcnt(6)
	v_pk_fma_f32 v[214:215], v[98:99], v[192:193], v[214:215] op_sel:[0,1,0] neg_lo:[1,0,0] neg_hi:[1,0,0]
	v_pk_fma_f32 v[216:217], v[100:101], v[192:193], v[216:217] op_sel:[0,1,0] neg_lo:[1,0,0] neg_hi:[1,0,0]
	ds_read_b128 v[94:97], v0 offset:12240
	s_waitcnt lgkmcnt(6)
	v_pk_fma_f32 v[198:199], v[104:105], v[198:199], v[198:199] op_sel_hi:[1,0,1] neg_lo:[1,0,0] neg_hi:[1,0,0]
	ds_read_b128 v[98:101], v0 offset:12256
	s_waitcnt lgkmcnt(6)
	v_pk_fma_f32 v[200:201], v[106:107], v[198:199], v[200:201] op_sel_hi:[1,0,1] neg_lo:[1,0,0] neg_hi:[1,0,0]
	v_pk_fma_f32 v[202:203], v[108:109], v[198:199], v[202:203] op_sel_hi:[1,0,1] neg_lo:[1,0,0] neg_hi:[1,0,0]
	ds_read_b128 v[102:105], v0 offset:12272
	s_waitcnt lgkmcnt(6)
	v_pk_fma_f32 v[204:205], v[110:111], v[198:199], v[204:205] op_sel_hi:[1,0,1] neg_lo:[1,0,0] neg_hi:[1,0,0]
	v_pk_fma_f32 v[208:209], v[112:113], v[198:199], v[208:209] op_sel_hi:[1,0,1] neg_lo:[1,0,0] neg_hi:[1,0,0]
	ds_read_b128 v[106:109], v0 offset:12480
	s_waitcnt lgkmcnt(6)
	v_pk_fma_f32 v[210:211], v[114:115], v[198:199], v[210:211] op_sel_hi:[1,0,1] neg_lo:[1,0,0] neg_hi:[1,0,0]
	v_pk_fma_f32 v[212:213], v[116:117], v[198:199], v[212:213] op_sel_hi:[1,0,1] neg_lo:[1,0,0] neg_hi:[1,0,0]
	ds_read_b128 v[110:113], v0 offset:12496
	s_waitcnt lgkmcnt(6)
	v_pk_fma_f32 v[214:215], v[118:119], v[198:199], v[214:215] op_sel_hi:[1,0,1] neg_lo:[1,0,0] neg_hi:[1,0,0]
	v_pk_fma_f32 v[216:217], v[120:121], v[198:199], v[216:217] op_sel_hi:[1,0,1] neg_lo:[1,0,0] neg_hi:[1,0,0]
	ds_read_b128 v[114:117], v0 offset:12512
	s_waitcnt lgkmcnt(6)
	v_pk_fma_f32 v[200:201], v[90:91], v[198:199], v[200:201] op_sel:[0,1,0] neg_lo:[1,0,0] neg_hi:[1,0,0]
	v_pk_fma_f32 v[202:203], v[92:93], v[198:199], v[202:203] op_sel:[0,1,0] neg_lo:[1,0,0] neg_hi:[1,0,0]
	ds_read_b128 v[118:121], v0 offset:12528
	s_waitcnt lgkmcnt(6)
	v_pk_fma_f32 v[204:205], v[94:95], v[198:199], v[204:205] op_sel:[0,1,0] neg_lo:[1,0,0] neg_hi:[1,0,0]
	v_pk_fma_f32 v[208:209], v[96:97], v[198:199], v[208:209] op_sel:[0,1,0] neg_lo:[1,0,0] neg_hi:[1,0,0]
	ds_read_b128 v[90:93], v0 offset:12736
	s_waitcnt lgkmcnt(6)
	v_pk_fma_f32 v[210:211], v[98:99], v[198:199], v[210:211] op_sel:[0,1,0] neg_lo:[1,0,0] neg_hi:[1,0,0]
	v_pk_fma_f32 v[212:213], v[100:101], v[198:199], v[212:213] op_sel:[0,1,0] neg_lo:[1,0,0] neg_hi:[1,0,0]
	ds_read_b128 v[94:97], v0 offset:12752
	s_waitcnt lgkmcnt(6)
	v_pk_fma_f32 v[214:215], v[102:103], v[198:199], v[214:215] op_sel:[0,1,0] neg_lo:[1,0,0] neg_hi:[1,0,0]
	v_pk_fma_f32 v[216:217], v[104:105], v[198:199], v[216:217] op_sel:[0,1,0] neg_lo:[1,0,0] neg_hi:[1,0,0]
	ds_read_b128 v[98:101], v0 offset:12768
	s_waitcnt lgkmcnt(6)
	v_pk_fma_f32 v[200:201], v[106:107], v[200:201], v[200:201] op_sel_hi:[1,0,1] neg_lo:[1,0,0] neg_hi:[1,0,0]
	v_pk_fma_f32 v[202:203], v[108:109], v[200:201], v[202:203] op_sel_hi:[1,0,1] neg_lo:[1,0,0] neg_hi:[1,0,0]
	ds_read_b128 v[102:105], v0 offset:12784
	s_waitcnt lgkmcnt(6)
	v_pk_fma_f32 v[204:205], v[110:111], v[200:201], v[204:205] op_sel_hi:[1,0,1] neg_lo:[1,0,0] neg_hi:[1,0,0]
	v_pk_fma_f32 v[208:209], v[112:113], v[200:201], v[208:209] op_sel_hi:[1,0,1] neg_lo:[1,0,0] neg_hi:[1,0,0]
	ds_read_b128 v[106:109], v0 offset:12992
	s_waitcnt lgkmcnt(6)
	v_pk_fma_f32 v[210:211], v[114:115], v[200:201], v[210:211] op_sel_hi:[1,0,1] neg_lo:[1,0,0] neg_hi:[1,0,0]
	v_pk_fma_f32 v[212:213], v[116:117], v[200:201], v[212:213] op_sel_hi:[1,0,1] neg_lo:[1,0,0] neg_hi:[1,0,0]
	ds_read_b128 v[110:113], v0 offset:13008
	s_waitcnt lgkmcnt(6)
	v_pk_fma_f32 v[214:215], v[118:119], v[200:201], v[214:215] op_sel_hi:[1,0,1] neg_lo:[1,0,0] neg_hi:[1,0,0]
	v_pk_fma_f32 v[216:217], v[120:121], v[200:201], v[216:217] op_sel_hi:[1,0,1] neg_lo:[1,0,0] neg_hi:[1,0,0]
	ds_read_b128 v[114:117], v0 offset:13024
	s_waitcnt lgkmcnt(6)
	v_pk_fma_f32 v[202:203], v[92:93], v[200:201], v[202:203] op_sel:[0,1,0] neg_lo:[1,0,0] neg_hi:[1,0,0]
	ds_read_b128 v[118:121], v0 offset:13040
	s_waitcnt lgkmcnt(6)
	v_pk_fma_f32 v[204:205], v[94:95], v[200:201], v[204:205] op_sel:[0,1,0] neg_lo:[1,0,0] neg_hi:[1,0,0]
	v_pk_fma_f32 v[208:209], v[96:97], v[200:201], v[208:209] op_sel:[0,1,0] neg_lo:[1,0,0] neg_hi:[1,0,0]
	ds_read_b128 v[90:93], v0 offset:13264
	s_waitcnt lgkmcnt(6)
	v_pk_fma_f32 v[210:211], v[98:99], v[200:201], v[210:211] op_sel:[0,1,0] neg_lo:[1,0,0] neg_hi:[1,0,0]
	v_pk_fma_f32 v[212:213], v[100:101], v[200:201], v[212:213] op_sel:[0,1,0] neg_lo:[1,0,0] neg_hi:[1,0,0]
	ds_read_b128 v[94:97], v0 offset:13280
	s_waitcnt lgkmcnt(6)
	v_pk_fma_f32 v[214:215], v[102:103], v[200:201], v[214:215] op_sel:[0,1,0] neg_lo:[1,0,0] neg_hi:[1,0,0]
	v_pk_fma_f32 v[216:217], v[104:105], v[200:201], v[216:217] op_sel:[0,1,0] neg_lo:[1,0,0] neg_hi:[1,0,0]
	ds_read_b128 v[98:101], v0 offset:13296
	s_waitcnt lgkmcnt(6)
	v_pk_fma_f32 v[202:203], v[108:109], v[202:203], v[202:203] op_sel_hi:[1,0,1] neg_lo:[1,0,0] neg_hi:[1,0,0]
	ds_read_b128 v[102:105], v0 offset:13520
	s_waitcnt lgkmcnt(6)
	v_pk_fma_f32 v[204:205], v[110:111], v[202:203], v[204:205] op_sel_hi:[1,0,1] neg_lo:[1,0,0] neg_hi:[1,0,0]
	v_pk_fma_f32 v[208:209], v[112:113], v[202:203], v[208:209] op_sel_hi:[1,0,1] neg_lo:[1,0,0] neg_hi:[1,0,0]
	ds_read_b128 v[106:109], v0 offset:13536
	s_waitcnt lgkmcnt(6)
; #define LAS __attribute__((address_space(3)))
; #define PIN16(o) asm volatile("" : "+v"(xr[o]), "+v"(xr[o + 1]), "+v"(xr[o + 2]), "+v"(xr[o + 3]), "+v"(xr[o + 4]), "+v"(xr[o + 5]), "+v"(xr[o + 6]), "+v"(xr[o + 7]), "+v"(xr[o + 8]), "+v"(xr[o + 9]), "+v"(xr[o + 10]), "+v"(xr[o + 11]), "+v"(xr[o + 12]), "+v"(xr[o + 13]), "+v"(xr[o + 14]), "+v"(xr[o + 15]) :: "memory")
; DI void gdn_prep_item(LAS unsigned char* lds, const Ctx& c, int l, int item) {
;     ...
; #pragma unroll
;         for (int j = 0; j < 63; ++j) {
;             const float xj = xr[j];
; #pragma unroll
;             for (int i4 = (j + 1) / 4; i4 < 16; ++i4) { const f32x4 Lv = *(const LAS f32x4*)(Lb + j * 64 + 4 * i4);
; #pragma unroll
;                 for (int q = 0; q < 4; ++q) xr[4 * i4 + q] -= Lv[q] * xj; }
;     ...
;             PIN16(0); PIN16(16); PIN16(32); PIN16(48);
;         }
	v_pk_fma_f32 v[210:211], v[114:115], v[202:203], v[210:211] op_sel_hi:[1,0,1] neg_lo:[1,0,0] neg_hi:[1,0,0]
	v_pk_fma_f32 v[212:213], v[116:117], v[202:203], v[212:213] op_sel_hi:[1,0,1] neg_lo:[1,0,0] neg_hi:[1,0,0]
	ds_read_b128 v[110:113], v0 offset:13552
	s_waitcnt lgkmcnt(6)
	v_pk_fma_f32 v[214:215], v[118:119], v[202:203], v[214:215] op_sel_hi:[1,0,1] neg_lo:[1,0,0] neg_hi:[1,0,0]
	v_pk_fma_f32 v[216:217], v[120:121], v[202:203], v[216:217] op_sel_hi:[1,0,1] neg_lo:[1,0,0] neg_hi:[1,0,0]
	ds_read_b128 v[114:117], v0 offset:13776
	s_waitcnt lgkmcnt(6)
	v_pk_fma_f32 v[204:205], v[90:91], v[202:203], v[204:205] op_sel:[0,1,0] neg_lo:[1,0,0] neg_hi:[1,0,0]
	v_pk_fma_f32 v[208:209], v[92:93], v[202:203], v[208:209] op_sel:[0,1,0] neg_lo:[1,0,0] neg_hi:[1,0,0]
	ds_read_b128 v[118:121], v0 offset:13792
	s_waitcnt lgkmcnt(6)
	v_pk_fma_f32 v[210:211], v[94:95], v[202:203], v[210:211] op_sel:[0,1,0] neg_lo:[1,0,0] neg_hi:[1,0,0]
	v_pk_fma_f32 v[212:213], v[96:97], v[202:203], v[212:213] op_sel:[0,1,0] neg_lo:[1,0,0] neg_hi:[1,0,0]
	ds_read_b128 v[90:93], v0 offset:13808
	s_waitcnt lgkmcnt(6)
	v_pk_fma_f32 v[214:215], v[98:99], v[202:203], v[214:215] op_sel:[0,1,0] neg_lo:[1,0,0] neg_hi:[1,0,0]
	v_pk_fma_f32 v[216:217], v[100:101], v[202:203], v[216:217] op_sel:[0,1,0] neg_lo:[1,0,0] neg_hi:[1,0,0]
	ds_read_b128 v[94:97], v0 offset:14032
	s_waitcnt lgkmcnt(6)
	v_pk_fma_f32 v[204:205], v[102:103], v[204:205], v[204:205] op_sel_hi:[1,0,1] neg_lo:[1,0,0] neg_hi:[1,0,0]
	v_pk_fma_f32 v[208:209], v[104:105], v[204:205], v[208:209] op_sel_hi:[1,0,1] neg_lo:[1,0,0] neg_hi:[1,0,0]
	ds_read_b128 v[98:101], v0 offset:14048
	s_waitcnt lgkmcnt(6)
	v_pk_fma_f32 v[210:211], v[106:107], v[204:205], v[210:211] op_sel_hi:[1,0,1] neg_lo:[1,0,0] neg_hi:[1,0,0]
	v_pk_fma_f32 v[212:213], v[108:109], v[204:205], v[212:213] op_sel_hi:[1,0,1] neg_lo:[1,0,0] neg_hi:[1,0,0]
	ds_read_b128 v[102:105], v0 offset:14064
	s_waitcnt lgkmcnt(6)
	v_pk_fma_f32 v[214:215], v[110:111], v[204:205], v[214:215] op_sel_hi:[1,0,1] neg_lo:[1,0,0] neg_hi:[1,0,0]
	v_pk_fma_f32 v[216:217], v[112:113], v[204:205], v[216:217] op_sel_hi:[1,0,1] neg_lo:[1,0,0] neg_hi:[1,0,0]
	ds_read_b128 v[106:109], v0 offset:14304
	s_waitcnt lgkmcnt(6)
	v_pk_fma_f32 v[208:209], v[116:117], v[204:205], v[208:209] op_sel:[0,1,0] neg_lo:[1,0,0] neg_hi:[1,0,0]
	ds_read_b128 v[110:113], v0 offset:14320
	s_waitcnt lgkmcnt(6)
	v_pk_fma_f32 v[210:211], v[118:119], v[204:205], v[210:211] op_sel:[0,1,0] neg_lo:[1,0,0] neg_hi:[1,0,0]
	v_pk_fma_f32 v[212:213], v[120:121], v[204:205], v[212:213] op_sel:[0,1,0] neg_lo:[1,0,0] neg_hi:[1,0,0]
	ds_read_b128 v[114:117], v0 offset:14560
	s_waitcnt lgkmcnt(6)
	v_pk_fma_f32 v[214:215], v[90:91], v[204:205], v[214:215] op_sel:[0,1,0] neg_lo:[1,0,0] neg_hi:[1,0,0]
	v_pk_fma_f32 v[216:217], v[92:93], v[204:205], v[216:217] op_sel:[0,1,0] neg_lo:[1,0,0] neg_hi:[1,0,0]
	ds_read_b128 v[118:121], v0 offset:14576
	s_waitcnt lgkmcnt(6)
	v_pk_fma_f32 v[208:209], v[96:97], v[208:209], v[208:209] op_sel_hi:[1,0,1] neg_lo:[1,0,0] neg_hi:[1,0,0]
	ds_read_b128 v[90:93], v0 offset:14816
	s_waitcnt lgkmcnt(6)
	v_pk_fma_f32 v[210:211], v[98:99], v[208:209], v[210:211] op_sel_hi:[1,0,1] neg_lo:[1,0,0] neg_hi:[1,0,0]
	v_pk_fma_f32 v[212:213], v[100:101], v[208:209], v[212:213] op_sel_hi:[1,0,1] neg_lo:[1,0,0] neg_hi:[1,0,0]
	ds_read_b128 v[94:97], v0 offset:14832
	s_waitcnt lgkmcnt(6)
	v_pk_fma_f32 v[214:215], v[102:103], v[208:209], v[214:215] op_sel_hi:[1,0,1] neg_lo:[1,0,0] neg_hi:[1,0,0]
	v_pk_fma_f32 v[216:217], v[104:105], v[208:209], v[216:217] op_sel_hi:[1,0,1] neg_lo:[1,0,0] neg_hi:[1,0,0]
	ds_read_b128 v[98:101], v0 offset:15072
	s_waitcnt lgkmcnt(6)
	v_pk_fma_f32 v[210:211], v[106:107], v[208:209], v[210:211] op_sel:[0,1,0] neg_lo:[1,0,0] neg_hi:[1,0,0]
	v_pk_fma_f32 v[212:213], v[108:109], v[208:209], v[212:213] op_sel:[0,1,0] neg_lo:[1,0,0] neg_hi:[1,0,0]
	ds_read_b128 v[102:105], v0 offset:15088
	s_waitcnt lgkmcnt(6)
	v_pk_fma_f32 v[214:215], v[110:111], v[208:209], v[214:215] op_sel:[0,1,0] neg_lo:[1,0,0] neg_hi:[1,0,0]
	v_pk_fma_f32 v[216:217], v[112:113], v[208:209], v[216:217] op_sel:[0,1,0] neg_lo:[1,0,0] neg_hi:[1,0,0]
	ds_read_b128 v[106:109], v0 offset:15344
	s_waitcnt lgkmcnt(6)
	v_pk_fma_f32 v[210:211], v[114:115], v[210:211], v[210:211] op_sel_hi:[1,0,1] neg_lo:[1,0,0] neg_hi:[1,0,0]
	v_pk_fma_f32 v[212:213], v[116:117], v[210:211], v[212:213] op_sel_hi:[1,0,1] neg_lo:[1,0,0] neg_hi:[1,0,0]
	ds_read_b128 v[110:113], v0 offset:15600
	s_waitcnt lgkmcnt(6)
	v_pk_fma_f32 v[214:215], v[118:119], v[210:211], v[214:215] op_sel_hi:[1,0,1] neg_lo:[1,0,0] neg_hi:[1,0,0]
	v_pk_fma_f32 v[216:217], v[120:121], v[210:211], v[216:217] op_sel_hi:[1,0,1] neg_lo:[1,0,0] neg_hi:[1,0,0]
	ds_read_b128 v[114:117], v0 offset:15856
	s_waitcnt lgkmcnt(6)
	v_pk_fma_f32 v[212:213], v[92:93], v[210:211], v[212:213] op_sel:[0,1,0] neg_lo:[1,0,0] neg_hi:[1,0,0]
	ds_read_b128 v[118:121], v0 offset:16112
	s_waitcnt lgkmcnt(6)
	v_pk_fma_f32 v[214:215], v[94:95], v[210:211], v[214:215] op_sel:[0,1,0] neg_lo:[1,0,0] neg_hi:[1,0,0]
	v_pk_fma_f32 v[216:217], v[96:97], v[210:211], v[216:217] op_sel:[0,1,0] neg_lo:[1,0,0] neg_hi:[1,0,0]
	s_waitcnt lgkmcnt(5)
	v_pk_fma_f32 v[212:213], v[100:101], v[212:213], v[212:213] op_sel_hi:[1,0,1] neg_lo:[1,0,0] neg_hi:[1,0,0]
	s_waitcnt lgkmcnt(4)
	v_pk_fma_f32 v[214:215], v[102:103], v[212:213], v[214:215] op_sel_hi:[1,0,1] neg_lo:[1,0,0] neg_hi:[1,0,0]
	v_pk_fma_f32 v[216:217], v[104:105], v[212:213], v[216:217] op_sel_hi:[1,0,1] neg_lo:[1,0,0] neg_hi:[1,0,0]
	s_waitcnt lgkmcnt(3)
; #define LAS __attribute__((address_space(3)))
; #define PIN16(o) asm volatile("" : "+v"(xr[o]), "+v"(xr[o + 1]), "+v"(xr[o + 2]), "+v"(xr[o + 3]), "+v"(xr[o + 4]), "+v"(xr[o + 5]), "+v"(xr[o + 6]), "+v"(xr[o + 7]), "+v"(xr[o + 8]), "+v"(xr[o + 9]), "+v"(xr[o + 10]), "+v"(xr[o + 11]), "+v"(xr[o + 12]), "+v"(xr[o + 13]), "+v"(xr[o + 14]), "+v"(xr[o + 15]) :: "memory")
; DI void gdn_prep_item(LAS unsigned char* lds, const Ctx& c, int l, int item) {
;     ...
; #pragma unroll
;         for (int j = 0; j < 63; ++j) {
;             const float xj = xr[j];
; #pragma unroll
;             for (int i4 = (j + 1) / 4; i4 < 16; ++i4) { const f32x4 Lv = *(const LAS f32x4*)(Lb + j * 64 + 4 * i4);
; #pragma unroll
;                 for (int q = 0; q < 4; ++q) xr[4 * i4 + q] -= Lv[q] * xj; }
;     ...
;             PIN16(0); PIN16(16); PIN16(32); PIN16(48);
;         }
;         if (col < 128) {
	v_pk_fma_f32 v[214:215], v[106:107], v[212:213], v[214:215] op_sel:[0,1,0] neg_lo:[1,0,0] neg_hi:[1,0,0]
	v_pk_fma_f32 v[216:217], v[108:109], v[212:213], v[216:217] op_sel:[0,1,0] neg_lo:[1,0,0] neg_hi:[1,0,0]
	s_waitcnt lgkmcnt(2)
	v_pk_fma_f32 v[214:215], v[110:111], v[214:215], v[214:215] op_sel_hi:[1,0,1] neg_lo:[1,0,0] neg_hi:[1,0,0]
	v_pk_fma_f32 v[216:217], v[112:113], v[214:215], v[216:217] op_sel_hi:[1,0,1] neg_lo:[1,0,0] neg_hi:[1,0,0]
	s_waitcnt lgkmcnt(1)
	v_pk_fma_f32 v[216:217], v[116:117], v[214:215], v[216:217] op_sel:[0,1,0] neg_lo:[1,0,0] neg_hi:[1,0,0]
	s_waitcnt lgkmcnt(0)
	v_pk_fma_f32 v[216:217], v[120:121], v[216:217], v[216:217] op_sel_hi:[1,0,1] neg_lo:[1,0,0] neg_hi:[1,0,0]
	s_waitcnt lgkmcnt(0)
	v_mov_b32_e32 v5, v122
	v_mov_b32_e32 v4, v123
	v_mov_b32_e32 v3, v124
	v_mov_b32_e32 v2, v125
	v_mov_b32_e32 v9, v126
	v_mov_b32_e32 v8, v127
	v_mov_b32_e32 v7, v128
	v_mov_b32_e32 v6, v129
	v_mov_b32_e32 v13, v156
	v_mov_b32_e32 v12, v157
	v_mov_b32_e32 v11, v158
	v_mov_b32_e32 v10, v159
	v_mov_b32_e32 v17, v160
	v_mov_b32_e32 v16, v161
	v_mov_b32_e32 v15, v162
	v_mov_b32_e32 v14, v163
	v_mov_b32_e32 v21, v164
	v_mov_b32_e32 v20, v165
	v_mov_b32_e32 v19, v166
	v_mov_b32_e32 v18, v167
	v_mov_b32_e32 v25, v168
	v_mov_b32_e32 v24, v169
	v_mov_b32_e32 v23, v170
	v_mov_b32_e32 v22, v171
	v_mov_b32_e32 v31, v172
	v_mov_b32_e32 v30, v173
	v_mov_b32_e32 v29, v174
	v_mov_b32_e32 v28, v175
	v_mov_b32_e32 v35, v176
	v_mov_b32_e32 v34, v177
	v_mov_b32_e32 v33, v178
	v_mov_b32_e32 v32, v179
	v_mov_b32_e32 v39, v180
	v_mov_b32_e32 v38, v181
	v_mov_b32_e32 v37, v182
	v_mov_b32_e32 v36, v183
	v_mov_b32_e32 v43, v184
	v_mov_b32_e32 v42, v185
	v_mov_b32_e32 v41, v186
	v_mov_b32_e32 v40, v187
	v_mov_b32_e32 v47, v188
	v_mov_b32_e32 v46, v189
	v_mov_b32_e32 v45, v190
	v_mov_b32_e32 v44, v191
	v_mov_b32_e32 v51, v192
	v_mov_b32_e32 v50, v193
	v_mov_b32_e32 v49, v198
	v_mov_b32_e32 v48, v199
	v_mov_b32_e32 v55, v200
	v_mov_b32_e32 v54, v201
	v_mov_b32_e32 v53, v202
	v_mov_b32_e32 v52, v203
	v_mov_b32_e32 v59, v204
	v_mov_b32_e32 v58, v205
	v_mov_b32_e32 v57, v208
	v_mov_b32_e32 v56, v209
	v_mov_b32_e32 v63, v210
	v_mov_b32_e32 v62, v211
	v_mov_b32_e32 v61, v212
	v_mov_b32_e32 v60, v213
	v_mov_b32_e32 v66, v214
	v_mov_b32_e32 v65, v215
	v_mov_b32_e32 v64, v216
	v_mov_b32_e32 v0, v217
	s_and_saveexec_b64 s[8:9], vcc
	s_xor_b64 s[8:9], exec, s[8:9]
	s_cbranch_execz .LBB0_316
; DI unsigned pk2(float lo, float hi) { f32x2 v = {lo, hi}; bf16x2_t b = __builtin_convertvector(v, bf16x2_t); return __builtin_bit_cast(unsigned, b); }
; DI void gdn_prep_item(LAS unsigned char* lds, const Ctx& c, int l, int item) {
;     ...
;         } else {
;             bf16_t* Wg = (bf16_t*)(ws + WS_WC) + cidx * 8192 + (col - 128);
; #pragma unroll
;             for (int i = 0; i < 64; ++i) Wg[i * 128] = (bf16_t)(pk2(xr[i], 0.f) & 0xffffu);
	s_add_u32 s10, s0, s6
	s_addc_u32 s11, s1, s7
	v_mov_b32_e32 v27, v1
	v_lshl_add_u64 v[26:27], v[26:27], 1, s[10:11]
	v_add_co_u32_e32 v68, vcc, 0xe5ff000, v26
	v_cvt_pk_bf16_f32 v5, v5, s0
	s_nop 0
	v_addc_co_u32_e32 v69, vcc, 0, v27, vcc
	v_cvt_pk_bf16_f32 v67, v4, s0
	v_add_co_u32_e32 v4, vcc, 0xe600000, v26
	global_store_short v[68:69], v5, off offset:3840
	s_nop 0
	v_addc_co_u32_e32 v5, vcc, 0, v27, vcc
	v_cvt_pk_bf16_f32 v2, v2, s0
	global_store_short v[4:5], v2, off offset:512
	v_cvt_pk_bf16_f32 v2, v9, s0
	global_store_short v[4:5], v2, off offset:768
	v_cvt_pk_bf16_f32 v2, v8, s0
	global_store_short v[4:5], v2, off offset:1024
	v_cvt_pk_bf16_f32 v2, v7, s0
	global_store_short v[4:5], v2, off offset:1280
	v_cvt_pk_bf16_f32 v2, v6, s0
	global_store_short v[4:5], v2, off offset:1536
	v_cvt_pk_bf16_f32 v2, v13, s0
	global_store_short v[4:5], v2, off offset:1792
	v_cvt_pk_bf16_f32 v2, v12, s0
	global_store_short v[4:5], v2, off offset:2048
	v_cvt_pk_bf16_f32 v2, v11, s0
	global_store_short v[4:5], v2, off offset:2304
	v_cvt_pk_bf16_f32 v2, v10, s0
	global_store_short v[4:5], v2, off offset:2560
	v_cvt_pk_bf16_f32 v2, v17, s0
	global_store_short v[4:5], v2, off offset:2816
	v_cvt_pk_bf16_f32 v2, v16, s0
	global_store_short v[4:5], v2, off offset:3072
	v_cvt_pk_bf16_f32 v2, v15, s0
	global_store_short v[4:5], v2, off offset:3328
	v_cvt_pk_bf16_f32 v2, v14, s0
	global_store_short v[4:5], v2, off offset:3584
	v_cvt_pk_bf16_f32 v2, v21, s0
	s_mov_b32 s10, 0xe601000
	v_cvt_pk_bf16_f32 v3, v3, s0
	global_store_short v[4:5], v2, off offset:3840
	v_add_co_u32_e32 v2, vcc, s10, v26
	global_store_short v[4:5], v3, off offset:256
	s_nop 0
	v_addc_co_u32_e32 v3, vcc, 0, v27, vcc
	s_mov_b32 s10, 0xe602000
	global_store_short v[4:5], v67, off
	v_add_co_u32_e32 v4, vcc, s10, v26
	v_cvt_pk_bf16_f32 v6, v20, s0
	s_nop 0
	v_addc_co_u32_e32 v5, vcc, 0, v27, vcc
	global_store_short v[4:5], v6, off offset:-4096
	v_cvt_pk_bf16_f32 v6, v19, s0
	global_store_short v[2:3], v6, off offset:256
	v_cvt_pk_bf16_f32 v6, v18, s0
	global_store_short v[2:3], v6, off offset:512
	v_cvt_pk_bf16_f32 v6, v25, s0
	global_store_short v[2:3], v6, off offset:768
	v_cvt_pk_bf16_f32 v6, v24, s0
	global_store_short v[2:3], v6, off offset:1024
	v_cvt_pk_bf16_f32 v6, v23, s0
	global_store_short v[2:3], v6, off offset:1280
	v_cvt_pk_bf16_f32 v6, v22, s0
	global_store_short v[2:3], v6, off offset:1536
	v_cvt_pk_bf16_f32 v6, v31, s0
	global_store_short v[2:3], v6, off offset:1792
	v_cvt_pk_bf16_f32 v6, v30, s0
	global_store_short v[2:3], v6, off offset:2048
	v_cvt_pk_bf16_f32 v6, v29, s0
	global_store_short v[2:3], v6, off offset:2304
	v_cvt_pk_bf16_f32 v6, v28, s0
	global_store_short v[2:3], v6, off offset:2560
	v_cvt_pk_bf16_f32 v6, v35, s0
	global_store_short v[2:3], v6, off offset:2816
	v_cvt_pk_bf16_f32 v6, v34, s0
	global_store_short v[2:3], v6, off offset:3072
	v_cvt_pk_bf16_f32 v6, v33, s0
	global_store_short v[2:3], v6, off offset:3328
	v_cvt_pk_bf16_f32 v6, v32, s0
	global_store_short v[2:3], v6, off offset:3584
	v_cvt_pk_bf16_f32 v6, v39, s0
	global_store_short v[2:3], v6, off offset:3840
	v_cvt_pk_bf16_f32 v2, v38, s0
	global_store_short v[4:5], v2, off
	v_cvt_pk_bf16_f32 v2, v37, s0
	global_store_short v[4:5], v2, off offset:256
	v_cvt_pk_bf16_f32 v2, v36, s0
	global_store_short v[4:5], v2, off offset:512
	v_cvt_pk_bf16_f32 v2, v43, s0
	global_store_short v[4:5], v2, off offset:768
	v_cvt_pk_bf16_f32 v2, v42, s0
	global_store_short v[4:5], v2, off offset:1024
	v_cvt_pk_bf16_f32 v2, v41, s0
	global_store_short v[4:5], v2, off offset:1280
	v_cvt_pk_bf16_f32 v2, v40, s0
	global_store_short v[4:5], v2, off offset:1536
	v_cvt_pk_bf16_f32 v2, v47, s0
	global_store_short v[4:5], v2, off offset:1792
	v_cvt_pk_bf16_f32 v2, v46, s0
	global_store_short v[4:5], v2, off offset:2048
	v_cvt_pk_bf16_f32 v2, v45, s0
	global_store_short v[4:5], v2, off offset:2304
	v_cvt_pk_bf16_f32 v2, v44, s0
	global_store_short v[4:5], v2, off offset:2560
	v_cvt_pk_bf16_f32 v2, v51, s0
	global_store_short v[4:5], v2, off offset:2816
	v_cvt_pk_bf16_f32 v2, v50, s0
	global_store_short v[4:5], v2, off offset:3072
	v_cvt_pk_bf16_f32 v2, v49, s0
	global_store_short v[4:5], v2, off offset:3328
	v_cvt_pk_bf16_f32 v2, v48, s0
	global_store_short v[4:5], v2, off offset:3584
	v_cvt_pk_bf16_f32 v2, v55, s0
	s_mov_b32 s10, 0xe603000
	global_store_short v[4:5], v2, off offset:3840
	v_add_co_u32_e32 v2, vcc, s10, v26
	v_cvt_pk_bf16_f32 v4, v54, s0
	s_nop 0
	v_addc_co_u32_e32 v3, vcc, 0, v27, vcc
	global_store_short v[2:3], v4, off
	v_cvt_pk_bf16_f32 v4, v53, s0
	global_store_short v[2:3], v4, off offset:256
	v_cvt_pk_bf16_f32 v4, v52, s0
	global_store_short v[2:3], v4, off offset:512
	v_cvt_pk_bf16_f32 v4, v59, s0
	global_store_short v[2:3], v4, off offset:768
	v_cvt_pk_bf16_f32 v4, v58, s0
	global_store_short v[2:3], v4, off offset:1024
	v_cvt_pk_bf16_f32 v4, v57, s0
	global_store_short v[2:3], v4, off offset:1280
	v_cvt_pk_bf16_f32 v4, v56, s0
	global_store_short v[2:3], v4, off offset:1536
	v_cvt_pk_bf16_f32 v4, v63, s0
	global_store_short v[2:3], v4, off offset:1792
	v_cvt_pk_bf16_f32 v4, v62, s0
	global_store_short v[2:3], v4, off offset:2048
	v_cvt_pk_bf16_f32 v4, v61, s0
	global_store_short v[2:3], v4, off offset:2304
	v_cvt_pk_bf16_f32 v4, v60, s0
	global_store_short v[2:3], v4, off offset:2560
	v_cvt_pk_bf16_f32 v4, v66, s0
	global_store_short v[2:3], v4, off offset:2816
	v_cvt_pk_bf16_f32 v4, v65, s0
	global_store_short v[2:3], v4, off offset:3072
	v_cvt_pk_bf16_f32 v4, v64, s0
	v_cvt_pk_bf16_f32 v0, v0, s0
	global_store_short v[2:3], v4, off offset:3328
	global_store_short v[2:3], v0, off offset:3584
